# P5 k-head norm+rope: 16 rows fully unrolled, loads issued three rows ahead
# speedup vs baseline: 1.0611x; 1.0029x over previous
; __device__ __forceinline__ unsigned pk2(float lo, float hi) { return f2bf(lo) | (f2bf(hi) << 16); }
; __global__ void __launch_bounds__(NWAVES * 64, 2) mk_fwd(Args args) {
;     ...
;     if (IN(5)) {
;         const int hh = lane >> 5, a = (lane >> 4) & 1, i = (lane & 15) * 2;
;         const float invf0 = exp2f(-(float)i * 0.41524101186092029f), invf1 = exp2f(-(float)(i + 1) * 0.41524101186092029f);
;         const float* qn = args.in[I_QN] + a * 64 + i; const float* kn = args.in[I_KN] + a * 64 + i;
;         const float gq1a = qn[0], gq1b = qn[1], gq2a = qn[32], gq2b = qn[33], gk1a = kn[0], gk1b = kn[1], gk2a = kn[32], gk2b = kn[33];
;         for (int row = gw; row < MTOK; row += NGW) {
;             const int s = row & (SEQ - 1);
;             const float pos = (float)(a == 0 ? (s >> 6) : (s & 63));
;             const float rev0 = pos * invf0 * 0.15915494309189535f, rev1 = pos * invf1 * 0.15915494309189535f;
;             const float sn0 = __builtin_amdgcn_sinf(rev0), cs0 = __builtin_amdgcn_cosf(rev0), sn1 = __builtin_amdgcn_sinf(rev1), cs1 = __builtin_amdgcn_cosf(rev1);
;             unsigned* prow = (unsigned*)(PROJ + (size_t)row * INW + a * 64 + i);
; #pragma unroll
;             for (int it = 4; it < 5; ++it) {
;                 unsigned* p = prow + (it * 2 + hh) * 64;
;                 const unsigned u1 = p[0], u2 = p[16];
;                 const float x1a = __builtin_bit_cast(float, u1 << 16), x1b = __builtin_bit_cast(float, u1 & 0xffff0000u);
;                 const float x2a = __builtin_bit_cast(float, u2 << 16), x2b = __builtin_bit_cast(float, u2 & 0xffff0000u);
;                 float ss = (x1a * x1a + x1b * x1b) + (x2a * x2a + x2b * x2b);
; #pragma unroll
;                 for (int o = 1; o < 32; o <<= 1) ss += __shfl_xor(ss, o);
;                 const float rstd = 1.0f / sqrtf(ss * (1.f / 128.f) + EPS);
;                 const bool isq = it < 4;
;                 const float y1a = x1a * rstd * (isq ? gq1a : gk1a), y1b = x1b * rstd * (isq ? gq1b : gk1b);
;                 const float y2a = x2a * rstd * (isq ? gq2a : gk2a), y2b = x2b * rstd * (isq ? gq2b : gk2b);
;                 p[0] = pk2(y1a * cs0 - y2a * sn0, y1b * cs1 - y2b * sn1);
;                 p[16] = pk2(y2a * cs0 + y1a * sn0, y2b * cs1 + y1b * sn1);
;             }
;         }
;     }
.LBB0_407:
	s_cmp_lt_i32 s10, 6
	s_cselect_b64 s[2:3], -1, 0
	s_and_b64 s[4:5], s[2:3], s[0:1]
	s_andn2_b64 vcc, exec, s[4:5]
	s_cbranch_vccnz .LBB0_411
	s_cmpk_gt_i32 s30, 0x7fff
	s_movk_i32 s14, 0x7fff
	s_cbranch_scc1 .LBB0_411
	v_bfe_u32 v13, v218, 4, 1
	v_lshlrev_b32_e32 v0, 1, v218
	v_and_b32_e32 v6, 30, v0
	v_lshlrev_b32_e32 v0, 8, v13
	s_waitcnt lgkmcnt(0)
	v_mov_b32_e32 v1, 0
	v_lshl_add_u64 v[2:3], s[38:39], 0, v[0:1]
	v_lshlrev_b32_e32 v0, 2, v6
	v_lshl_add_u64 v[4:5], v[2:3], 0, v[0:1]
	global_load_dwordx2 v[0:1], v[4:5], off
	global_load_dwordx2 v[2:3], v[4:5], off offset:128
	v_cvt_f32_ubyte0_e32 v4, v6
	v_or_b32_e32 v6, 1, v6
	v_mul_f32_e32 v5, 0xbed49a78, v4
	s_mov_b32 s0, 0xc2fc0000
	v_cvt_f32_ubyte0_e32 v6, v6
	v_mov_b32_e32 v7, 0x42800000
	v_cmp_gt_f32_e32 vcc, s0, v5
	v_mul_f32_e32 v8, 0xbed49a78, v6
	v_cmp_gt_f32_e64 s[0:1], s0, v8
	v_cndmask_b32_e32 v5, 0, v7, vcc
	v_fmac_f32_e32 v5, 0xbed49a78, v4
	v_cndmask_b32_e64 v7, 0, v7, s[0:1]
	v_exp_f32_e32 v4, v5
	v_fmac_f32_e32 v7, 0xbed49a78, v6
	v_exp_f32_e32 v7, v7
	v_not_b32_e32 v5, 63
	v_cndmask_b32_e32 v6, 0, v5, vcc
	v_ldexp_f32 v6, v4, v6
	v_cndmask_b32_e64 v4, 0, v5, s[0:1]
	v_ldexp_f32 v7, v7, v4
	v_mbcnt_lo_u32_b32 v4, -1, 0
	v_mbcnt_hi_u32_b32 v4, -1, v4
	v_and_b32_e32 v5, 64, v4
	v_add_u32_e32 v5, 64, v5
	v_xor_b32_e32 v8, 1, v4
	v_cmp_lt_i32_e32 vcc, v8, v5
	v_xor_b32_e32 v9, 2, v4
	v_xor_b32_e32 v10, 4, v4
	v_cndmask_b32_e32 v8, v4, v8, vcc
	v_cmp_lt_i32_e32 vcc, v9, v5
	v_xor_b32_e32 v11, 8, v4
	v_xor_b32_e32 v12, 16, v4
	v_cndmask_b32_e32 v9, v4, v9, vcc
	v_cmp_lt_i32_e32 vcc, v10, v5
	v_cmp_eq_u32_e64 s[2:3], 0, v13
	s_mul_i32 s1, s30, 0x5400
	v_cndmask_b32_e32 v10, v4, v10, vcc
	v_cmp_lt_i32_e32 vcc, v11, v5
	s_mul_hi_i32 s0, s30, 0x5400
	v_lshlrev_b32_e32 v8, 2, v8
	v_cndmask_b32_e32 v11, v4, v11, vcc
	v_cmp_lt_i32_e32 vcc, v12, v5
	v_lshlrev_b32_e32 v5, 7, v13
	v_and_b32_e32 v13, 15, v218
	v_cndmask_b32_e32 v4, v4, v12, vcc
	v_lshlrev_b32_e32 v12, 2, v4
	v_lshlrev_b32_e32 v4, 3, v218
	v_and_b32_e32 v4, 0x100, v4
	v_or_b32_e32 v4, s1, v4
	v_lshlrev_b32_e32 v13, 2, v13
	v_or3_b32 v4, v4, v5, v13
	v_mov_b32_e32 v5, s0
	v_lshl_add_u64 v[4:5], s[26:27], 0, v[4:5]
	s_mov_b64 s[0:1], 0x14800840
	v_lshlrev_b32_e32 v9, 2, v9
	v_lshlrev_b32_e32 v10, 2, v10
	v_lshlrev_b32_e32 v11, 2, v11
	v_lshl_add_u64 v[4:5], v[4:5], 0, s[0:1]
	s_mul_hi_i32 s13, s34, 0x5400
	s_mul_i32 s12, s34, 0x5400
	s_mov_b32 s15, 0xffff0000
	v_mov_b32_e32 v13, 0x358637bd
	s_mov_b32 s16, 0xf800000
	v_mov_b32_e32 v14, 0x260
	s_mov_b32 s17, s30
	s_cmp_lg_u32 s34, 0x800
	s_cbranch_scc1 .LBB0_410
	v_mov_b32_e32 v38, v4
	v_mov_b32_e32 v39, v5
	global_load_dword v30, v[38:39], off offset:-64
	global_load_dword v31, v[38:39], off
	v_lshl_add_u64 v[38:39], v[38:39], 0, s[12:13]
	global_load_dword v32, v[38:39], off offset:-64
	global_load_dword v33, v[38:39], off
	v_lshl_add_u64 v[38:39], v[38:39], 0, s[12:13]
	global_load_dword v34, v[38:39], off offset:-64
	global_load_dword v35, v[38:39], off
	v_lshl_add_u64 v[38:39], v[38:39], 0, s[12:13]
	s_lshr_b32 s0, s17, 6
	s_and_b32 s1, s17, 63
	v_mov_b32_e32 v21, s1
	v_mov_b32_e32 v22, s0
	v_cndmask_b32_e64 v21, v21, v22, s[2:3]
	v_cvt_f32_ubyte0_e32 v21, v21
	v_mul_f32_e32 v22, v6, v21
	v_mul_f32_e32 v21, v7, v21
	v_mul_f32_e32 v22, 0.15915494, v22
	v_mul_f32_e32 v21, 0.15915494, v21
	v_sin_f32_e32 v23, v22
	v_sin_f32_e32 v24, v21
	v_cos_f32_e32 v22, v22
	v_cos_f32_e32 v21, v21
	s_add_i32 s17, s17, s34
	s_cmp_lt_i32 s17, 0x8000
	s_waitcnt vmcnt(4)
	v_mov_b32_e32 v15, v30
	v_mov_b32_e32 v16, v31
	global_load_dword v36, v[38:39], off offset:-64
	global_load_dword v37, v[38:39], off
	v_lshl_add_u64 v[38:39], v[38:39], 0, s[12:13]
	v_lshlrev_b32_e32 v17, 16, v15
	v_and_b32_e32 v15, 0xffff0000, v15
	v_lshlrev_b32_e32 v18, 16, v16
	v_and_b32_e32 v16, 0xffff0000, v16
	v_mul_f32_e32 v19, v15, v15
	v_mul_f32_e32 v20, v16, v16
	v_fmac_f32_e32 v19, v17, v17
	v_fmac_f32_e32 v20, v18, v18
	v_add_f32_e32 v19, v19, v20
	ds_bpermute_b32 v20, v8, v19
	s_waitcnt lgkmcnt(0)
	v_add_f32_e32 v19, v19, v20
	ds_bpermute_b32 v20, v9, v19
	s_waitcnt lgkmcnt(0)
	v_add_f32_e32 v19, v19, v20
	ds_bpermute_b32 v20, v10, v19
	s_waitcnt lgkmcnt(0)
	v_add_f32_e32 v19, v19, v20
	ds_bpermute_b32 v20, v11, v19
	s_waitcnt lgkmcnt(0)
	v_add_f32_e32 v19, v19, v20
	ds_bpermute_b32 v20, v12, v19
	s_waitcnt lgkmcnt(0)
	v_add_f32_e32 v19, v19, v20
	v_fmamk_f32 v19, v19, 0x3c000000, v13
	v_mul_f32_e32 v20, 0x4f800000, v19
	v_cmp_gt_f32_e32 vcc, s16, v19
	s_nop 1
	v_cndmask_b32_e32 v19, v19, v20, vcc
	v_sqrt_f32_e32 v20, v19
	s_nop 0
	v_add_u32_e32 v25, -1, v20
	v_add_u32_e32 v26, 1, v20
	v_fma_f32 v27, -v25, v20, v19
	v_fma_f32 v28, -v26, v20, v19
	v_cmp_ge_f32_e64 s[0:1], 0, v27
	s_nop 1
	v_cndmask_b32_e64 v20, v20, v25, s[0:1]
	v_cmp_lt_f32_e64 s[0:1], 0, v28
	s_nop 1
	v_cndmask_b32_e64 v20, v20, v26, s[0:1]
	v_mul_f32_e32 v25, 0x37800000, v20
	v_cndmask_b32_e32 v20, v20, v25, vcc
	v_cmp_class_f32_e32 vcc, v19, v14
	s_nop 1
	v_cndmask_b32_e32 v19, v20, v19, vcc
	v_div_scale_f32 v20, s[0:1], v19, v19, 1.0
	v_rcp_f32_e32 v25, v20
	v_div_scale_f32 v26, vcc, 1.0, v19, 1.0
	v_fma_f32 v27, -v20, v25, 1.0
	v_fmac_f32_e32 v25, v27, v25
	v_mul_f32_e32 v27, v26, v25
	v_fma_f32 v28, -v20, v27, v26
	v_fmac_f32_e32 v27, v28, v25
	v_fma_f32 v20, -v20, v27, v26
	v_div_fmas_f32 v20, v20, v25, v27
	v_div_fixup_f32 v19, v20, v19, 1.0
	v_mul_f32_e32 v18, v19, v18
	v_mul_f32_e32 v17, v19, v17
	v_mul_f32_e32 v15, v19, v15
	v_mul_f32_e32 v16, v19, v16
	v_mul_f32_e32 v18, v2, v18
	v_mul_f32_e32 v17, v0, v17
	v_mul_f32_e32 v15, v1, v15
	v_mul_f32_e32 v16, v3, v16
	v_mul_f32_e32 v19, v23, v18
	v_mul_f32_e32 v20, v24, v16
	v_mul_f32_e32 v23, v23, v17
	v_mul_f32_e32 v24, v24, v15
	v_fma_f32 v17, v22, v17, -v19
	v_fma_f32 v15, v21, v15, -v20
	v_fmac_f32_e32 v23, v22, v18
	v_fmac_f32_e32 v24, v21, v16
	v_bfe_u32 v16, v17, 16, 1
	v_bfe_u32 v18, v15, 16, 1
	v_bfe_u32 v19, v23, 16, 1
	v_add3_u32 v16, v17, v16, s14
	v_bfe_u32 v20, v24, 16, 1
	v_add3_u32 v15, v15, v18, s14
	v_add3_u32 v17, v23, v19, s14
	v_lshrrev_b32_e32 v16, 16, v16
	v_add3_u32 v18, v24, v20, s14
	v_lshrrev_b32_e32 v17, 16, v17
	v_and_or_b32 v15, v15, s15, v16
	v_and_or_b32 v16, v18, s15, v17
	global_store_dword v[4:5], v15, off offset:-64
	global_store_dword v[4:5], v16, off
	v_lshl_add_u64 v[4:5], v[4:5], 0, s[12:13]
	s_lshr_b32 s0, s17, 6
	s_and_b32 s1, s17, 63
	v_mov_b32_e32 v21, s1
	v_mov_b32_e32 v22, s0
	v_cndmask_b32_e64 v21, v21, v22, s[2:3]
	v_cvt_f32_ubyte0_e32 v21, v21
	v_mul_f32_e32 v22, v6, v21
	v_mul_f32_e32 v21, v7, v21
	v_mul_f32_e32 v22, 0.15915494, v22
	v_mul_f32_e32 v21, 0.15915494, v21
	v_sin_f32_e32 v23, v22
	v_sin_f32_e32 v24, v21
	v_cos_f32_e32 v22, v22
	v_cos_f32_e32 v21, v21
	s_add_i32 s17, s17, s34
	s_cmp_lt_i32 s17, 0x8000
	s_waitcnt vmcnt(6)
; __device__ __forceinline__ unsigned pk2(float lo, float hi) { return f2bf(lo) | (f2bf(hi) << 16); }
; __global__ void __launch_bounds__(NWAVES * 64, 2) mk_fwd(Args args) {
;     ...
;         for (int row = gw; row < MTOK; row += NGW) {
;             const int s = row & (SEQ - 1);
;             const float pos = (float)(a == 0 ? (s >> 6) : (s & 63));
;             const float rev0 = pos * invf0 * 0.15915494309189535f, rev1 = pos * invf1 * 0.15915494309189535f;
;             const float sn0 = __builtin_amdgcn_sinf(rev0), cs0 = __builtin_amdgcn_cosf(rev0), sn1 = __builtin_amdgcn_sinf(rev1), cs1 = __builtin_amdgcn_cosf(rev1);
;             unsigned* prow = (unsigned*)(PROJ + (size_t)row * INW + a * 64 + i);
; #pragma unroll
;             for (int it = 4; it < 5; ++it) {
;                 unsigned* p = prow + (it * 2 + hh) * 64;
;                 const unsigned u1 = p[0], u2 = p[16];
;                 const float x1a = __builtin_bit_cast(float, u1 << 16), x1b = __builtin_bit_cast(float, u1 & 0xffff0000u);
;                 const float x2a = __builtin_bit_cast(float, u2 << 16), x2b = __builtin_bit_cast(float, u2 & 0xffff0000u);
;                 float ss = (x1a * x1a + x1b * x1b) + (x2a * x2a + x2b * x2b);
; #pragma unroll
;                 for (int o = 1; o < 32; o <<= 1) ss += __shfl_xor(ss, o);
;                 const float rstd = 1.0f / sqrtf(ss * (1.f / 128.f) + EPS);
;                 const bool isq = it < 4;
;                 const float y1a = x1a * rstd * (isq ? gq1a : gk1a), y1b = x1b * rstd * (isq ? gq1b : gk1b);
;                 const float y2a = x2a * rstd * (isq ? gq2a : gk2a), y2b = x2b * rstd * (isq ? gq2b : gk2b);
;                 p[0] = pk2(y1a * cs0 - y2a * sn0, y1b * cs1 - y2b * sn1);
;                 p[16] = pk2(y2a * cs0 + y1a * sn0, y2b * cs1 + y1b * sn1);
;             }
	v_mov_b32_e32 v15, v32
	v_mov_b32_e32 v16, v33
	global_load_dword v30, v[38:39], off offset:-64
	global_load_dword v31, v[38:39], off
	v_lshl_add_u64 v[38:39], v[38:39], 0, s[12:13]
	v_lshlrev_b32_e32 v17, 16, v15
	v_and_b32_e32 v15, 0xffff0000, v15
	v_lshlrev_b32_e32 v18, 16, v16
	v_and_b32_e32 v16, 0xffff0000, v16
	v_mul_f32_e32 v19, v15, v15
	v_mul_f32_e32 v20, v16, v16
	v_fmac_f32_e32 v19, v17, v17
	v_fmac_f32_e32 v20, v18, v18
	v_add_f32_e32 v19, v19, v20
	ds_bpermute_b32 v20, v8, v19
	s_waitcnt lgkmcnt(0)
	v_add_f32_e32 v19, v19, v20
	ds_bpermute_b32 v20, v9, v19
	s_waitcnt lgkmcnt(0)
	v_add_f32_e32 v19, v19, v20
	ds_bpermute_b32 v20, v10, v19
	s_waitcnt lgkmcnt(0)
	v_add_f32_e32 v19, v19, v20
	ds_bpermute_b32 v20, v11, v19
	s_waitcnt lgkmcnt(0)
	v_add_f32_e32 v19, v19, v20
	ds_bpermute_b32 v20, v12, v19
	s_waitcnt lgkmcnt(0)
	v_add_f32_e32 v19, v19, v20
	v_fmamk_f32 v19, v19, 0x3c000000, v13
	v_mul_f32_e32 v20, 0x4f800000, v19
	v_cmp_gt_f32_e32 vcc, s16, v19
	s_nop 1
	v_cndmask_b32_e32 v19, v19, v20, vcc
	v_sqrt_f32_e32 v20, v19
	s_nop 0
	v_add_u32_e32 v25, -1, v20
	v_add_u32_e32 v26, 1, v20
	v_fma_f32 v27, -v25, v20, v19
	v_fma_f32 v28, -v26, v20, v19
	v_cmp_ge_f32_e64 s[0:1], 0, v27
	s_nop 1
	v_cndmask_b32_e64 v20, v20, v25, s[0:1]
	v_cmp_lt_f32_e64 s[0:1], 0, v28
	s_nop 1
	v_cndmask_b32_e64 v20, v20, v26, s[0:1]
	v_mul_f32_e32 v25, 0x37800000, v20
	v_cndmask_b32_e32 v20, v20, v25, vcc
	v_cmp_class_f32_e32 vcc, v19, v14
	s_nop 1
	v_cndmask_b32_e32 v19, v20, v19, vcc
	v_div_scale_f32 v20, s[0:1], v19, v19, 1.0
	v_rcp_f32_e32 v25, v20
	v_div_scale_f32 v26, vcc, 1.0, v19, 1.0
	v_fma_f32 v27, -v20, v25, 1.0
	v_fmac_f32_e32 v25, v27, v25
	v_mul_f32_e32 v27, v26, v25
	v_fma_f32 v28, -v20, v27, v26
	v_fmac_f32_e32 v27, v28, v25
	v_fma_f32 v20, -v20, v27, v26
	v_div_fmas_f32 v20, v20, v25, v27
	v_div_fixup_f32 v19, v20, v19, 1.0
	v_mul_f32_e32 v18, v19, v18
	v_mul_f32_e32 v17, v19, v17
	v_mul_f32_e32 v15, v19, v15
	v_mul_f32_e32 v16, v19, v16
	v_mul_f32_e32 v18, v2, v18
	v_mul_f32_e32 v17, v0, v17
	v_mul_f32_e32 v15, v1, v15
	v_mul_f32_e32 v16, v3, v16
	v_mul_f32_e32 v19, v23, v18
	v_mul_f32_e32 v20, v24, v16
	v_mul_f32_e32 v23, v23, v17
	v_mul_f32_e32 v24, v24, v15
	v_fma_f32 v17, v22, v17, -v19
	v_fma_f32 v15, v21, v15, -v20
	v_fmac_f32_e32 v23, v22, v18
	v_fmac_f32_e32 v24, v21, v16
	v_bfe_u32 v16, v17, 16, 1
	v_bfe_u32 v18, v15, 16, 1
	v_bfe_u32 v19, v23, 16, 1
	v_add3_u32 v16, v17, v16, s14
	v_bfe_u32 v20, v24, 16, 1
	v_add3_u32 v15, v15, v18, s14
	v_add3_u32 v17, v23, v19, s14
	v_lshrrev_b32_e32 v16, 16, v16
	v_add3_u32 v18, v24, v20, s14
	v_lshrrev_b32_e32 v17, 16, v17
	v_and_or_b32 v15, v15, s15, v16
	v_and_or_b32 v16, v18, s15, v17
	global_store_dword v[4:5], v15, off offset:-64
	global_store_dword v[4:5], v16, off
	v_lshl_add_u64 v[4:5], v[4:5], 0, s[12:13]
	s_lshr_b32 s0, s17, 6
	s_and_b32 s1, s17, 63
	v_mov_b32_e32 v21, s1
	v_mov_b32_e32 v22, s0
	v_cndmask_b32_e64 v21, v21, v22, s[2:3]
	v_cvt_f32_ubyte0_e32 v21, v21
	v_mul_f32_e32 v22, v6, v21
	v_mul_f32_e32 v21, v7, v21
	v_mul_f32_e32 v22, 0.15915494, v22
	v_mul_f32_e32 v21, 0.15915494, v21
	v_sin_f32_e32 v23, v22
	v_sin_f32_e32 v24, v21
	v_cos_f32_e32 v22, v22
	v_cos_f32_e32 v21, v21
	s_add_i32 s17, s17, s34
	s_cmp_lt_i32 s17, 0x8000
	s_waitcnt vmcnt(8)
	v_mov_b32_e32 v15, v34
	v_mov_b32_e32 v16, v35
	global_load_dword v32, v[38:39], off offset:-64
	global_load_dword v33, v[38:39], off
	v_lshl_add_u64 v[38:39], v[38:39], 0, s[12:13]
	v_lshlrev_b32_e32 v17, 16, v15
	v_and_b32_e32 v15, 0xffff0000, v15
	v_lshlrev_b32_e32 v18, 16, v16
	v_and_b32_e32 v16, 0xffff0000, v16
	v_mul_f32_e32 v19, v15, v15
	v_mul_f32_e32 v20, v16, v16
	v_fmac_f32_e32 v19, v17, v17
	v_fmac_f32_e32 v20, v18, v18
	v_add_f32_e32 v19, v19, v20
	ds_bpermute_b32 v20, v8, v19
	s_waitcnt lgkmcnt(0)
	v_add_f32_e32 v19, v19, v20
	ds_bpermute_b32 v20, v9, v19
	s_waitcnt lgkmcnt(0)
	v_add_f32_e32 v19, v19, v20
	ds_bpermute_b32 v20, v10, v19
	s_waitcnt lgkmcnt(0)
	v_add_f32_e32 v19, v19, v20
	ds_bpermute_b32 v20, v11, v19
	s_waitcnt lgkmcnt(0)
	v_add_f32_e32 v19, v19, v20
	ds_bpermute_b32 v20, v12, v19
	s_waitcnt lgkmcnt(0)
	v_add_f32_e32 v19, v19, v20
	v_fmamk_f32 v19, v19, 0x3c000000, v13
	v_mul_f32_e32 v20, 0x4f800000, v19
	v_cmp_gt_f32_e32 vcc, s16, v19
	s_nop 1
	v_cndmask_b32_e32 v19, v19, v20, vcc
	v_sqrt_f32_e32 v20, v19
	s_nop 0
	v_add_u32_e32 v25, -1, v20
	v_add_u32_e32 v26, 1, v20
	v_fma_f32 v27, -v25, v20, v19
	v_fma_f32 v28, -v26, v20, v19
	v_cmp_ge_f32_e64 s[0:1], 0, v27
	s_nop 1
	v_cndmask_b32_e64 v20, v20, v25, s[0:1]
	v_cmp_lt_f32_e64 s[0:1], 0, v28
	s_nop 1
	v_cndmask_b32_e64 v20, v20, v26, s[0:1]
	v_mul_f32_e32 v25, 0x37800000, v20
	v_cndmask_b32_e32 v20, v20, v25, vcc
	v_cmp_class_f32_e32 vcc, v19, v14
	s_nop 1
	v_cndmask_b32_e32 v19, v20, v19, vcc
	v_div_scale_f32 v20, s[0:1], v19, v19, 1.0
	v_rcp_f32_e32 v25, v20
	v_div_scale_f32 v26, vcc, 1.0, v19, 1.0
	v_fma_f32 v27, -v20, v25, 1.0
	v_fmac_f32_e32 v25, v27, v25
	v_mul_f32_e32 v27, v26, v25
	v_fma_f32 v28, -v20, v27, v26
	v_fmac_f32_e32 v27, v28, v25
	v_fma_f32 v20, -v20, v27, v26
	v_div_fmas_f32 v20, v20, v25, v27
	v_div_fixup_f32 v19, v20, v19, 1.0
	v_mul_f32_e32 v18, v19, v18
	v_mul_f32_e32 v17, v19, v17
	v_mul_f32_e32 v15, v19, v15
	v_mul_f32_e32 v16, v19, v16
	v_mul_f32_e32 v18, v2, v18
	v_mul_f32_e32 v17, v0, v17
	v_mul_f32_e32 v15, v1, v15
	v_mul_f32_e32 v16, v3, v16
	v_mul_f32_e32 v19, v23, v18
	v_mul_f32_e32 v20, v24, v16
	v_mul_f32_e32 v23, v23, v17
	v_mul_f32_e32 v24, v24, v15
	v_fma_f32 v17, v22, v17, -v19
	v_fma_f32 v15, v21, v15, -v20
	v_fmac_f32_e32 v23, v22, v18
	v_fmac_f32_e32 v24, v21, v16
	v_bfe_u32 v16, v17, 16, 1
	v_bfe_u32 v18, v15, 16, 1
	v_bfe_u32 v19, v23, 16, 1
	v_add3_u32 v16, v17, v16, s14
	v_bfe_u32 v20, v24, 16, 1
	v_add3_u32 v15, v15, v18, s14
	v_add3_u32 v17, v23, v19, s14
	v_lshrrev_b32_e32 v16, 16, v16
	v_add3_u32 v18, v24, v20, s14
	v_lshrrev_b32_e32 v17, 16, v17
	v_and_or_b32 v15, v15, s15, v16
	v_and_or_b32 v16, v18, s15, v17
	global_store_dword v[4:5], v15, off offset:-64
	global_store_dword v[4:5], v16, off
	v_lshl_add_u64 v[4:5], v[4:5], 0, s[12:13]
	s_lshr_b32 s0, s17, 6
	s_and_b32 s1, s17, 63
	v_mov_b32_e32 v21, s1
	v_mov_b32_e32 v22, s0
	v_cndmask_b32_e64 v21, v21, v22, s[2:3]
	v_cvt_f32_ubyte0_e32 v21, v21
	v_mul_f32_e32 v22, v6, v21
	v_mul_f32_e32 v21, v7, v21
	v_mul_f32_e32 v22, 0.15915494, v22
	v_mul_f32_e32 v21, 0.15915494, v21
	v_sin_f32_e32 v23, v22
	v_sin_f32_e32 v24, v21
	v_cos_f32_e32 v22, v22
	v_cos_f32_e32 v21, v21
	s_add_i32 s17, s17, s34
	s_cmp_lt_i32 s17, 0x8000
	s_waitcnt vmcnt(10)
; __device__ __forceinline__ unsigned pk2(float lo, float hi) { return f2bf(lo) | (f2bf(hi) << 16); }
; __global__ void __launch_bounds__(NWAVES * 64, 2) mk_fwd(Args args) {
;     ...
;         for (int row = gw; row < MTOK; row += NGW) {
;             const int s = row & (SEQ - 1);
;             const float pos = (float)(a == 0 ? (s >> 6) : (s & 63));
;             const float rev0 = pos * invf0 * 0.15915494309189535f, rev1 = pos * invf1 * 0.15915494309189535f;
;             const float sn0 = __builtin_amdgcn_sinf(rev0), cs0 = __builtin_amdgcn_cosf(rev0), sn1 = __builtin_amdgcn_sinf(rev1), cs1 = __builtin_amdgcn_cosf(rev1);
;             unsigned* prow = (unsigned*)(PROJ + (size_t)row * INW + a * 64 + i);
; #pragma unroll
;             for (int it = 4; it < 5; ++it) {
;                 unsigned* p = prow + (it * 2 + hh) * 64;
;                 const unsigned u1 = p[0], u2 = p[16];
;                 const float x1a = __builtin_bit_cast(float, u1 << 16), x1b = __builtin_bit_cast(float, u1 & 0xffff0000u);
;                 const float x2a = __builtin_bit_cast(float, u2 << 16), x2b = __builtin_bit_cast(float, u2 & 0xffff0000u);
;                 float ss = (x1a * x1a + x1b * x1b) + (x2a * x2a + x2b * x2b);
; #pragma unroll
;                 for (int o = 1; o < 32; o <<= 1) ss += __shfl_xor(ss, o);
;                 const float rstd = 1.0f / sqrtf(ss * (1.f / 128.f) + EPS);
;                 const bool isq = it < 4;
;                 const float y1a = x1a * rstd * (isq ? gq1a : gk1a), y1b = x1b * rstd * (isq ? gq1b : gk1b);
;                 const float y2a = x2a * rstd * (isq ? gq2a : gk2a), y2b = x2b * rstd * (isq ? gq2b : gk2b);
;                 p[0] = pk2(y1a * cs0 - y2a * sn0, y1b * cs1 - y2b * sn1);
;                 p[16] = pk2(y2a * cs0 + y1a * sn0, y2b * cs1 + y1b * sn1);
;             }
	v_mov_b32_e32 v15, v36
	v_mov_b32_e32 v16, v37
	global_load_dword v34, v[38:39], off offset:-64
	global_load_dword v35, v[38:39], off
	v_lshl_add_u64 v[38:39], v[38:39], 0, s[12:13]
	v_lshlrev_b32_e32 v17, 16, v15
	v_and_b32_e32 v15, 0xffff0000, v15
	v_lshlrev_b32_e32 v18, 16, v16
	v_and_b32_e32 v16, 0xffff0000, v16
	v_mul_f32_e32 v19, v15, v15
	v_mul_f32_e32 v20, v16, v16
	v_fmac_f32_e32 v19, v17, v17
	v_fmac_f32_e32 v20, v18, v18
	v_add_f32_e32 v19, v19, v20
	ds_bpermute_b32 v20, v8, v19
	s_waitcnt lgkmcnt(0)
	v_add_f32_e32 v19, v19, v20
	ds_bpermute_b32 v20, v9, v19
	s_waitcnt lgkmcnt(0)
	v_add_f32_e32 v19, v19, v20
	ds_bpermute_b32 v20, v10, v19
	s_waitcnt lgkmcnt(0)
	v_add_f32_e32 v19, v19, v20
	ds_bpermute_b32 v20, v11, v19
	s_waitcnt lgkmcnt(0)
	v_add_f32_e32 v19, v19, v20
	ds_bpermute_b32 v20, v12, v19
	s_waitcnt lgkmcnt(0)
	v_add_f32_e32 v19, v19, v20
	v_fmamk_f32 v19, v19, 0x3c000000, v13
	v_mul_f32_e32 v20, 0x4f800000, v19
	v_cmp_gt_f32_e32 vcc, s16, v19
	s_nop 1
	v_cndmask_b32_e32 v19, v19, v20, vcc
	v_sqrt_f32_e32 v20, v19
	s_nop 0
	v_add_u32_e32 v25, -1, v20
	v_add_u32_e32 v26, 1, v20
	v_fma_f32 v27, -v25, v20, v19
	v_fma_f32 v28, -v26, v20, v19
	v_cmp_ge_f32_e64 s[0:1], 0, v27
	s_nop 1
	v_cndmask_b32_e64 v20, v20, v25, s[0:1]
	v_cmp_lt_f32_e64 s[0:1], 0, v28
	s_nop 1
	v_cndmask_b32_e64 v20, v20, v26, s[0:1]
	v_mul_f32_e32 v25, 0x37800000, v20
	v_cndmask_b32_e32 v20, v20, v25, vcc
	v_cmp_class_f32_e32 vcc, v19, v14
	s_nop 1
	v_cndmask_b32_e32 v19, v20, v19, vcc
	v_div_scale_f32 v20, s[0:1], v19, v19, 1.0
	v_rcp_f32_e32 v25, v20
	v_div_scale_f32 v26, vcc, 1.0, v19, 1.0
	v_fma_f32 v27, -v20, v25, 1.0
	v_fmac_f32_e32 v25, v27, v25
	v_mul_f32_e32 v27, v26, v25
	v_fma_f32 v28, -v20, v27, v26
	v_fmac_f32_e32 v27, v28, v25
	v_fma_f32 v20, -v20, v27, v26
	v_div_fmas_f32 v20, v20, v25, v27
	v_div_fixup_f32 v19, v20, v19, 1.0
	v_mul_f32_e32 v18, v19, v18
	v_mul_f32_e32 v17, v19, v17
	v_mul_f32_e32 v15, v19, v15
	v_mul_f32_e32 v16, v19, v16
	v_mul_f32_e32 v18, v2, v18
	v_mul_f32_e32 v17, v0, v17
	v_mul_f32_e32 v15, v1, v15
	v_mul_f32_e32 v16, v3, v16
	v_mul_f32_e32 v19, v23, v18
	v_mul_f32_e32 v20, v24, v16
	v_mul_f32_e32 v23, v23, v17
	v_mul_f32_e32 v24, v24, v15
	v_fma_f32 v17, v22, v17, -v19
	v_fma_f32 v15, v21, v15, -v20
	v_fmac_f32_e32 v23, v22, v18
	v_fmac_f32_e32 v24, v21, v16
	v_bfe_u32 v16, v17, 16, 1
	v_bfe_u32 v18, v15, 16, 1
	v_bfe_u32 v19, v23, 16, 1
	v_add3_u32 v16, v17, v16, s14
	v_bfe_u32 v20, v24, 16, 1
	v_add3_u32 v15, v15, v18, s14
	v_add3_u32 v17, v23, v19, s14
	v_lshrrev_b32_e32 v16, 16, v16
	v_add3_u32 v18, v24, v20, s14
	v_lshrrev_b32_e32 v17, 16, v17
	v_and_or_b32 v15, v15, s15, v16
	v_and_or_b32 v16, v18, s15, v17
	global_store_dword v[4:5], v15, off offset:-64
	global_store_dword v[4:5], v16, off
	v_lshl_add_u64 v[4:5], v[4:5], 0, s[12:13]
	s_lshr_b32 s0, s17, 6
	s_and_b32 s1, s17, 63
	v_mov_b32_e32 v21, s1
	v_mov_b32_e32 v22, s0
	v_cndmask_b32_e64 v21, v21, v22, s[2:3]
	v_cvt_f32_ubyte0_e32 v21, v21
	v_mul_f32_e32 v22, v6, v21
	v_mul_f32_e32 v21, v7, v21
	v_mul_f32_e32 v22, 0.15915494, v22
	v_mul_f32_e32 v21, 0.15915494, v21
	v_sin_f32_e32 v23, v22
	v_sin_f32_e32 v24, v21
	v_cos_f32_e32 v22, v22
	v_cos_f32_e32 v21, v21
	s_add_i32 s17, s17, s34
	s_cmp_lt_i32 s17, 0x8000
	s_waitcnt vmcnt(10)
	v_mov_b32_e32 v15, v30
	v_mov_b32_e32 v16, v31
	global_load_dword v36, v[38:39], off offset:-64
	global_load_dword v37, v[38:39], off
	v_lshl_add_u64 v[38:39], v[38:39], 0, s[12:13]
	v_lshlrev_b32_e32 v17, 16, v15
	v_and_b32_e32 v15, 0xffff0000, v15
	v_lshlrev_b32_e32 v18, 16, v16
	v_and_b32_e32 v16, 0xffff0000, v16
	v_mul_f32_e32 v19, v15, v15
	v_mul_f32_e32 v20, v16, v16
	v_fmac_f32_e32 v19, v17, v17
	v_fmac_f32_e32 v20, v18, v18
	v_add_f32_e32 v19, v19, v20
	ds_bpermute_b32 v20, v8, v19
	s_waitcnt lgkmcnt(0)
	v_add_f32_e32 v19, v19, v20
	ds_bpermute_b32 v20, v9, v19
	s_waitcnt lgkmcnt(0)
	v_add_f32_e32 v19, v19, v20
	ds_bpermute_b32 v20, v10, v19
	s_waitcnt lgkmcnt(0)
	v_add_f32_e32 v19, v19, v20
	ds_bpermute_b32 v20, v11, v19
	s_waitcnt lgkmcnt(0)
	v_add_f32_e32 v19, v19, v20
	ds_bpermute_b32 v20, v12, v19
	s_waitcnt lgkmcnt(0)
	v_add_f32_e32 v19, v19, v20
	v_fmamk_f32 v19, v19, 0x3c000000, v13
	v_mul_f32_e32 v20, 0x4f800000, v19
	v_cmp_gt_f32_e32 vcc, s16, v19
	s_nop 1
	v_cndmask_b32_e32 v19, v19, v20, vcc
	v_sqrt_f32_e32 v20, v19
	s_nop 0
	v_add_u32_e32 v25, -1, v20
	v_add_u32_e32 v26, 1, v20
	v_fma_f32 v27, -v25, v20, v19
	v_fma_f32 v28, -v26, v20, v19
	v_cmp_ge_f32_e64 s[0:1], 0, v27
	s_nop 1
	v_cndmask_b32_e64 v20, v20, v25, s[0:1]
	v_cmp_lt_f32_e64 s[0:1], 0, v28
	s_nop 1
	v_cndmask_b32_e64 v20, v20, v26, s[0:1]
	v_mul_f32_e32 v25, 0x37800000, v20
	v_cndmask_b32_e32 v20, v20, v25, vcc
	v_cmp_class_f32_e32 vcc, v19, v14
	s_nop 1
	v_cndmask_b32_e32 v19, v20, v19, vcc
	v_div_scale_f32 v20, s[0:1], v19, v19, 1.0
	v_rcp_f32_e32 v25, v20
	v_div_scale_f32 v26, vcc, 1.0, v19, 1.0
	v_fma_f32 v27, -v20, v25, 1.0
	v_fmac_f32_e32 v25, v27, v25
	v_mul_f32_e32 v27, v26, v25
	v_fma_f32 v28, -v20, v27, v26
	v_fmac_f32_e32 v27, v28, v25
	v_fma_f32 v20, -v20, v27, v26
	v_div_fmas_f32 v20, v20, v25, v27
	v_div_fixup_f32 v19, v20, v19, 1.0
	v_mul_f32_e32 v18, v19, v18
	v_mul_f32_e32 v17, v19, v17
	v_mul_f32_e32 v15, v19, v15
	v_mul_f32_e32 v16, v19, v16
	v_mul_f32_e32 v18, v2, v18
	v_mul_f32_e32 v17, v0, v17
	v_mul_f32_e32 v15, v1, v15
	v_mul_f32_e32 v16, v3, v16
	v_mul_f32_e32 v19, v23, v18
	v_mul_f32_e32 v20, v24, v16
	v_mul_f32_e32 v23, v23, v17
	v_mul_f32_e32 v24, v24, v15
	v_fma_f32 v17, v22, v17, -v19
	v_fma_f32 v15, v21, v15, -v20
	v_fmac_f32_e32 v23, v22, v18
	v_fmac_f32_e32 v24, v21, v16
	v_bfe_u32 v16, v17, 16, 1
	v_bfe_u32 v18, v15, 16, 1
	v_bfe_u32 v19, v23, 16, 1
	v_add3_u32 v16, v17, v16, s14
	v_bfe_u32 v20, v24, 16, 1
	v_add3_u32 v15, v15, v18, s14
	v_add3_u32 v17, v23, v19, s14
	v_lshrrev_b32_e32 v16, 16, v16
	v_add3_u32 v18, v24, v20, s14
	v_lshrrev_b32_e32 v17, 16, v17
	v_and_or_b32 v15, v15, s15, v16
	v_and_or_b32 v16, v18, s15, v17
	global_store_dword v[4:5], v15, off offset:-64
	global_store_dword v[4:5], v16, off
	v_lshl_add_u64 v[4:5], v[4:5], 0, s[12:13]
	s_lshr_b32 s0, s17, 6
	s_and_b32 s1, s17, 63
	v_mov_b32_e32 v21, s1
	v_mov_b32_e32 v22, s0
	v_cndmask_b32_e64 v21, v21, v22, s[2:3]
	v_cvt_f32_ubyte0_e32 v21, v21
	v_mul_f32_e32 v22, v6, v21
	v_mul_f32_e32 v21, v7, v21
	v_mul_f32_e32 v22, 0.15915494, v22
	v_mul_f32_e32 v21, 0.15915494, v21
	v_sin_f32_e32 v23, v22
	v_sin_f32_e32 v24, v21
	v_cos_f32_e32 v22, v22
	v_cos_f32_e32 v21, v21
	s_add_i32 s17, s17, s34
	s_cmp_lt_i32 s17, 0x8000
	s_waitcnt vmcnt(10)
; __device__ __forceinline__ unsigned pk2(float lo, float hi) { return f2bf(lo) | (f2bf(hi) << 16); }
; __global__ void __launch_bounds__(NWAVES * 64, 2) mk_fwd(Args args) {
;     ...
;         for (int row = gw; row < MTOK; row += NGW) {
;             const int s = row & (SEQ - 1);
;             const float pos = (float)(a == 0 ? (s >> 6) : (s & 63));
;             const float rev0 = pos * invf0 * 0.15915494309189535f, rev1 = pos * invf1 * 0.15915494309189535f;
;             const float sn0 = __builtin_amdgcn_sinf(rev0), cs0 = __builtin_amdgcn_cosf(rev0), sn1 = __builtin_amdgcn_sinf(rev1), cs1 = __builtin_amdgcn_cosf(rev1);
;             unsigned* prow = (unsigned*)(PROJ + (size_t)row * INW + a * 64 + i);
; #pragma unroll
;             for (int it = 4; it < 5; ++it) {
;                 unsigned* p = prow + (it * 2 + hh) * 64;
;                 const unsigned u1 = p[0], u2 = p[16];
;                 const float x1a = __builtin_bit_cast(float, u1 << 16), x1b = __builtin_bit_cast(float, u1 & 0xffff0000u);
;                 const float x2a = __builtin_bit_cast(float, u2 << 16), x2b = __builtin_bit_cast(float, u2 & 0xffff0000u);
;                 float ss = (x1a * x1a + x1b * x1b) + (x2a * x2a + x2b * x2b);
; #pragma unroll
;                 for (int o = 1; o < 32; o <<= 1) ss += __shfl_xor(ss, o);
;                 const float rstd = 1.0f / sqrtf(ss * (1.f / 128.f) + EPS);
;                 const bool isq = it < 4;
;                 const float y1a = x1a * rstd * (isq ? gq1a : gk1a), y1b = x1b * rstd * (isq ? gq1b : gk1b);
;                 const float y2a = x2a * rstd * (isq ? gq2a : gk2a), y2b = x2b * rstd * (isq ? gq2b : gk2b);
;                 p[0] = pk2(y1a * cs0 - y2a * sn0, y1b * cs1 - y2b * sn1);
;                 p[16] = pk2(y2a * cs0 + y1a * sn0, y2b * cs1 + y1b * sn1);
;             }
	v_mov_b32_e32 v15, v32
	v_mov_b32_e32 v16, v33
	global_load_dword v30, v[38:39], off offset:-64
	global_load_dword v31, v[38:39], off
	v_lshl_add_u64 v[38:39], v[38:39], 0, s[12:13]
	v_lshlrev_b32_e32 v17, 16, v15
	v_and_b32_e32 v15, 0xffff0000, v15
	v_lshlrev_b32_e32 v18, 16, v16
	v_and_b32_e32 v16, 0xffff0000, v16
	v_mul_f32_e32 v19, v15, v15
	v_mul_f32_e32 v20, v16, v16
	v_fmac_f32_e32 v19, v17, v17
	v_fmac_f32_e32 v20, v18, v18
	v_add_f32_e32 v19, v19, v20
	ds_bpermute_b32 v20, v8, v19
	s_waitcnt lgkmcnt(0)
	v_add_f32_e32 v19, v19, v20
	ds_bpermute_b32 v20, v9, v19
	s_waitcnt lgkmcnt(0)
	v_add_f32_e32 v19, v19, v20
	ds_bpermute_b32 v20, v10, v19
	s_waitcnt lgkmcnt(0)
	v_add_f32_e32 v19, v19, v20
	ds_bpermute_b32 v20, v11, v19
	s_waitcnt lgkmcnt(0)
	v_add_f32_e32 v19, v19, v20
	ds_bpermute_b32 v20, v12, v19
	s_waitcnt lgkmcnt(0)
	v_add_f32_e32 v19, v19, v20
	v_fmamk_f32 v19, v19, 0x3c000000, v13
	v_mul_f32_e32 v20, 0x4f800000, v19
	v_cmp_gt_f32_e32 vcc, s16, v19
	s_nop 1
	v_cndmask_b32_e32 v19, v19, v20, vcc
	v_sqrt_f32_e32 v20, v19
	s_nop 0
	v_add_u32_e32 v25, -1, v20
	v_add_u32_e32 v26, 1, v20
	v_fma_f32 v27, -v25, v20, v19
	v_fma_f32 v28, -v26, v20, v19
	v_cmp_ge_f32_e64 s[0:1], 0, v27
	s_nop 1
	v_cndmask_b32_e64 v20, v20, v25, s[0:1]
	v_cmp_lt_f32_e64 s[0:1], 0, v28
	s_nop 1
	v_cndmask_b32_e64 v20, v20, v26, s[0:1]
	v_mul_f32_e32 v25, 0x37800000, v20
	v_cndmask_b32_e32 v20, v20, v25, vcc
	v_cmp_class_f32_e32 vcc, v19, v14
	s_nop 1
	v_cndmask_b32_e32 v19, v20, v19, vcc
	v_div_scale_f32 v20, s[0:1], v19, v19, 1.0
	v_rcp_f32_e32 v25, v20
	v_div_scale_f32 v26, vcc, 1.0, v19, 1.0
	v_fma_f32 v27, -v20, v25, 1.0
	v_fmac_f32_e32 v25, v27, v25
	v_mul_f32_e32 v27, v26, v25
	v_fma_f32 v28, -v20, v27, v26
	v_fmac_f32_e32 v27, v28, v25
	v_fma_f32 v20, -v20, v27, v26
	v_div_fmas_f32 v20, v20, v25, v27
	v_div_fixup_f32 v19, v20, v19, 1.0
	v_mul_f32_e32 v18, v19, v18
	v_mul_f32_e32 v17, v19, v17
	v_mul_f32_e32 v15, v19, v15
	v_mul_f32_e32 v16, v19, v16
	v_mul_f32_e32 v18, v2, v18
	v_mul_f32_e32 v17, v0, v17
	v_mul_f32_e32 v15, v1, v15
	v_mul_f32_e32 v16, v3, v16
	v_mul_f32_e32 v19, v23, v18
	v_mul_f32_e32 v20, v24, v16
	v_mul_f32_e32 v23, v23, v17
	v_mul_f32_e32 v24, v24, v15
	v_fma_f32 v17, v22, v17, -v19
	v_fma_f32 v15, v21, v15, -v20
	v_fmac_f32_e32 v23, v22, v18
	v_fmac_f32_e32 v24, v21, v16
	v_bfe_u32 v16, v17, 16, 1
	v_bfe_u32 v18, v15, 16, 1
	v_bfe_u32 v19, v23, 16, 1
	v_add3_u32 v16, v17, v16, s14
	v_bfe_u32 v20, v24, 16, 1
	v_add3_u32 v15, v15, v18, s14
	v_add3_u32 v17, v23, v19, s14
	v_lshrrev_b32_e32 v16, 16, v16
	v_add3_u32 v18, v24, v20, s14
	v_lshrrev_b32_e32 v17, 16, v17
	v_and_or_b32 v15, v15, s15, v16
	v_and_or_b32 v16, v18, s15, v17
	global_store_dword v[4:5], v15, off offset:-64
	global_store_dword v[4:5], v16, off
	v_lshl_add_u64 v[4:5], v[4:5], 0, s[12:13]
	s_lshr_b32 s0, s17, 6
	s_and_b32 s1, s17, 63
	v_mov_b32_e32 v21, s1
	v_mov_b32_e32 v22, s0
	v_cndmask_b32_e64 v21, v21, v22, s[2:3]
	v_cvt_f32_ubyte0_e32 v21, v21
	v_mul_f32_e32 v22, v6, v21
	v_mul_f32_e32 v21, v7, v21
	v_mul_f32_e32 v22, 0.15915494, v22
	v_mul_f32_e32 v21, 0.15915494, v21
	v_sin_f32_e32 v23, v22
	v_sin_f32_e32 v24, v21
	v_cos_f32_e32 v22, v22
	v_cos_f32_e32 v21, v21
	s_add_i32 s17, s17, s34
	s_cmp_lt_i32 s17, 0x8000
	s_waitcnt vmcnt(10)
	v_mov_b32_e32 v15, v34
	v_mov_b32_e32 v16, v35
	global_load_dword v32, v[38:39], off offset:-64
	global_load_dword v33, v[38:39], off
	v_lshl_add_u64 v[38:39], v[38:39], 0, s[12:13]
	v_lshlrev_b32_e32 v17, 16, v15
	v_and_b32_e32 v15, 0xffff0000, v15
	v_lshlrev_b32_e32 v18, 16, v16
	v_and_b32_e32 v16, 0xffff0000, v16
	v_mul_f32_e32 v19, v15, v15
	v_mul_f32_e32 v20, v16, v16
	v_fmac_f32_e32 v19, v17, v17
	v_fmac_f32_e32 v20, v18, v18
	v_add_f32_e32 v19, v19, v20
	ds_bpermute_b32 v20, v8, v19
	s_waitcnt lgkmcnt(0)
	v_add_f32_e32 v19, v19, v20
	ds_bpermute_b32 v20, v9, v19
	s_waitcnt lgkmcnt(0)
	v_add_f32_e32 v19, v19, v20
	ds_bpermute_b32 v20, v10, v19
	s_waitcnt lgkmcnt(0)
	v_add_f32_e32 v19, v19, v20
	ds_bpermute_b32 v20, v11, v19
	s_waitcnt lgkmcnt(0)
	v_add_f32_e32 v19, v19, v20
	ds_bpermute_b32 v20, v12, v19
	s_waitcnt lgkmcnt(0)
	v_add_f32_e32 v19, v19, v20
	v_fmamk_f32 v19, v19, 0x3c000000, v13
	v_mul_f32_e32 v20, 0x4f800000, v19
	v_cmp_gt_f32_e32 vcc, s16, v19
	s_nop 1
	v_cndmask_b32_e32 v19, v19, v20, vcc
	v_sqrt_f32_e32 v20, v19
	s_nop 0
	v_add_u32_e32 v25, -1, v20
	v_add_u32_e32 v26, 1, v20
	v_fma_f32 v27, -v25, v20, v19
	v_fma_f32 v28, -v26, v20, v19
	v_cmp_ge_f32_e64 s[0:1], 0, v27
	s_nop 1
	v_cndmask_b32_e64 v20, v20, v25, s[0:1]
	v_cmp_lt_f32_e64 s[0:1], 0, v28
	s_nop 1
	v_cndmask_b32_e64 v20, v20, v26, s[0:1]
	v_mul_f32_e32 v25, 0x37800000, v20
	v_cndmask_b32_e32 v20, v20, v25, vcc
	v_cmp_class_f32_e32 vcc, v19, v14
	s_nop 1
	v_cndmask_b32_e32 v19, v20, v19, vcc
	v_div_scale_f32 v20, s[0:1], v19, v19, 1.0
	v_rcp_f32_e32 v25, v20
	v_div_scale_f32 v26, vcc, 1.0, v19, 1.0
	v_fma_f32 v27, -v20, v25, 1.0
	v_fmac_f32_e32 v25, v27, v25
	v_mul_f32_e32 v27, v26, v25
	v_fma_f32 v28, -v20, v27, v26
	v_fmac_f32_e32 v27, v28, v25
	v_fma_f32 v20, -v20, v27, v26
	v_div_fmas_f32 v20, v20, v25, v27
	v_div_fixup_f32 v19, v20, v19, 1.0
	v_mul_f32_e32 v18, v19, v18
	v_mul_f32_e32 v17, v19, v17
	v_mul_f32_e32 v15, v19, v15
	v_mul_f32_e32 v16, v19, v16
	v_mul_f32_e32 v18, v2, v18
	v_mul_f32_e32 v17, v0, v17
	v_mul_f32_e32 v15, v1, v15
	v_mul_f32_e32 v16, v3, v16
	v_mul_f32_e32 v19, v23, v18
	v_mul_f32_e32 v20, v24, v16
	v_mul_f32_e32 v23, v23, v17
	v_mul_f32_e32 v24, v24, v15
	v_fma_f32 v17, v22, v17, -v19
	v_fma_f32 v15, v21, v15, -v20
	v_fmac_f32_e32 v23, v22, v18
	v_fmac_f32_e32 v24, v21, v16
	v_bfe_u32 v16, v17, 16, 1
	v_bfe_u32 v18, v15, 16, 1
	v_bfe_u32 v19, v23, 16, 1
	v_add3_u32 v16, v17, v16, s14
	v_bfe_u32 v20, v24, 16, 1
	v_add3_u32 v15, v15, v18, s14
	v_add3_u32 v17, v23, v19, s14
	v_lshrrev_b32_e32 v16, 16, v16
	v_add3_u32 v18, v24, v20, s14
	v_lshrrev_b32_e32 v17, 16, v17
	v_and_or_b32 v15, v15, s15, v16
	v_and_or_b32 v16, v18, s15, v17
	global_store_dword v[4:5], v15, off offset:-64
	global_store_dword v[4:5], v16, off
	v_lshl_add_u64 v[4:5], v[4:5], 0, s[12:13]
	s_lshr_b32 s0, s17, 6
	s_and_b32 s1, s17, 63
	v_mov_b32_e32 v21, s1
	v_mov_b32_e32 v22, s0
	v_cndmask_b32_e64 v21, v21, v22, s[2:3]
	v_cvt_f32_ubyte0_e32 v21, v21
	v_mul_f32_e32 v22, v6, v21
	v_mul_f32_e32 v21, v7, v21
	v_mul_f32_e32 v22, 0.15915494, v22
	v_mul_f32_e32 v21, 0.15915494, v21
	v_sin_f32_e32 v23, v22
	v_sin_f32_e32 v24, v21
	v_cos_f32_e32 v22, v22
	v_cos_f32_e32 v21, v21
	s_add_i32 s17, s17, s34
	s_cmp_lt_i32 s17, 0x8000
	s_waitcnt vmcnt(10)
; __device__ __forceinline__ unsigned pk2(float lo, float hi) { return f2bf(lo) | (f2bf(hi) << 16); }
; __global__ void __launch_bounds__(NWAVES * 64, 2) mk_fwd(Args args) {
;     ...
;         for (int row = gw; row < MTOK; row += NGW) {
;             const int s = row & (SEQ - 1);
;             const float pos = (float)(a == 0 ? (s >> 6) : (s & 63));
;             const float rev0 = pos * invf0 * 0.15915494309189535f, rev1 = pos * invf1 * 0.15915494309189535f;
;             const float sn0 = __builtin_amdgcn_sinf(rev0), cs0 = __builtin_amdgcn_cosf(rev0), sn1 = __builtin_amdgcn_sinf(rev1), cs1 = __builtin_amdgcn_cosf(rev1);
;             unsigned* prow = (unsigned*)(PROJ + (size_t)row * INW + a * 64 + i);
; #pragma unroll
;             for (int it = 4; it < 5; ++it) {
;                 unsigned* p = prow + (it * 2 + hh) * 64;
;                 const unsigned u1 = p[0], u2 = p[16];
;                 const float x1a = __builtin_bit_cast(float, u1 << 16), x1b = __builtin_bit_cast(float, u1 & 0xffff0000u);
;                 const float x2a = __builtin_bit_cast(float, u2 << 16), x2b = __builtin_bit_cast(float, u2 & 0xffff0000u);
;                 float ss = (x1a * x1a + x1b * x1b) + (x2a * x2a + x2b * x2b);
; #pragma unroll
;                 for (int o = 1; o < 32; o <<= 1) ss += __shfl_xor(ss, o);
;                 const float rstd = 1.0f / sqrtf(ss * (1.f / 128.f) + EPS);
;                 const bool isq = it < 4;
;                 const float y1a = x1a * rstd * (isq ? gq1a : gk1a), y1b = x1b * rstd * (isq ? gq1b : gk1b);
;                 const float y2a = x2a * rstd * (isq ? gq2a : gk2a), y2b = x2b * rstd * (isq ? gq2b : gk2b);
;                 p[0] = pk2(y1a * cs0 - y2a * sn0, y1b * cs1 - y2b * sn1);
;                 p[16] = pk2(y2a * cs0 + y1a * sn0, y2b * cs1 + y1b * sn1);
;             }
	v_mov_b32_e32 v15, v36
	v_mov_b32_e32 v16, v37
	global_load_dword v34, v[38:39], off offset:-64
	global_load_dword v35, v[38:39], off
	v_lshl_add_u64 v[38:39], v[38:39], 0, s[12:13]
	v_lshlrev_b32_e32 v17, 16, v15
	v_and_b32_e32 v15, 0xffff0000, v15
	v_lshlrev_b32_e32 v18, 16, v16
	v_and_b32_e32 v16, 0xffff0000, v16
	v_mul_f32_e32 v19, v15, v15
	v_mul_f32_e32 v20, v16, v16
	v_fmac_f32_e32 v19, v17, v17
	v_fmac_f32_e32 v20, v18, v18
	v_add_f32_e32 v19, v19, v20
	ds_bpermute_b32 v20, v8, v19
	s_waitcnt lgkmcnt(0)
	v_add_f32_e32 v19, v19, v20
	ds_bpermute_b32 v20, v9, v19
	s_waitcnt lgkmcnt(0)
	v_add_f32_e32 v19, v19, v20
	ds_bpermute_b32 v20, v10, v19
	s_waitcnt lgkmcnt(0)
	v_add_f32_e32 v19, v19, v20
	ds_bpermute_b32 v20, v11, v19
	s_waitcnt lgkmcnt(0)
	v_add_f32_e32 v19, v19, v20
	ds_bpermute_b32 v20, v12, v19
	s_waitcnt lgkmcnt(0)
	v_add_f32_e32 v19, v19, v20
	v_fmamk_f32 v19, v19, 0x3c000000, v13
	v_mul_f32_e32 v20, 0x4f800000, v19
	v_cmp_gt_f32_e32 vcc, s16, v19
	s_nop 1
	v_cndmask_b32_e32 v19, v19, v20, vcc
	v_sqrt_f32_e32 v20, v19
	s_nop 0
	v_add_u32_e32 v25, -1, v20
	v_add_u32_e32 v26, 1, v20
	v_fma_f32 v27, -v25, v20, v19
	v_fma_f32 v28, -v26, v20, v19
	v_cmp_ge_f32_e64 s[0:1], 0, v27
	s_nop 1
	v_cndmask_b32_e64 v20, v20, v25, s[0:1]
	v_cmp_lt_f32_e64 s[0:1], 0, v28
	s_nop 1
	v_cndmask_b32_e64 v20, v20, v26, s[0:1]
	v_mul_f32_e32 v25, 0x37800000, v20
	v_cndmask_b32_e32 v20, v20, v25, vcc
	v_cmp_class_f32_e32 vcc, v19, v14
	s_nop 1
	v_cndmask_b32_e32 v19, v20, v19, vcc
	v_div_scale_f32 v20, s[0:1], v19, v19, 1.0
	v_rcp_f32_e32 v25, v20
	v_div_scale_f32 v26, vcc, 1.0, v19, 1.0
	v_fma_f32 v27, -v20, v25, 1.0
	v_fmac_f32_e32 v25, v27, v25
	v_mul_f32_e32 v27, v26, v25
	v_fma_f32 v28, -v20, v27, v26
	v_fmac_f32_e32 v27, v28, v25
	v_fma_f32 v20, -v20, v27, v26
	v_div_fmas_f32 v20, v20, v25, v27
	v_div_fixup_f32 v19, v20, v19, 1.0
	v_mul_f32_e32 v18, v19, v18
	v_mul_f32_e32 v17, v19, v17
	v_mul_f32_e32 v15, v19, v15
	v_mul_f32_e32 v16, v19, v16
	v_mul_f32_e32 v18, v2, v18
	v_mul_f32_e32 v17, v0, v17
	v_mul_f32_e32 v15, v1, v15
	v_mul_f32_e32 v16, v3, v16
	v_mul_f32_e32 v19, v23, v18
	v_mul_f32_e32 v20, v24, v16
	v_mul_f32_e32 v23, v23, v17
	v_mul_f32_e32 v24, v24, v15
	v_fma_f32 v17, v22, v17, -v19
	v_fma_f32 v15, v21, v15, -v20
	v_fmac_f32_e32 v23, v22, v18
	v_fmac_f32_e32 v24, v21, v16
	v_bfe_u32 v16, v17, 16, 1
	v_bfe_u32 v18, v15, 16, 1
	v_bfe_u32 v19, v23, 16, 1
	v_add3_u32 v16, v17, v16, s14
	v_bfe_u32 v20, v24, 16, 1
	v_add3_u32 v15, v15, v18, s14
	v_add3_u32 v17, v23, v19, s14
	v_lshrrev_b32_e32 v16, 16, v16
	v_add3_u32 v18, v24, v20, s14
	v_lshrrev_b32_e32 v17, 16, v17
	v_and_or_b32 v15, v15, s15, v16
	v_and_or_b32 v16, v18, s15, v17
	global_store_dword v[4:5], v15, off offset:-64
	global_store_dword v[4:5], v16, off
	v_lshl_add_u64 v[4:5], v[4:5], 0, s[12:13]
	s_lshr_b32 s0, s17, 6
	s_and_b32 s1, s17, 63
	v_mov_b32_e32 v21, s1
	v_mov_b32_e32 v22, s0
	v_cndmask_b32_e64 v21, v21, v22, s[2:3]
	v_cvt_f32_ubyte0_e32 v21, v21
	v_mul_f32_e32 v22, v6, v21
	v_mul_f32_e32 v21, v7, v21
	v_mul_f32_e32 v22, 0.15915494, v22
	v_mul_f32_e32 v21, 0.15915494, v21
	v_sin_f32_e32 v23, v22
	v_sin_f32_e32 v24, v21
	v_cos_f32_e32 v22, v22
	v_cos_f32_e32 v21, v21
	s_add_i32 s17, s17, s34
	s_cmp_lt_i32 s17, 0x8000
	s_waitcnt vmcnt(10)
	v_mov_b32_e32 v15, v30
	v_mov_b32_e32 v16, v31
	global_load_dword v36, v[38:39], off offset:-64
	global_load_dword v37, v[38:39], off
	v_lshl_add_u64 v[38:39], v[38:39], 0, s[12:13]
	v_lshlrev_b32_e32 v17, 16, v15
	v_and_b32_e32 v15, 0xffff0000, v15
	v_lshlrev_b32_e32 v18, 16, v16
	v_and_b32_e32 v16, 0xffff0000, v16
	v_mul_f32_e32 v19, v15, v15
	v_mul_f32_e32 v20, v16, v16
	v_fmac_f32_e32 v19, v17, v17
	v_fmac_f32_e32 v20, v18, v18
	v_add_f32_e32 v19, v19, v20
	ds_bpermute_b32 v20, v8, v19
	s_waitcnt lgkmcnt(0)
	v_add_f32_e32 v19, v19, v20
	ds_bpermute_b32 v20, v9, v19
	s_waitcnt lgkmcnt(0)
	v_add_f32_e32 v19, v19, v20
	ds_bpermute_b32 v20, v10, v19
	s_waitcnt lgkmcnt(0)
	v_add_f32_e32 v19, v19, v20
	ds_bpermute_b32 v20, v11, v19
	s_waitcnt lgkmcnt(0)
	v_add_f32_e32 v19, v19, v20
	ds_bpermute_b32 v20, v12, v19
	s_waitcnt lgkmcnt(0)
	v_add_f32_e32 v19, v19, v20
	v_fmamk_f32 v19, v19, 0x3c000000, v13
	v_mul_f32_e32 v20, 0x4f800000, v19
	v_cmp_gt_f32_e32 vcc, s16, v19
	s_nop 1
	v_cndmask_b32_e32 v19, v19, v20, vcc
	v_sqrt_f32_e32 v20, v19
	s_nop 0
	v_add_u32_e32 v25, -1, v20
	v_add_u32_e32 v26, 1, v20
	v_fma_f32 v27, -v25, v20, v19
	v_fma_f32 v28, -v26, v20, v19
	v_cmp_ge_f32_e64 s[0:1], 0, v27
	s_nop 1
	v_cndmask_b32_e64 v20, v20, v25, s[0:1]
	v_cmp_lt_f32_e64 s[0:1], 0, v28
	s_nop 1
	v_cndmask_b32_e64 v20, v20, v26, s[0:1]
	v_mul_f32_e32 v25, 0x37800000, v20
	v_cndmask_b32_e32 v20, v20, v25, vcc
	v_cmp_class_f32_e32 vcc, v19, v14
	s_nop 1
	v_cndmask_b32_e32 v19, v20, v19, vcc
	v_div_scale_f32 v20, s[0:1], v19, v19, 1.0
	v_rcp_f32_e32 v25, v20
	v_div_scale_f32 v26, vcc, 1.0, v19, 1.0
	v_fma_f32 v27, -v20, v25, 1.0
	v_fmac_f32_e32 v25, v27, v25
	v_mul_f32_e32 v27, v26, v25
	v_fma_f32 v28, -v20, v27, v26
	v_fmac_f32_e32 v27, v28, v25
	v_fma_f32 v20, -v20, v27, v26
	v_div_fmas_f32 v20, v20, v25, v27
	v_div_fixup_f32 v19, v20, v19, 1.0
	v_mul_f32_e32 v18, v19, v18
	v_mul_f32_e32 v17, v19, v17
	v_mul_f32_e32 v15, v19, v15
	v_mul_f32_e32 v16, v19, v16
	v_mul_f32_e32 v18, v2, v18
	v_mul_f32_e32 v17, v0, v17
	v_mul_f32_e32 v15, v1, v15
	v_mul_f32_e32 v16, v3, v16
	v_mul_f32_e32 v19, v23, v18
	v_mul_f32_e32 v20, v24, v16
	v_mul_f32_e32 v23, v23, v17
	v_mul_f32_e32 v24, v24, v15
	v_fma_f32 v17, v22, v17, -v19
	v_fma_f32 v15, v21, v15, -v20
	v_fmac_f32_e32 v23, v22, v18
	v_fmac_f32_e32 v24, v21, v16
	v_bfe_u32 v16, v17, 16, 1
	v_bfe_u32 v18, v15, 16, 1
	v_bfe_u32 v19, v23, 16, 1
	v_add3_u32 v16, v17, v16, s14
	v_bfe_u32 v20, v24, 16, 1
	v_add3_u32 v15, v15, v18, s14
	v_add3_u32 v17, v23, v19, s14
	v_lshrrev_b32_e32 v16, 16, v16
	v_add3_u32 v18, v24, v20, s14
	v_lshrrev_b32_e32 v17, 16, v17
	v_and_or_b32 v15, v15, s15, v16
	v_and_or_b32 v16, v18, s15, v17
	global_store_dword v[4:5], v15, off offset:-64
	global_store_dword v[4:5], v16, off
	v_lshl_add_u64 v[4:5], v[4:5], 0, s[12:13]
	s_lshr_b32 s0, s17, 6
	s_and_b32 s1, s17, 63
	v_mov_b32_e32 v21, s1
	v_mov_b32_e32 v22, s0
	v_cndmask_b32_e64 v21, v21, v22, s[2:3]
	v_cvt_f32_ubyte0_e32 v21, v21
	v_mul_f32_e32 v22, v6, v21
	v_mul_f32_e32 v21, v7, v21
	v_mul_f32_e32 v22, 0.15915494, v22
	v_mul_f32_e32 v21, 0.15915494, v21
	v_sin_f32_e32 v23, v22
	v_sin_f32_e32 v24, v21
	v_cos_f32_e32 v22, v22
	v_cos_f32_e32 v21, v21
	s_add_i32 s17, s17, s34
	s_cmp_lt_i32 s17, 0x8000
	s_waitcnt vmcnt(10)
; __device__ __forceinline__ unsigned pk2(float lo, float hi) { return f2bf(lo) | (f2bf(hi) << 16); }
; __global__ void __launch_bounds__(NWAVES * 64, 2) mk_fwd(Args args) {
;     ...
;         for (int row = gw; row < MTOK; row += NGW) {
;             const int s = row & (SEQ - 1);
;             const float pos = (float)(a == 0 ? (s >> 6) : (s & 63));
;             const float rev0 = pos * invf0 * 0.15915494309189535f, rev1 = pos * invf1 * 0.15915494309189535f;
;             const float sn0 = __builtin_amdgcn_sinf(rev0), cs0 = __builtin_amdgcn_cosf(rev0), sn1 = __builtin_amdgcn_sinf(rev1), cs1 = __builtin_amdgcn_cosf(rev1);
;             unsigned* prow = (unsigned*)(PROJ + (size_t)row * INW + a * 64 + i);
; #pragma unroll
;             for (int it = 4; it < 5; ++it) {
;                 unsigned* p = prow + (it * 2 + hh) * 64;
;                 const unsigned u1 = p[0], u2 = p[16];
;                 const float x1a = __builtin_bit_cast(float, u1 << 16), x1b = __builtin_bit_cast(float, u1 & 0xffff0000u);
;                 const float x2a = __builtin_bit_cast(float, u2 << 16), x2b = __builtin_bit_cast(float, u2 & 0xffff0000u);
;                 float ss = (x1a * x1a + x1b * x1b) + (x2a * x2a + x2b * x2b);
; #pragma unroll
;                 for (int o = 1; o < 32; o <<= 1) ss += __shfl_xor(ss, o);
;                 const float rstd = 1.0f / sqrtf(ss * (1.f / 128.f) + EPS);
;                 const bool isq = it < 4;
;                 const float y1a = x1a * rstd * (isq ? gq1a : gk1a), y1b = x1b * rstd * (isq ? gq1b : gk1b);
;                 const float y2a = x2a * rstd * (isq ? gq2a : gk2a), y2b = x2b * rstd * (isq ? gq2b : gk2b);
;                 p[0] = pk2(y1a * cs0 - y2a * sn0, y1b * cs1 - y2b * sn1);
;                 p[16] = pk2(y2a * cs0 + y1a * sn0, y2b * cs1 + y1b * sn1);
;             }
	v_mov_b32_e32 v15, v32
	v_mov_b32_e32 v16, v33
	global_load_dword v30, v[38:39], off offset:-64
	global_load_dword v31, v[38:39], off
	v_lshl_add_u64 v[38:39], v[38:39], 0, s[12:13]
	v_lshlrev_b32_e32 v17, 16, v15
	v_and_b32_e32 v15, 0xffff0000, v15
	v_lshlrev_b32_e32 v18, 16, v16
	v_and_b32_e32 v16, 0xffff0000, v16
	v_mul_f32_e32 v19, v15, v15
	v_mul_f32_e32 v20, v16, v16
	v_fmac_f32_e32 v19, v17, v17
	v_fmac_f32_e32 v20, v18, v18
	v_add_f32_e32 v19, v19, v20
	ds_bpermute_b32 v20, v8, v19
	s_waitcnt lgkmcnt(0)
	v_add_f32_e32 v19, v19, v20
	ds_bpermute_b32 v20, v9, v19
	s_waitcnt lgkmcnt(0)
	v_add_f32_e32 v19, v19, v20
	ds_bpermute_b32 v20, v10, v19
	s_waitcnt lgkmcnt(0)
	v_add_f32_e32 v19, v19, v20
	ds_bpermute_b32 v20, v11, v19
	s_waitcnt lgkmcnt(0)
	v_add_f32_e32 v19, v19, v20
	ds_bpermute_b32 v20, v12, v19
	s_waitcnt lgkmcnt(0)
	v_add_f32_e32 v19, v19, v20
	v_fmamk_f32 v19, v19, 0x3c000000, v13
	v_mul_f32_e32 v20, 0x4f800000, v19
	v_cmp_gt_f32_e32 vcc, s16, v19
	s_nop 1
	v_cndmask_b32_e32 v19, v19, v20, vcc
	v_sqrt_f32_e32 v20, v19
	s_nop 0
	v_add_u32_e32 v25, -1, v20
	v_add_u32_e32 v26, 1, v20
	v_fma_f32 v27, -v25, v20, v19
	v_fma_f32 v28, -v26, v20, v19
	v_cmp_ge_f32_e64 s[0:1], 0, v27
	s_nop 1
	v_cndmask_b32_e64 v20, v20, v25, s[0:1]
	v_cmp_lt_f32_e64 s[0:1], 0, v28
	s_nop 1
	v_cndmask_b32_e64 v20, v20, v26, s[0:1]
	v_mul_f32_e32 v25, 0x37800000, v20
	v_cndmask_b32_e32 v20, v20, v25, vcc
	v_cmp_class_f32_e32 vcc, v19, v14
	s_nop 1
	v_cndmask_b32_e32 v19, v20, v19, vcc
	v_div_scale_f32 v20, s[0:1], v19, v19, 1.0
	v_rcp_f32_e32 v25, v20
	v_div_scale_f32 v26, vcc, 1.0, v19, 1.0
	v_fma_f32 v27, -v20, v25, 1.0
	v_fmac_f32_e32 v25, v27, v25
	v_mul_f32_e32 v27, v26, v25
	v_fma_f32 v28, -v20, v27, v26
	v_fmac_f32_e32 v27, v28, v25
	v_fma_f32 v20, -v20, v27, v26
	v_div_fmas_f32 v20, v20, v25, v27
	v_div_fixup_f32 v19, v20, v19, 1.0
	v_mul_f32_e32 v18, v19, v18
	v_mul_f32_e32 v17, v19, v17
	v_mul_f32_e32 v15, v19, v15
	v_mul_f32_e32 v16, v19, v16
	v_mul_f32_e32 v18, v2, v18
	v_mul_f32_e32 v17, v0, v17
	v_mul_f32_e32 v15, v1, v15
	v_mul_f32_e32 v16, v3, v16
	v_mul_f32_e32 v19, v23, v18
	v_mul_f32_e32 v20, v24, v16
	v_mul_f32_e32 v23, v23, v17
	v_mul_f32_e32 v24, v24, v15
	v_fma_f32 v17, v22, v17, -v19
	v_fma_f32 v15, v21, v15, -v20
	v_fmac_f32_e32 v23, v22, v18
	v_fmac_f32_e32 v24, v21, v16
	v_bfe_u32 v16, v17, 16, 1
	v_bfe_u32 v18, v15, 16, 1
	v_bfe_u32 v19, v23, 16, 1
	v_add3_u32 v16, v17, v16, s14
	v_bfe_u32 v20, v24, 16, 1
	v_add3_u32 v15, v15, v18, s14
	v_add3_u32 v17, v23, v19, s14
	v_lshrrev_b32_e32 v16, 16, v16
	v_add3_u32 v18, v24, v20, s14
	v_lshrrev_b32_e32 v17, 16, v17
	v_and_or_b32 v15, v15, s15, v16
	v_and_or_b32 v16, v18, s15, v17
	global_store_dword v[4:5], v15, off offset:-64
	global_store_dword v[4:5], v16, off
	v_lshl_add_u64 v[4:5], v[4:5], 0, s[12:13]
	s_lshr_b32 s0, s17, 6
	s_and_b32 s1, s17, 63
	v_mov_b32_e32 v21, s1
	v_mov_b32_e32 v22, s0
	v_cndmask_b32_e64 v21, v21, v22, s[2:3]
	v_cvt_f32_ubyte0_e32 v21, v21
	v_mul_f32_e32 v22, v6, v21
	v_mul_f32_e32 v21, v7, v21
	v_mul_f32_e32 v22, 0.15915494, v22
	v_mul_f32_e32 v21, 0.15915494, v21
	v_sin_f32_e32 v23, v22
	v_sin_f32_e32 v24, v21
	v_cos_f32_e32 v22, v22
	v_cos_f32_e32 v21, v21
	s_add_i32 s17, s17, s34
	s_cmp_lt_i32 s17, 0x8000
	s_waitcnt vmcnt(10)
	v_mov_b32_e32 v15, v34
	v_mov_b32_e32 v16, v35
	global_load_dword v32, v[38:39], off offset:-64
	global_load_dword v33, v[38:39], off
	v_lshl_add_u64 v[38:39], v[38:39], 0, s[12:13]
	v_lshlrev_b32_e32 v17, 16, v15
	v_and_b32_e32 v15, 0xffff0000, v15
	v_lshlrev_b32_e32 v18, 16, v16
	v_and_b32_e32 v16, 0xffff0000, v16
	v_mul_f32_e32 v19, v15, v15
	v_mul_f32_e32 v20, v16, v16
	v_fmac_f32_e32 v19, v17, v17
	v_fmac_f32_e32 v20, v18, v18
	v_add_f32_e32 v19, v19, v20
	ds_bpermute_b32 v20, v8, v19
	s_waitcnt lgkmcnt(0)
	v_add_f32_e32 v19, v19, v20
	ds_bpermute_b32 v20, v9, v19
	s_waitcnt lgkmcnt(0)
	v_add_f32_e32 v19, v19, v20
	ds_bpermute_b32 v20, v10, v19
	s_waitcnt lgkmcnt(0)
	v_add_f32_e32 v19, v19, v20
	ds_bpermute_b32 v20, v11, v19
	s_waitcnt lgkmcnt(0)
	v_add_f32_e32 v19, v19, v20
	ds_bpermute_b32 v20, v12, v19
	s_waitcnt lgkmcnt(0)
	v_add_f32_e32 v19, v19, v20
	v_fmamk_f32 v19, v19, 0x3c000000, v13
	v_mul_f32_e32 v20, 0x4f800000, v19
	v_cmp_gt_f32_e32 vcc, s16, v19
	s_nop 1
	v_cndmask_b32_e32 v19, v19, v20, vcc
	v_sqrt_f32_e32 v20, v19
	s_nop 0
	v_add_u32_e32 v25, -1, v20
	v_add_u32_e32 v26, 1, v20
	v_fma_f32 v27, -v25, v20, v19
	v_fma_f32 v28, -v26, v20, v19
	v_cmp_ge_f32_e64 s[0:1], 0, v27
	s_nop 1
	v_cndmask_b32_e64 v20, v20, v25, s[0:1]
	v_cmp_lt_f32_e64 s[0:1], 0, v28
	s_nop 1
	v_cndmask_b32_e64 v20, v20, v26, s[0:1]
	v_mul_f32_e32 v25, 0x37800000, v20
	v_cndmask_b32_e32 v20, v20, v25, vcc
	v_cmp_class_f32_e32 vcc, v19, v14
	s_nop 1
	v_cndmask_b32_e32 v19, v20, v19, vcc
	v_div_scale_f32 v20, s[0:1], v19, v19, 1.0
	v_rcp_f32_e32 v25, v20
	v_div_scale_f32 v26, vcc, 1.0, v19, 1.0
	v_fma_f32 v27, -v20, v25, 1.0
	v_fmac_f32_e32 v25, v27, v25
	v_mul_f32_e32 v27, v26, v25
	v_fma_f32 v28, -v20, v27, v26
	v_fmac_f32_e32 v27, v28, v25
	v_fma_f32 v20, -v20, v27, v26
	v_div_fmas_f32 v20, v20, v25, v27
	v_div_fixup_f32 v19, v20, v19, 1.0
	v_mul_f32_e32 v18, v19, v18
	v_mul_f32_e32 v17, v19, v17
	v_mul_f32_e32 v15, v19, v15
	v_mul_f32_e32 v16, v19, v16
	v_mul_f32_e32 v18, v2, v18
	v_mul_f32_e32 v17, v0, v17
	v_mul_f32_e32 v15, v1, v15
	v_mul_f32_e32 v16, v3, v16
	v_mul_f32_e32 v19, v23, v18
	v_mul_f32_e32 v20, v24, v16
	v_mul_f32_e32 v23, v23, v17
	v_mul_f32_e32 v24, v24, v15
	v_fma_f32 v17, v22, v17, -v19
	v_fma_f32 v15, v21, v15, -v20
	v_fmac_f32_e32 v23, v22, v18
	v_fmac_f32_e32 v24, v21, v16
	v_bfe_u32 v16, v17, 16, 1
	v_bfe_u32 v18, v15, 16, 1
	v_bfe_u32 v19, v23, 16, 1
	v_add3_u32 v16, v17, v16, s14
	v_bfe_u32 v20, v24, 16, 1
	v_add3_u32 v15, v15, v18, s14
	v_add3_u32 v17, v23, v19, s14
	v_lshrrev_b32_e32 v16, 16, v16
	v_add3_u32 v18, v24, v20, s14
	v_lshrrev_b32_e32 v17, 16, v17
	v_and_or_b32 v15, v15, s15, v16
	v_and_or_b32 v16, v18, s15, v17
	global_store_dword v[4:5], v15, off offset:-64
	global_store_dword v[4:5], v16, off
	v_lshl_add_u64 v[4:5], v[4:5], 0, s[12:13]
	s_lshr_b32 s0, s17, 6
	s_and_b32 s1, s17, 63
	v_mov_b32_e32 v21, s1
	v_mov_b32_e32 v22, s0
	v_cndmask_b32_e64 v21, v21, v22, s[2:3]
	v_cvt_f32_ubyte0_e32 v21, v21
	v_mul_f32_e32 v22, v6, v21
	v_mul_f32_e32 v21, v7, v21
	v_mul_f32_e32 v22, 0.15915494, v22
	v_mul_f32_e32 v21, 0.15915494, v21
	v_sin_f32_e32 v23, v22
	v_sin_f32_e32 v24, v21
	v_cos_f32_e32 v22, v22
	v_cos_f32_e32 v21, v21
	s_add_i32 s17, s17, s34
	s_cmp_lt_i32 s17, 0x8000
	s_waitcnt vmcnt(10)
; __device__ __forceinline__ unsigned pk2(float lo, float hi) { return f2bf(lo) | (f2bf(hi) << 16); }
; __global__ void __launch_bounds__(NWAVES * 64, 2) mk_fwd(Args args) {
;     ...
;         for (int row = gw; row < MTOK; row += NGW) {
;             const int s = row & (SEQ - 1);
;             const float pos = (float)(a == 0 ? (s >> 6) : (s & 63));
;             const float rev0 = pos * invf0 * 0.15915494309189535f, rev1 = pos * invf1 * 0.15915494309189535f;
;             const float sn0 = __builtin_amdgcn_sinf(rev0), cs0 = __builtin_amdgcn_cosf(rev0), sn1 = __builtin_amdgcn_sinf(rev1), cs1 = __builtin_amdgcn_cosf(rev1);
;             unsigned* prow = (unsigned*)(PROJ + (size_t)row * INW + a * 64 + i);
; #pragma unroll
;             for (int it = 4; it < 5; ++it) {
;                 unsigned* p = prow + (it * 2 + hh) * 64;
;                 const unsigned u1 = p[0], u2 = p[16];
;                 const float x1a = __builtin_bit_cast(float, u1 << 16), x1b = __builtin_bit_cast(float, u1 & 0xffff0000u);
;                 const float x2a = __builtin_bit_cast(float, u2 << 16), x2b = __builtin_bit_cast(float, u2 & 0xffff0000u);
;                 float ss = (x1a * x1a + x1b * x1b) + (x2a * x2a + x2b * x2b);
; #pragma unroll
;                 for (int o = 1; o < 32; o <<= 1) ss += __shfl_xor(ss, o);
;                 const float rstd = 1.0f / sqrtf(ss * (1.f / 128.f) + EPS);
;                 const bool isq = it < 4;
;                 const float y1a = x1a * rstd * (isq ? gq1a : gk1a), y1b = x1b * rstd * (isq ? gq1b : gk1b);
;                 const float y2a = x2a * rstd * (isq ? gq2a : gk2a), y2b = x2b * rstd * (isq ? gq2b : gk2b);
;                 p[0] = pk2(y1a * cs0 - y2a * sn0, y1b * cs1 - y2b * sn1);
;                 p[16] = pk2(y2a * cs0 + y1a * sn0, y2b * cs1 + y1b * sn1);
;             }
	v_mov_b32_e32 v15, v36
	v_mov_b32_e32 v16, v37
	global_load_dword v34, v[38:39], off offset:-64
	global_load_dword v35, v[38:39], off
	v_lshl_add_u64 v[38:39], v[38:39], 0, s[12:13]
	v_lshlrev_b32_e32 v17, 16, v15
	v_and_b32_e32 v15, 0xffff0000, v15
	v_lshlrev_b32_e32 v18, 16, v16
	v_and_b32_e32 v16, 0xffff0000, v16
	v_mul_f32_e32 v19, v15, v15
	v_mul_f32_e32 v20, v16, v16
	v_fmac_f32_e32 v19, v17, v17
	v_fmac_f32_e32 v20, v18, v18
	v_add_f32_e32 v19, v19, v20
	ds_bpermute_b32 v20, v8, v19
	s_waitcnt lgkmcnt(0)
	v_add_f32_e32 v19, v19, v20
	ds_bpermute_b32 v20, v9, v19
	s_waitcnt lgkmcnt(0)
	v_add_f32_e32 v19, v19, v20
	ds_bpermute_b32 v20, v10, v19
	s_waitcnt lgkmcnt(0)
	v_add_f32_e32 v19, v19, v20
	ds_bpermute_b32 v20, v11, v19
	s_waitcnt lgkmcnt(0)
	v_add_f32_e32 v19, v19, v20
	ds_bpermute_b32 v20, v12, v19
	s_waitcnt lgkmcnt(0)
	v_add_f32_e32 v19, v19, v20
	v_fmamk_f32 v19, v19, 0x3c000000, v13
	v_mul_f32_e32 v20, 0x4f800000, v19
	v_cmp_gt_f32_e32 vcc, s16, v19
	s_nop 1
	v_cndmask_b32_e32 v19, v19, v20, vcc
	v_sqrt_f32_e32 v20, v19
	s_nop 0
	v_add_u32_e32 v25, -1, v20
	v_add_u32_e32 v26, 1, v20
	v_fma_f32 v27, -v25, v20, v19
	v_fma_f32 v28, -v26, v20, v19
	v_cmp_ge_f32_e64 s[0:1], 0, v27
	s_nop 1
	v_cndmask_b32_e64 v20, v20, v25, s[0:1]
	v_cmp_lt_f32_e64 s[0:1], 0, v28
	s_nop 1
	v_cndmask_b32_e64 v20, v20, v26, s[0:1]
	v_mul_f32_e32 v25, 0x37800000, v20
	v_cndmask_b32_e32 v20, v20, v25, vcc
	v_cmp_class_f32_e32 vcc, v19, v14
	s_nop 1
	v_cndmask_b32_e32 v19, v20, v19, vcc
	v_div_scale_f32 v20, s[0:1], v19, v19, 1.0
	v_rcp_f32_e32 v25, v20
	v_div_scale_f32 v26, vcc, 1.0, v19, 1.0
	v_fma_f32 v27, -v20, v25, 1.0
	v_fmac_f32_e32 v25, v27, v25
	v_mul_f32_e32 v27, v26, v25
	v_fma_f32 v28, -v20, v27, v26
	v_fmac_f32_e32 v27, v28, v25
	v_fma_f32 v20, -v20, v27, v26
	v_div_fmas_f32 v20, v20, v25, v27
	v_div_fixup_f32 v19, v20, v19, 1.0
	v_mul_f32_e32 v18, v19, v18
	v_mul_f32_e32 v17, v19, v17
	v_mul_f32_e32 v15, v19, v15
	v_mul_f32_e32 v16, v19, v16
	v_mul_f32_e32 v18, v2, v18
	v_mul_f32_e32 v17, v0, v17
	v_mul_f32_e32 v15, v1, v15
	v_mul_f32_e32 v16, v3, v16
	v_mul_f32_e32 v19, v23, v18
	v_mul_f32_e32 v20, v24, v16
	v_mul_f32_e32 v23, v23, v17
	v_mul_f32_e32 v24, v24, v15
	v_fma_f32 v17, v22, v17, -v19
	v_fma_f32 v15, v21, v15, -v20
	v_fmac_f32_e32 v23, v22, v18
	v_fmac_f32_e32 v24, v21, v16
	v_bfe_u32 v16, v17, 16, 1
	v_bfe_u32 v18, v15, 16, 1
	v_bfe_u32 v19, v23, 16, 1
	v_add3_u32 v16, v17, v16, s14
	v_bfe_u32 v20, v24, 16, 1
	v_add3_u32 v15, v15, v18, s14
	v_add3_u32 v17, v23, v19, s14
	v_lshrrev_b32_e32 v16, 16, v16
	v_add3_u32 v18, v24, v20, s14
	v_lshrrev_b32_e32 v17, 16, v17
	v_and_or_b32 v15, v15, s15, v16
	v_and_or_b32 v16, v18, s15, v17
	global_store_dword v[4:5], v15, off offset:-64
	global_store_dword v[4:5], v16, off
	v_lshl_add_u64 v[4:5], v[4:5], 0, s[12:13]
	s_lshr_b32 s0, s17, 6
	s_and_b32 s1, s17, 63
	v_mov_b32_e32 v21, s1
	v_mov_b32_e32 v22, s0
	v_cndmask_b32_e64 v21, v21, v22, s[2:3]
	v_cvt_f32_ubyte0_e32 v21, v21
	v_mul_f32_e32 v22, v6, v21
	v_mul_f32_e32 v21, v7, v21
	v_mul_f32_e32 v22, 0.15915494, v22
	v_mul_f32_e32 v21, 0.15915494, v21
	v_sin_f32_e32 v23, v22
	v_sin_f32_e32 v24, v21
	v_cos_f32_e32 v22, v22
	v_cos_f32_e32 v21, v21
	s_add_i32 s17, s17, s34
	s_cmp_lt_i32 s17, 0x8000
	s_waitcnt vmcnt(10)
	v_mov_b32_e32 v15, v30
	v_mov_b32_e32 v16, v31
	global_load_dword v36, v[38:39], off offset:-64
	global_load_dword v37, v[38:39], off
	v_lshl_add_u64 v[38:39], v[38:39], 0, s[12:13]
	v_lshlrev_b32_e32 v17, 16, v15
	v_and_b32_e32 v15, 0xffff0000, v15
	v_lshlrev_b32_e32 v18, 16, v16
	v_and_b32_e32 v16, 0xffff0000, v16
	v_mul_f32_e32 v19, v15, v15
	v_mul_f32_e32 v20, v16, v16
	v_fmac_f32_e32 v19, v17, v17
	v_fmac_f32_e32 v20, v18, v18
	v_add_f32_e32 v19, v19, v20
	ds_bpermute_b32 v20, v8, v19
	s_waitcnt lgkmcnt(0)
	v_add_f32_e32 v19, v19, v20
	ds_bpermute_b32 v20, v9, v19
	s_waitcnt lgkmcnt(0)
	v_add_f32_e32 v19, v19, v20
	ds_bpermute_b32 v20, v10, v19
	s_waitcnt lgkmcnt(0)
	v_add_f32_e32 v19, v19, v20
	ds_bpermute_b32 v20, v11, v19
	s_waitcnt lgkmcnt(0)
	v_add_f32_e32 v19, v19, v20
	ds_bpermute_b32 v20, v12, v19
	s_waitcnt lgkmcnt(0)
	v_add_f32_e32 v19, v19, v20
	v_fmamk_f32 v19, v19, 0x3c000000, v13
	v_mul_f32_e32 v20, 0x4f800000, v19
	v_cmp_gt_f32_e32 vcc, s16, v19
	s_nop 1
	v_cndmask_b32_e32 v19, v19, v20, vcc
	v_sqrt_f32_e32 v20, v19
	s_nop 0
	v_add_u32_e32 v25, -1, v20
	v_add_u32_e32 v26, 1, v20
	v_fma_f32 v27, -v25, v20, v19
	v_fma_f32 v28, -v26, v20, v19
	v_cmp_ge_f32_e64 s[0:1], 0, v27
	s_nop 1
	v_cndmask_b32_e64 v20, v20, v25, s[0:1]
	v_cmp_lt_f32_e64 s[0:1], 0, v28
	s_nop 1
	v_cndmask_b32_e64 v20, v20, v26, s[0:1]
	v_mul_f32_e32 v25, 0x37800000, v20
	v_cndmask_b32_e32 v20, v20, v25, vcc
	v_cmp_class_f32_e32 vcc, v19, v14
	s_nop 1
	v_cndmask_b32_e32 v19, v20, v19, vcc
	v_div_scale_f32 v20, s[0:1], v19, v19, 1.0
	v_rcp_f32_e32 v25, v20
	v_div_scale_f32 v26, vcc, 1.0, v19, 1.0
	v_fma_f32 v27, -v20, v25, 1.0
	v_fmac_f32_e32 v25, v27, v25
	v_mul_f32_e32 v27, v26, v25
	v_fma_f32 v28, -v20, v27, v26
	v_fmac_f32_e32 v27, v28, v25
	v_fma_f32 v20, -v20, v27, v26
	v_div_fmas_f32 v20, v20, v25, v27
	v_div_fixup_f32 v19, v20, v19, 1.0
	v_mul_f32_e32 v18, v19, v18
	v_mul_f32_e32 v17, v19, v17
	v_mul_f32_e32 v15, v19, v15
	v_mul_f32_e32 v16, v19, v16
	v_mul_f32_e32 v18, v2, v18
	v_mul_f32_e32 v17, v0, v17
	v_mul_f32_e32 v15, v1, v15
	v_mul_f32_e32 v16, v3, v16
	v_mul_f32_e32 v19, v23, v18
	v_mul_f32_e32 v20, v24, v16
	v_mul_f32_e32 v23, v23, v17
	v_mul_f32_e32 v24, v24, v15
	v_fma_f32 v17, v22, v17, -v19
	v_fma_f32 v15, v21, v15, -v20
	v_fmac_f32_e32 v23, v22, v18
	v_fmac_f32_e32 v24, v21, v16
	v_bfe_u32 v16, v17, 16, 1
	v_bfe_u32 v18, v15, 16, 1
	v_bfe_u32 v19, v23, 16, 1
	v_add3_u32 v16, v17, v16, s14
	v_bfe_u32 v20, v24, 16, 1
	v_add3_u32 v15, v15, v18, s14
	v_add3_u32 v17, v23, v19, s14
	v_lshrrev_b32_e32 v16, 16, v16
	v_add3_u32 v18, v24, v20, s14
	v_lshrrev_b32_e32 v17, 16, v17
	v_and_or_b32 v15, v15, s15, v16
	v_and_or_b32 v16, v18, s15, v17
	global_store_dword v[4:5], v15, off offset:-64
	global_store_dword v[4:5], v16, off
	v_lshl_add_u64 v[4:5], v[4:5], 0, s[12:13]
	s_lshr_b32 s0, s17, 6
	s_and_b32 s1, s17, 63
	v_mov_b32_e32 v21, s1
	v_mov_b32_e32 v22, s0
	v_cndmask_b32_e64 v21, v21, v22, s[2:3]
	v_cvt_f32_ubyte0_e32 v21, v21
	v_mul_f32_e32 v22, v6, v21
	v_mul_f32_e32 v21, v7, v21
	v_mul_f32_e32 v22, 0.15915494, v22
	v_mul_f32_e32 v21, 0.15915494, v21
	v_sin_f32_e32 v23, v22
	v_sin_f32_e32 v24, v21
	v_cos_f32_e32 v22, v22
	v_cos_f32_e32 v21, v21
	s_add_i32 s17, s17, s34
	s_cmp_lt_i32 s17, 0x8000
	s_waitcnt vmcnt(10)
; __device__ __forceinline__ unsigned pk2(float lo, float hi) { return f2bf(lo) | (f2bf(hi) << 16); }
; __global__ void __launch_bounds__(NWAVES * 64, 2) mk_fwd(Args args) {
;     ...
;         for (int row = gw; row < MTOK; row += NGW) {
;             const int s = row & (SEQ - 1);
;             const float pos = (float)(a == 0 ? (s >> 6) : (s & 63));
;             const float rev0 = pos * invf0 * 0.15915494309189535f, rev1 = pos * invf1 * 0.15915494309189535f;
;             const float sn0 = __builtin_amdgcn_sinf(rev0), cs0 = __builtin_amdgcn_cosf(rev0), sn1 = __builtin_amdgcn_sinf(rev1), cs1 = __builtin_amdgcn_cosf(rev1);
;             unsigned* prow = (unsigned*)(PROJ + (size_t)row * INW + a * 64 + i);
; #pragma unroll
;             for (int it = 4; it < 5; ++it) {
;                 unsigned* p = prow + (it * 2 + hh) * 64;
;                 const unsigned u1 = p[0], u2 = p[16];
;                 const float x1a = __builtin_bit_cast(float, u1 << 16), x1b = __builtin_bit_cast(float, u1 & 0xffff0000u);
;                 const float x2a = __builtin_bit_cast(float, u2 << 16), x2b = __builtin_bit_cast(float, u2 & 0xffff0000u);
;                 float ss = (x1a * x1a + x1b * x1b) + (x2a * x2a + x2b * x2b);
; #pragma unroll
;                 for (int o = 1; o < 32; o <<= 1) ss += __shfl_xor(ss, o);
;                 const float rstd = 1.0f / sqrtf(ss * (1.f / 128.f) + EPS);
;                 const bool isq = it < 4;
;                 const float y1a = x1a * rstd * (isq ? gq1a : gk1a), y1b = x1b * rstd * (isq ? gq1b : gk1b);
;                 const float y2a = x2a * rstd * (isq ? gq2a : gk2a), y2b = x2b * rstd * (isq ? gq2b : gk2b);
;                 p[0] = pk2(y1a * cs0 - y2a * sn0, y1b * cs1 - y2b * sn1);
;                 p[16] = pk2(y2a * cs0 + y1a * sn0, y2b * cs1 + y1b * sn1);
;             }
	v_mov_b32_e32 v15, v32
	v_mov_b32_e32 v16, v33
	v_lshlrev_b32_e32 v17, 16, v15
	v_and_b32_e32 v15, 0xffff0000, v15
	v_lshlrev_b32_e32 v18, 16, v16
	v_and_b32_e32 v16, 0xffff0000, v16
	v_mul_f32_e32 v19, v15, v15
	v_mul_f32_e32 v20, v16, v16
	v_fmac_f32_e32 v19, v17, v17
	v_fmac_f32_e32 v20, v18, v18
	v_add_f32_e32 v19, v19, v20
	ds_bpermute_b32 v20, v8, v19
	s_waitcnt lgkmcnt(0)
	v_add_f32_e32 v19, v19, v20
	ds_bpermute_b32 v20, v9, v19
	s_waitcnt lgkmcnt(0)
	v_add_f32_e32 v19, v19, v20
	ds_bpermute_b32 v20, v10, v19
	s_waitcnt lgkmcnt(0)
	v_add_f32_e32 v19, v19, v20
	ds_bpermute_b32 v20, v11, v19
	s_waitcnt lgkmcnt(0)
	v_add_f32_e32 v19, v19, v20
	ds_bpermute_b32 v20, v12, v19
	s_waitcnt lgkmcnt(0)
	v_add_f32_e32 v19, v19, v20
	v_fmamk_f32 v19, v19, 0x3c000000, v13
	v_mul_f32_e32 v20, 0x4f800000, v19
	v_cmp_gt_f32_e32 vcc, s16, v19
	s_nop 1
	v_cndmask_b32_e32 v19, v19, v20, vcc
	v_sqrt_f32_e32 v20, v19
	s_nop 0
	v_add_u32_e32 v25, -1, v20
	v_add_u32_e32 v26, 1, v20
	v_fma_f32 v27, -v25, v20, v19
	v_fma_f32 v28, -v26, v20, v19
	v_cmp_ge_f32_e64 s[0:1], 0, v27
	s_nop 1
	v_cndmask_b32_e64 v20, v20, v25, s[0:1]
	v_cmp_lt_f32_e64 s[0:1], 0, v28
	s_nop 1
	v_cndmask_b32_e64 v20, v20, v26, s[0:1]
	v_mul_f32_e32 v25, 0x37800000, v20
	v_cndmask_b32_e32 v20, v20, v25, vcc
	v_cmp_class_f32_e32 vcc, v19, v14
	s_nop 1
	v_cndmask_b32_e32 v19, v20, v19, vcc
	v_div_scale_f32 v20, s[0:1], v19, v19, 1.0
	v_rcp_f32_e32 v25, v20
	v_div_scale_f32 v26, vcc, 1.0, v19, 1.0
	v_fma_f32 v27, -v20, v25, 1.0
	v_fmac_f32_e32 v25, v27, v25
	v_mul_f32_e32 v27, v26, v25
	v_fma_f32 v28, -v20, v27, v26
	v_fmac_f32_e32 v27, v28, v25
	v_fma_f32 v20, -v20, v27, v26
	v_div_fmas_f32 v20, v20, v25, v27
	v_div_fixup_f32 v19, v20, v19, 1.0
	v_mul_f32_e32 v18, v19, v18
	v_mul_f32_e32 v17, v19, v17
	v_mul_f32_e32 v15, v19, v15
	v_mul_f32_e32 v16, v19, v16
	v_mul_f32_e32 v18, v2, v18
	v_mul_f32_e32 v17, v0, v17
	v_mul_f32_e32 v15, v1, v15
	v_mul_f32_e32 v16, v3, v16
	v_mul_f32_e32 v19, v23, v18
	v_mul_f32_e32 v20, v24, v16
	v_mul_f32_e32 v23, v23, v17
	v_mul_f32_e32 v24, v24, v15
	v_fma_f32 v17, v22, v17, -v19
	v_fma_f32 v15, v21, v15, -v20
	v_fmac_f32_e32 v23, v22, v18
	v_fmac_f32_e32 v24, v21, v16
	v_bfe_u32 v16, v17, 16, 1
	v_bfe_u32 v18, v15, 16, 1
	v_bfe_u32 v19, v23, 16, 1
	v_add3_u32 v16, v17, v16, s14
	v_bfe_u32 v20, v24, 16, 1
	v_add3_u32 v15, v15, v18, s14
	v_add3_u32 v17, v23, v19, s14
	v_lshrrev_b32_e32 v16, 16, v16
	v_add3_u32 v18, v24, v20, s14
	v_lshrrev_b32_e32 v17, 16, v17
	v_and_or_b32 v15, v15, s15, v16
	v_and_or_b32 v16, v18, s15, v17
	global_store_dword v[4:5], v15, off offset:-64
	global_store_dword v[4:5], v16, off
	v_lshl_add_u64 v[4:5], v[4:5], 0, s[12:13]
	s_lshr_b32 s0, s17, 6
	s_and_b32 s1, s17, 63
	v_mov_b32_e32 v21, s1
	v_mov_b32_e32 v22, s0
	v_cndmask_b32_e64 v21, v21, v22, s[2:3]
	v_cvt_f32_ubyte0_e32 v21, v21
	v_mul_f32_e32 v22, v6, v21
	v_mul_f32_e32 v21, v7, v21
	v_mul_f32_e32 v22, 0.15915494, v22
	v_mul_f32_e32 v21, 0.15915494, v21
	v_sin_f32_e32 v23, v22
	v_sin_f32_e32 v24, v21
	v_cos_f32_e32 v22, v22
	v_cos_f32_e32 v21, v21
	s_add_i32 s17, s17, s34
	s_cmp_lt_i32 s17, 0x8000
	s_waitcnt vmcnt(8)
	v_mov_b32_e32 v15, v34
	v_mov_b32_e32 v16, v35
	v_lshlrev_b32_e32 v17, 16, v15
	v_and_b32_e32 v15, 0xffff0000, v15
	v_lshlrev_b32_e32 v18, 16, v16
	v_and_b32_e32 v16, 0xffff0000, v16
	v_mul_f32_e32 v19, v15, v15
	v_mul_f32_e32 v20, v16, v16
	v_fmac_f32_e32 v19, v17, v17
	v_fmac_f32_e32 v20, v18, v18
	v_add_f32_e32 v19, v19, v20
	ds_bpermute_b32 v20, v8, v19
	s_waitcnt lgkmcnt(0)
	v_add_f32_e32 v19, v19, v20
	ds_bpermute_b32 v20, v9, v19
	s_waitcnt lgkmcnt(0)
	v_add_f32_e32 v19, v19, v20
	ds_bpermute_b32 v20, v10, v19
	s_waitcnt lgkmcnt(0)
	v_add_f32_e32 v19, v19, v20
	ds_bpermute_b32 v20, v11, v19
	s_waitcnt lgkmcnt(0)
	v_add_f32_e32 v19, v19, v20
	ds_bpermute_b32 v20, v12, v19
	s_waitcnt lgkmcnt(0)
; __device__ __forceinline__ unsigned pk2(float lo, float hi) { return f2bf(lo) | (f2bf(hi) << 16); }
; __global__ void __launch_bounds__(NWAVES * 64, 2) mk_fwd(Args args) {
;     ...
;         for (int row = gw; row < MTOK; row += NGW) {
;             const int s = row & (SEQ - 1);
;             const float pos = (float)(a == 0 ? (s >> 6) : (s & 63));
;             const float rev0 = pos * invf0 * 0.15915494309189535f, rev1 = pos * invf1 * 0.15915494309189535f;
;             const float sn0 = __builtin_amdgcn_sinf(rev0), cs0 = __builtin_amdgcn_cosf(rev0), sn1 = __builtin_amdgcn_sinf(rev1), cs1 = __builtin_amdgcn_cosf(rev1);
;             unsigned* prow = (unsigned*)(PROJ + (size_t)row * INW + a * 64 + i);
; #pragma unroll
;             for (int it = 4; it < 5; ++it) {
;                 unsigned* p = prow + (it * 2 + hh) * 64;
;                 const unsigned u1 = p[0], u2 = p[16];
;                 const float x1a = __builtin_bit_cast(float, u1 << 16), x1b = __builtin_bit_cast(float, u1 & 0xffff0000u);
;                 const float x2a = __builtin_bit_cast(float, u2 << 16), x2b = __builtin_bit_cast(float, u2 & 0xffff0000u);
;                 float ss = (x1a * x1a + x1b * x1b) + (x2a * x2a + x2b * x2b);
; #pragma unroll
;                 for (int o = 1; o < 32; o <<= 1) ss += __shfl_xor(ss, o);
;                 const float rstd = 1.0f / sqrtf(ss * (1.f / 128.f) + EPS);
;                 const bool isq = it < 4;
;                 const float y1a = x1a * rstd * (isq ? gq1a : gk1a), y1b = x1b * rstd * (isq ? gq1b : gk1b);
;                 const float y2a = x2a * rstd * (isq ? gq2a : gk2a), y2b = x2b * rstd * (isq ? gq2b : gk2b);
;                 p[0] = pk2(y1a * cs0 - y2a * sn0, y1b * cs1 - y2b * sn1);
;                 p[16] = pk2(y2a * cs0 + y1a * sn0, y2b * cs1 + y1b * sn1);
;             }
	v_add_f32_e32 v19, v19, v20
	v_fmamk_f32 v19, v19, 0x3c000000, v13
	v_mul_f32_e32 v20, 0x4f800000, v19
	v_cmp_gt_f32_e32 vcc, s16, v19
	s_nop 1
	v_cndmask_b32_e32 v19, v19, v20, vcc
	v_sqrt_f32_e32 v20, v19
	s_nop 0
	v_add_u32_e32 v25, -1, v20
	v_add_u32_e32 v26, 1, v20
	v_fma_f32 v27, -v25, v20, v19
	v_fma_f32 v28, -v26, v20, v19
	v_cmp_ge_f32_e64 s[0:1], 0, v27
	s_nop 1
	v_cndmask_b32_e64 v20, v20, v25, s[0:1]
	v_cmp_lt_f32_e64 s[0:1], 0, v28
	s_nop 1
	v_cndmask_b32_e64 v20, v20, v26, s[0:1]
	v_mul_f32_e32 v25, 0x37800000, v20
	v_cndmask_b32_e32 v20, v20, v25, vcc
	v_cmp_class_f32_e32 vcc, v19, v14
	s_nop 1
	v_cndmask_b32_e32 v19, v20, v19, vcc
	v_div_scale_f32 v20, s[0:1], v19, v19, 1.0
	v_rcp_f32_e32 v25, v20
	v_div_scale_f32 v26, vcc, 1.0, v19, 1.0
	v_fma_f32 v27, -v20, v25, 1.0
	v_fmac_f32_e32 v25, v27, v25
	v_mul_f32_e32 v27, v26, v25
	v_fma_f32 v28, -v20, v27, v26
	v_fmac_f32_e32 v27, v28, v25
	v_fma_f32 v20, -v20, v27, v26
	v_div_fmas_f32 v20, v20, v25, v27
	v_div_fixup_f32 v19, v20, v19, 1.0
	v_mul_f32_e32 v18, v19, v18
	v_mul_f32_e32 v17, v19, v17
	v_mul_f32_e32 v15, v19, v15
	v_mul_f32_e32 v16, v19, v16
	v_mul_f32_e32 v18, v2, v18
	v_mul_f32_e32 v17, v0, v17
	v_mul_f32_e32 v15, v1, v15
	v_mul_f32_e32 v16, v3, v16
	v_mul_f32_e32 v19, v23, v18
	v_mul_f32_e32 v20, v24, v16
	v_mul_f32_e32 v23, v23, v17
	v_mul_f32_e32 v24, v24, v15
	v_fma_f32 v17, v22, v17, -v19
	v_fma_f32 v15, v21, v15, -v20
	v_fmac_f32_e32 v23, v22, v18
	v_fmac_f32_e32 v24, v21, v16
	v_bfe_u32 v16, v17, 16, 1
	v_bfe_u32 v18, v15, 16, 1
	v_bfe_u32 v19, v23, 16, 1
	v_add3_u32 v16, v17, v16, s14
	v_bfe_u32 v20, v24, 16, 1
	v_add3_u32 v15, v15, v18, s14
	v_add3_u32 v17, v23, v19, s14
	v_lshrrev_b32_e32 v16, 16, v16
	v_add3_u32 v18, v24, v20, s14
	v_lshrrev_b32_e32 v17, 16, v17
	v_and_or_b32 v15, v15, s15, v16
	v_and_or_b32 v16, v18, s15, v17
	global_store_dword v[4:5], v15, off offset:-64
	global_store_dword v[4:5], v16, off
	v_lshl_add_u64 v[4:5], v[4:5], 0, s[12:13]
	s_lshr_b32 s0, s17, 6
	s_and_b32 s1, s17, 63
	v_mov_b32_e32 v21, s1
	v_mov_b32_e32 v22, s0
	v_cndmask_b32_e64 v21, v21, v22, s[2:3]
	v_cvt_f32_ubyte0_e32 v21, v21
	v_mul_f32_e32 v22, v6, v21
	v_mul_f32_e32 v21, v7, v21
	v_mul_f32_e32 v22, 0.15915494, v22
	v_mul_f32_e32 v21, 0.15915494, v21
	v_sin_f32_e32 v23, v22
	v_sin_f32_e32 v24, v21
	v_cos_f32_e32 v22, v22
	v_cos_f32_e32 v21, v21
	s_add_i32 s17, s17, s34
	s_cmp_lt_i32 s17, 0x8000
	s_waitcnt vmcnt(6)
	v_mov_b32_e32 v15, v36
	v_mov_b32_e32 v16, v37
	v_lshlrev_b32_e32 v17, 16, v15
	v_and_b32_e32 v15, 0xffff0000, v15
	v_lshlrev_b32_e32 v18, 16, v16
	v_and_b32_e32 v16, 0xffff0000, v16
	v_mul_f32_e32 v19, v15, v15
	v_mul_f32_e32 v20, v16, v16
	v_fmac_f32_e32 v19, v17, v17
	v_fmac_f32_e32 v20, v18, v18
	v_add_f32_e32 v19, v19, v20
	ds_bpermute_b32 v20, v8, v19
	s_waitcnt lgkmcnt(0)
	v_add_f32_e32 v19, v19, v20
	ds_bpermute_b32 v20, v9, v19
	s_waitcnt lgkmcnt(0)
	v_add_f32_e32 v19, v19, v20
	ds_bpermute_b32 v20, v10, v19
	s_waitcnt lgkmcnt(0)
	v_add_f32_e32 v19, v19, v20
	ds_bpermute_b32 v20, v11, v19
	s_waitcnt lgkmcnt(0)
	v_add_f32_e32 v19, v19, v20
	ds_bpermute_b32 v20, v12, v19
	s_waitcnt lgkmcnt(0)
	v_add_f32_e32 v19, v19, v20
	v_fmamk_f32 v19, v19, 0x3c000000, v13
	v_mul_f32_e32 v20, 0x4f800000, v19
	v_cmp_gt_f32_e32 vcc, s16, v19
	s_nop 1
	v_cndmask_b32_e32 v19, v19, v20, vcc
	v_sqrt_f32_e32 v20, v19
	s_nop 0
	v_add_u32_e32 v25, -1, v20
	v_add_u32_e32 v26, 1, v20
	v_fma_f32 v27, -v25, v20, v19
	v_fma_f32 v28, -v26, v20, v19
	v_cmp_ge_f32_e64 s[0:1], 0, v27
	s_nop 1
	v_cndmask_b32_e64 v20, v20, v25, s[0:1]
	v_cmp_lt_f32_e64 s[0:1], 0, v28
	s_nop 1
	v_cndmask_b32_e64 v20, v20, v26, s[0:1]
	v_mul_f32_e32 v25, 0x37800000, v20
	v_cndmask_b32_e32 v20, v20, v25, vcc
	v_cmp_class_f32_e32 vcc, v19, v14
	s_nop 1
	v_cndmask_b32_e32 v19, v20, v19, vcc
	v_div_scale_f32 v20, s[0:1], v19, v19, 1.0
	v_rcp_f32_e32 v25, v20
	v_div_scale_f32 v26, vcc, 1.0, v19, 1.0
	v_fma_f32 v27, -v20, v25, 1.0
	v_fmac_f32_e32 v25, v27, v25
	v_mul_f32_e32 v27, v26, v25
	v_fma_f32 v28, -v20, v27, v26
	v_fmac_f32_e32 v27, v28, v25
	v_fma_f32 v20, -v20, v27, v26
	v_div_fmas_f32 v20, v20, v25, v27
	v_div_fixup_f32 v19, v20, v19, 1.0
	v_mul_f32_e32 v18, v19, v18
	v_mul_f32_e32 v17, v19, v17
	v_mul_f32_e32 v15, v19, v15
	v_mul_f32_e32 v16, v19, v16
	v_mul_f32_e32 v18, v2, v18
	v_mul_f32_e32 v17, v0, v17
	v_mul_f32_e32 v15, v1, v15
	v_mul_f32_e32 v16, v3, v16
	v_mul_f32_e32 v19, v23, v18
	v_mul_f32_e32 v20, v24, v16
	v_mul_f32_e32 v23, v23, v17
	v_mul_f32_e32 v24, v24, v15
	v_fma_f32 v17, v22, v17, -v19
	v_fma_f32 v15, v21, v15, -v20
	v_fmac_f32_e32 v23, v22, v18
	v_fmac_f32_e32 v24, v21, v16
	v_bfe_u32 v16, v17, 16, 1
	v_bfe_u32 v18, v15, 16, 1
	v_bfe_u32 v19, v23, 16, 1
	v_add3_u32 v16, v17, v16, s14
	v_bfe_u32 v20, v24, 16, 1
	v_add3_u32 v15, v15, v18, s14
	v_add3_u32 v17, v23, v19, s14
	v_lshrrev_b32_e32 v16, 16, v16
	v_add3_u32 v18, v24, v20, s14
	v_lshrrev_b32_e32 v17, 16, v17
	v_and_or_b32 v15, v15, s15, v16
	v_and_or_b32 v16, v18, s15, v17
	global_store_dword v[4:5], v15, off offset:-64
	global_store_dword v[4:5], v16, off
	v_lshl_add_u64 v[4:5], v[4:5], 0, s[12:13]
	s_branch .LBB0_411

; __device__ __forceinline__ void finishSM(f32x16& p0, f32x16& p1, float alpha, float& l_reg, bf16x8& pa0, bf16x8& pa1, bf16x8& pa2, bf16x8& pa3) {
; #pragma unroll
;   for (int r = 0; r < 16; ++r) p1[r] = __builtin_amdgcn_exp2f(p1[r]);
;   float ps = 0;
; #pragma unroll
;   for (int r = 0; r < 16; ++r) ps += p0[r];
; #pragma unroll
;   for (int r = 0; r < 16; ++r) ps += p1[r];
;   { auto rr = __builtin_amdgcn_permlane32_swap(__float_as_uint(ps), __float_as_uint(ps), false, false);
;     ps = __uint_as_float(rr[0]) + __uint_as_float(rr[1]); }
;   l_reg = l_reg * alpha + ps;
;     ...
;   PK4(p0, 0, pa0); PK4(p0, 8, pa1); PK4(p1, 0, pa2); PK4(p1, 8, pa3);
;     ...
; }
; __device__ __forceinline__ void qkt(f32x16& p0, f32x16& p1, const bf16* Ks, const bf16x8* qr, int r32, int hi) {
;   p0 = f32x16{}; p1 = f32x16{};
; #pragma unroll
;   for (int d0 = 0; d0 < 8; ++d0) { int cb = (d0 * 16 + hi * 8) * 2;
;     bf16x8 b0 = *reinterpret_cast<const bf16x8*>((const char*)Ks + KSWZ(r32, cb));
;     bf16x8 b1 = *reinterpret_cast<const bf16x8*>((const char*)Ks + KSWZ(32 + r32, cb));
;     p0 = __builtin_amdgcn_mfma_f32_32x32x16_bf16(b0, qr[d0], p0, 0, 0, 0);
;     p1 = __builtin_amdgcn_mfma_f32_32x32x16_bf16(b1, qr[d0], p1, 0, 0, 0); }
; }
; __device__ __forceinline__ int v_st(int k, int c) { const int kk = (k & ~0xC) | ((k & 4) << 1) | ((k & 8) >> 1); return ((kk >> 3) * 4 + (c >> 5)) * 512 + ((kk & 7) * 32 + (c & 31)) * 2; }
; __device__ __forceinline__ int v_rd_base(int lane) { return ((lane & 3) << 3) | (((lane >> 2) & 3) << 6) | (((lane >> 4) & 1) << 5) | (((lane >> 5) & 1) << 8); }
; template <int OFF> __device__ __forceinline__ s16x4 tr_read(int vb) {
;   s16x4 r; asm volatile("ds_read_b64_tr_b16 %0, %1 offset:%2" : "=&v"(r) : "v"(vb), "i"(OFF) : "memory"); return r;
; }
; template <int D0> __device__ __forceinline__ void pv_one(f32x16& od, int vb, bf16x8 pa0, bf16x8 pa1, bf16x8 pa2, bf16x8 pa3) {
;   const s16x4 l0 = tr_read<v_rd_off(D0, 0, 0)>(vb), h0 = tr_read<v_rd_off(D0, 0, 1)>(vb), l1 = tr_read<v_rd_off(D0, 1, 0)>(vb), h1 = tr_read<v_rd_off(D0, 1, 1)>(vb);
;   const s16x4 l2 = tr_read<v_rd_off(D0, 2, 0)>(vb), h2 = tr_read<v_rd_off(D0, 2, 1)>(vb), l3 = tr_read<v_rd_off(D0, 3, 0)>(vb), h3 = tr_read<v_rd_off(D0, 3, 1)>(vb);
;   asm volatile("s_waitcnt lgkmcnt(0)" ::: "memory"); SBAR();
;     ...
;   od = __builtin_amdgcn_mfma_f32_32x32x16_bf16(pa0, PK(l0, h0), od, 0, 0, 0);
.Ldense_loop:
	s_waitcnt lgkmcnt(7)
	v_mfma_f32_32x32x16_bf16 v[128:143], v[200:203], v[124:127], 0
	ds_read_b128 v[200:203], v176 offset:16384
	v_cvt_pk_bf16_f32 v184, v64, v65
	v_add_f32_e32 v169, v169, v64
	v_add_f32_e32 v219, v219, v65
	global_load_dwordx4 v[246:249], v183, s[98:99]
	s_waitcnt lgkmcnt(7)
	v_mfma_f32_32x32x16_bf16 v[144:159], v[204:207], v[124:127], 0
	ds_read_b128 v[204:207], v176 offset:24576
	v_cvt_pk_bf16_f32 v185, v66, v67
	v_add_f32_e32 v222, v222, v66
	v_add_f32_e32 v254, v254, v67
	s_waitcnt lgkmcnt(7)
	v_mfma_f32_32x32x16_bf16 v[128:143], v[208:211], v[120:123], v[128:143]
	ds_read_b128 v[208:211], v177 offset:16384
	v_cvt_pk_bf16_f32 v186, v68, v69
	v_add_f32_e32 v169, v169, v68
	v_add_f32_e32 v219, v219, v69
	global_load_dwordx4 v[250:253], v183, s[100:101]
	s_add_u32 s98, s98, 0x150000
	s_addc_u32 s99, s99, 0
	s_add_u32 s100, s100, 0x150000
	s_addc_u32 s101, s101, 0
	s_waitcnt lgkmcnt(7)
	v_mfma_f32_32x32x16_bf16 v[144:159], v[212:215], v[120:123], v[144:159]
	ds_read_b128 v[212:215], v177 offset:24576
	v_cvt_pk_bf16_f32 v187, v70, v71
	v_add_f32_e32 v222, v222, v70
	v_add_f32_e32 v254, v254, v71
	s_waitcnt lgkmcnt(7)
	v_mfma_f32_32x32x16_bf16 v[128:143], v[230:233], v[116:119], v[128:143]
	ds_read_b128 v[230:233], v178 offset:16384
	v_cvt_pk_bf16_f32 v188, v72, v73
	v_add_f32_e32 v169, v169, v72
	v_add_f32_e32 v219, v219, v73
	v_permlane32_swap_b32_e32 v184, v186
	global_load_dwordx4 v[164:167], v183, s[0:1] offset:512
	s_waitcnt lgkmcnt(7)
	v_mfma_f32_32x32x16_bf16 v[144:159], v[234:237], v[116:119], v[144:159]
	ds_read_b128 v[234:237], v178 offset:24576
	v_cvt_pk_bf16_f32 v189, v74, v75
	v_add_f32_e32 v222, v222, v74
	v_add_f32_e32 v254, v254, v75
	v_permlane32_swap_b32_e32 v185, v187
	s_waitcnt lgkmcnt(7)
	v_mfma_f32_32x32x16_bf16 v[128:143], v[238:241], v[112:115], v[128:143]
	ds_read_b128 v[238:241], v179 offset:16384
	v_cvt_pk_bf16_f32 v190, v76, v77
	v_add_f32_e32 v169, v169, v76
	v_add_f32_e32 v219, v219, v77
	global_load_dwordx4 v[160:163], v183, s[4:5] offset:512
	s_add_u32 s0, s0, 0x150000
	s_addc_u32 s1, s1, 0
	s_add_u32 s4, s4, 0x150000
	s_addc_u32 s5, s5, 0
	s_waitcnt lgkmcnt(7)
	v_mfma_f32_32x32x16_bf16 v[144:159], v[242:245], v[112:115], v[144:159]
	ds_read_b128 v[242:245], v179 offset:24576
	v_cvt_pk_bf16_f32 v191, v78, v79
	v_add_f32_e32 v222, v222, v78
	v_add_f32_e32 v254, v254, v79
	s_waitcnt lgkmcnt(7)
	v_mfma_f32_32x32x16_bf16 v[128:143], v[200:203], v[108:111], v[128:143]
	v_cvt_pk_bf16_f32 v192, v80, v81
	v_add_f32_e32 v169, v169, v80
	v_add_f32_e32 v219, v219, v81
	v_permlane32_swap_b32_e32 v188, v190
	s_waitcnt lgkmcnt(6)
	v_mfma_f32_32x32x16_bf16 v[144:159], v[204:207], v[108:111], v[144:159]
	v_cvt_pk_bf16_f32 v193, v82, v83
	v_add_f32_e32 v222, v222, v82
	v_add_f32_e32 v254, v254, v83
	v_permlane32_swap_b32_e32 v189, v191
	s_waitcnt lgkmcnt(5)
	v_mfma_f32_32x32x16_bf16 v[128:143], v[208:211], v[104:107], v[128:143]
	v_cvt_pk_bf16_f32 v194, v84, v85
	v_add_f32_e32 v169, v169, v84
	v_add_f32_e32 v219, v219, v85
	s_waitcnt lgkmcnt(4)
	v_mfma_f32_32x32x16_bf16 v[144:159], v[212:215], v[104:107], v[144:159]
	ds_read_b64_tr_b16 v[200:201], v182 offset:0
	ds_read_b64_tr_b16 v[202:203], v182 offset:2048
	v_cvt_pk_bf16_f32 v195, v86, v87
	v_add_f32_e32 v222, v222, v86
	v_add_f32_e32 v254, v254, v87
	s_waitcnt lgkmcnt(5)
	v_mfma_f32_32x32x16_bf16 v[128:143], v[230:233], v[100:103], v[128:143]
	ds_read_b64_tr_b16 v[204:205], v182 offset:4096
	ds_read_b64_tr_b16 v[206:207], v182 offset:6144
	v_cvt_pk_bf16_f32 v196, v88, v89
	v_add_f32_e32 v169, v169, v88
	v_add_f32_e32 v219, v219, v89
	v_permlane32_swap_b32_e32 v192, v194
	s_waitcnt lgkmcnt(6)
	v_mfma_f32_32x32x16_bf16 v[144:159], v[234:237], v[100:103], v[144:159]
	ds_read_b64_tr_b16 v[208:209], v182 offset:8192
	ds_read_b64_tr_b16 v[210:211], v182 offset:10240
	v_cvt_pk_bf16_f32 v197, v90, v91
	v_add_f32_e32 v222, v222, v90
	v_add_f32_e32 v254, v254, v91
	v_permlane32_swap_b32_e32 v193, v195
	s_waitcnt lgkmcnt(7)
	v_mfma_f32_32x32x16_bf16 v[128:143], v[238:241], v[96:99], v[128:143]
	ds_read_b64_tr_b16 v[212:213], v182 offset:12288
	ds_read_b64_tr_b16 v[214:215], v182 offset:14336
	v_cvt_pk_bf16_f32 v198, v92, v93
	v_add_f32_e32 v169, v169, v92
	v_add_f32_e32 v219, v219, v93
	s_waitcnt lgkmcnt(8)
	v_mfma_f32_32x32x16_bf16 v[144:159], v[242:245], v[96:99], v[144:159]
	ds_read_b64_tr_b16 v[230:231], v182 offset:512
	ds_read_b64_tr_b16 v[232:233], v182 offset:2560
	v_cvt_pk_bf16_f32 v199, v94, v95
	v_add_f32_e32 v222, v222, v94
	v_add_f32_e32 v254, v254, v95
	v_permlane32_swap_b32_e32 v196, v198
	v_permlane32_swap_b32_e32 v197, v199
	s_waitcnt lgkmcnt(8)
	v_mfma_f32_32x32x16_bf16 v[0:15], v[184:187], v[200:203], v[0:15]
	ds_read_b64_tr_b16 v[234:235], v182 offset:4608
	ds_read_b64_tr_b16 v[236:237], v182 offset:6656
	v_exp_f32_e32 v128, v128
	v_exp_f32_e32 v129, v129
	s_waitcnt lgkmcnt(8)
	v_mfma_f32_32x32x16_bf16 v[0:15], v[188:191], v[204:207], v[0:15]
	ds_read_b64_tr_b16 v[238:239], v182 offset:8704
	ds_read_b64_tr_b16 v[240:241], v182 offset:10752
	v_exp_f32_e32 v130, v130
	v_exp_f32_e32 v131, v131
	s_waitcnt vmcnt(3)
	ds_write_b128 v181, v[246:249] offset:49152
	s_waitcnt lgkmcnt(9)
	v_mfma_f32_32x32x16_bf16 v[0:15], v[192:195], v[208:211], v[0:15]
	ds_read_b64_tr_b16 v[242:243], v182 offset:12800
	ds_read_b64_tr_b16 v[244:245], v182 offset:14848
	v_exp_f32_e32 v132, v132
	v_exp_f32_e32 v133, v133
	s_waitcnt lgkmcnt(9)
	v_mfma_f32_32x32x16_bf16 v[0:15], v[196:199], v[212:215], v[0:15]
	ds_read_b64_tr_b16 v[200:201], v182 offset:1024
	ds_read_b64_tr_b16 v[202:203], v182 offset:3072
	v_exp_f32_e32 v134, v134
	v_exp_f32_e32 v135, v135
	s_waitcnt vmcnt(2)
; __device__ __forceinline__ void finishSM(f32x16& p0, f32x16& p1, float alpha, float& l_reg, bf16x8& pa0, bf16x8& pa1, bf16x8& pa2, bf16x8& pa3) {
; #pragma unroll
;   for (int r = 0; r < 16; ++r) p1[r] = __builtin_amdgcn_exp2f(p1[r]);
;   float ps = 0;
; #pragma unroll
;   for (int r = 0; r < 16; ++r) ps += p0[r];
; #pragma unroll
;   for (int r = 0; r < 16; ++r) ps += p1[r];
;   { auto rr = __builtin_amdgcn_permlane32_swap(__float_as_uint(ps), __float_as_uint(ps), false, false);
;     ps = __uint_as_float(rr[0]) + __uint_as_float(rr[1]); }
;   l_reg = l_reg * alpha + ps;
;     ...
;   PK4(p0, 0, pa0); PK4(p0, 8, pa1); PK4(p1, 0, pa2); PK4(p1, 8, pa3);
;     ...
; }
; __device__ __forceinline__ void qkt(f32x16& p0, f32x16& p1, const bf16* Ks, const bf16x8* qr, int r32, int hi) {
;   p0 = f32x16{}; p1 = f32x16{};
; #pragma unroll
;   for (int d0 = 0; d0 < 8; ++d0) { int cb = (d0 * 16 + hi * 8) * 2;
;     bf16x8 b0 = *reinterpret_cast<const bf16x8*>((const char*)Ks + KSWZ(r32, cb));
;     bf16x8 b1 = *reinterpret_cast<const bf16x8*>((const char*)Ks + KSWZ(32 + r32, cb));
;     p0 = __builtin_amdgcn_mfma_f32_32x32x16_bf16(b0, qr[d0], p0, 0, 0, 0);
;     p1 = __builtin_amdgcn_mfma_f32_32x32x16_bf16(b1, qr[d0], p1, 0, 0, 0); }
; }
; __device__ __forceinline__ int v_st(int k, int c) { const int kk = (k & ~0xC) | ((k & 4) << 1) | ((k & 8) >> 1); return ((kk >> 3) * 4 + (c >> 5)) * 512 + ((kk & 7) * 32 + (c & 31)) * 2; }
; __device__ __forceinline__ int v_rd_base(int lane) { return ((lane & 3) << 3) | (((lane >> 2) & 3) << 6) | (((lane >> 4) & 1) << 5) | (((lane >> 5) & 1) << 8); }
; template <int OFF> __device__ __forceinline__ s16x4 tr_read(int vb) {
;   s16x4 r; asm volatile("ds_read_b64_tr_b16 %0, %1 offset:%2" : "=&v"(r) : "v"(vb), "i"(OFF) : "memory"); return r;
; }
; template <int D0> __device__ __forceinline__ void pv_one(f32x16& od, int vb, bf16x8 pa0, bf16x8 pa1, bf16x8 pa2, bf16x8 pa3) {
;   const s16x4 l0 = tr_read<v_rd_off(D0, 0, 0)>(vb), h0 = tr_read<v_rd_off(D0, 0, 1)>(vb), l1 = tr_read<v_rd_off(D0, 1, 0)>(vb), h1 = tr_read<v_rd_off(D0, 1, 1)>(vb);
;   const s16x4 l2 = tr_read<v_rd_off(D0, 2, 0)>(vb), h2 = tr_read<v_rd_off(D0, 2, 1)>(vb), l3 = tr_read<v_rd_off(D0, 3, 0)>(vb), h3 = tr_read<v_rd_off(D0, 3, 1)>(vb);
;   asm volatile("s_waitcnt lgkmcnt(0)" ::: "memory"); SBAR();
;     ...
;   od = __builtin_amdgcn_mfma_f32_32x32x16_bf16(pa0, PK(l0, h0), od, 0, 0, 0);
	ds_write_b128 v181, v[250:253] offset:57344
	s_waitcnt lgkmcnt(10)
	v_mfma_f32_32x32x16_bf16 v[48:63], v[184:187], v[230:233], v[48:63]
	ds_read_b64_tr_b16 v[204:205], v182 offset:5120
	ds_read_b64_tr_b16 v[206:207], v182 offset:7168
	v_exp_f32_e32 v136, v136
	v_exp_f32_e32 v137, v137
	s_waitcnt lgkmcnt(10)
	v_mfma_f32_32x32x16_bf16 v[48:63], v[188:191], v[234:237], v[48:63]
	ds_read_b64_tr_b16 v[208:209], v182 offset:9216
	ds_read_b64_tr_b16 v[210:211], v182 offset:11264
	v_exp_f32_e32 v138, v138
	v_exp_f32_e32 v139, v139
	s_waitcnt vmcnt(1)
	ds_write_b128 v180, v[164:167] offset:32768
	s_waitcnt lgkmcnt(11)
	v_mfma_f32_32x32x16_bf16 v[48:63], v[192:195], v[238:241], v[48:63]
	ds_read_b64_tr_b16 v[212:213], v182 offset:13312
	ds_read_b64_tr_b16 v[214:215], v182 offset:15360
	v_exp_f32_e32 v140, v140
	v_exp_f32_e32 v141, v141
	s_waitcnt lgkmcnt(10)
	v_mfma_f32_32x32x16_bf16 v[48:63], v[196:199], v[242:245], v[48:63]
	ds_read_b64_tr_b16 v[230:231], v182 offset:1536
	ds_read_b64_tr_b16 v[232:233], v182 offset:3584
	v_exp_f32_e32 v142, v142
	v_exp_f32_e32 v143, v143
	s_waitcnt vmcnt(0)
	ds_write_b128 v180, v[160:163] offset:40960
	s_waitcnt lgkmcnt(11)
	v_mfma_f32_32x32x16_bf16 v[32:47], v[184:187], v[200:203], v[32:47]
	ds_read_b64_tr_b16 v[234:235], v182 offset:5632
	ds_read_b64_tr_b16 v[236:237], v182 offset:7680
	ds_read_b128 v[200:203], v172 offset:32768
	v_exp_f32_e32 v144, v144
	v_exp_f32_e32 v145, v145
	s_waitcnt lgkmcnt(11)
	v_mfma_f32_32x32x16_bf16 v[32:47], v[188:191], v[204:207], v[32:47]
	ds_read_b64_tr_b16 v[238:239], v182 offset:9728
	ds_read_b64_tr_b16 v[240:241], v182 offset:11776
	ds_read_b128 v[204:207], v172 offset:40960
	v_exp_f32_e32 v146, v146
	v_exp_f32_e32 v147, v147
	s_waitcnt lgkmcnt(12)
	v_mfma_f32_32x32x16_bf16 v[32:47], v[192:195], v[208:211], v[32:47]
	ds_read_b64_tr_b16 v[242:243], v182 offset:13824
	ds_read_b64_tr_b16 v[244:245], v182 offset:15872
	ds_read_b128 v[208:211], v173 offset:32768
	v_exp_f32_e32 v148, v148
	v_exp_f32_e32 v149, v149
	s_waitcnt lgkmcnt(12)
	v_mfma_f32_32x32x16_bf16 v[32:47], v[196:199], v[212:215], v[32:47]
	ds_read_b128 v[212:215], v173 offset:40960
	v_exp_f32_e32 v150, v150
	v_exp_f32_e32 v151, v151
	s_waitcnt lgkmcnt(11)
	v_mfma_f32_32x32x16_bf16 v[16:31], v[184:187], v[230:233], v[16:31]
	ds_read_b128 v[230:233], v174 offset:32768
	v_exp_f32_e32 v152, v152
	v_exp_f32_e32 v153, v153
	s_waitcnt lgkmcnt(9)
	v_mfma_f32_32x32x16_bf16 v[16:31], v[188:191], v[234:237], v[16:31]
	ds_read_b128 v[234:237], v174 offset:40960
	v_exp_f32_e32 v154, v154
	v_exp_f32_e32 v155, v155
	s_waitcnt lgkmcnt(7)
	v_mfma_f32_32x32x16_bf16 v[16:31], v[192:195], v[238:241], v[16:31]
	ds_read_b128 v[238:241], v175 offset:32768
	v_exp_f32_e32 v156, v156
	v_exp_f32_e32 v157, v157
	s_waitcnt lgkmcnt(5)
	v_mfma_f32_32x32x16_bf16 v[16:31], v[196:199], v[242:245], v[16:31]
	ds_read_b128 v[242:245], v175 offset:40960
	v_exp_f32_e32 v158, v158
	v_exp_f32_e32 v159, v159
	s_barrier
	v_mfma_f32_32x32x16_bf16 v[64:79], v[200:203], v[124:127], 0
	ds_read_b128 v[200:203], v176 offset:32768
	v_cvt_pk_bf16_f32 v184, v128, v129
	v_add_f32_e32 v169, v169, v128
	v_add_f32_e32 v219, v219, v129
	global_load_dwordx4 v[246:249], v183, s[98:99]
	v_mfma_f32_32x32x16_bf16 v[80:95], v[204:207], v[124:127], 0
	ds_read_b128 v[204:207], v176 offset:40960
	v_cvt_pk_bf16_f32 v185, v130, v131
	v_add_f32_e32 v222, v222, v130
	v_add_f32_e32 v254, v254, v131
	s_waitcnt lgkmcnt(7)
	v_mfma_f32_32x32x16_bf16 v[64:79], v[208:211], v[120:123], v[64:79]
	ds_read_b128 v[208:211], v177 offset:32768
	v_cvt_pk_bf16_f32 v186, v132, v133
	v_add_f32_e32 v169, v169, v132
	v_add_f32_e32 v219, v219, v133
	global_load_dwordx4 v[250:253], v183, s[100:101]
	s_add_u32 s98, s98, 0x150000
	s_addc_u32 s99, s99, 0
	s_add_u32 s100, s100, 0x150000
	s_addc_u32 s101, s101, 0
	s_waitcnt lgkmcnt(7)
	v_mfma_f32_32x32x16_bf16 v[80:95], v[212:215], v[120:123], v[80:95]
	ds_read_b128 v[212:215], v177 offset:40960
	v_cvt_pk_bf16_f32 v187, v134, v135
	v_add_f32_e32 v222, v222, v134
	v_add_f32_e32 v254, v254, v135
	s_waitcnt lgkmcnt(7)
	v_mfma_f32_32x32x16_bf16 v[64:79], v[230:233], v[116:119], v[64:79]
	ds_read_b128 v[230:233], v178 offset:32768
	v_cvt_pk_bf16_f32 v188, v136, v137
	v_add_f32_e32 v169, v169, v136
	v_add_f32_e32 v219, v219, v137
	v_permlane32_swap_b32_e32 v184, v186
	global_load_dwordx4 v[164:167], v183, s[0:1] offset:512
	s_waitcnt lgkmcnt(7)
	v_mfma_f32_32x32x16_bf16 v[80:95], v[234:237], v[116:119], v[80:95]
	ds_read_b128 v[234:237], v178 offset:40960
	v_cvt_pk_bf16_f32 v189, v138, v139
	v_add_f32_e32 v222, v222, v138
	v_add_f32_e32 v254, v254, v139
	v_permlane32_swap_b32_e32 v185, v187
	s_waitcnt lgkmcnt(7)
	v_mfma_f32_32x32x16_bf16 v[64:79], v[238:241], v[112:115], v[64:79]
	ds_read_b128 v[238:241], v179 offset:32768
	v_cvt_pk_bf16_f32 v190, v140, v141
	v_add_f32_e32 v169, v169, v140
	v_add_f32_e32 v219, v219, v141
	global_load_dwordx4 v[160:163], v183, s[4:5] offset:512
	s_add_u32 s0, s0, 0x150000
	s_addc_u32 s1, s1, 0
	s_add_u32 s4, s4, 0x150000
	s_addc_u32 s5, s5, 0
	s_waitcnt lgkmcnt(7)
	v_mfma_f32_32x32x16_bf16 v[80:95], v[242:245], v[112:115], v[80:95]
	ds_read_b128 v[242:245], v179 offset:40960
	v_cvt_pk_bf16_f32 v191, v142, v143
	v_add_f32_e32 v222, v222, v142
	v_add_f32_e32 v254, v254, v143
	s_waitcnt lgkmcnt(7)
	v_mfma_f32_32x32x16_bf16 v[64:79], v[200:203], v[108:111], v[64:79]
	v_cvt_pk_bf16_f32 v192, v144, v145
	v_add_f32_e32 v169, v169, v144
	v_add_f32_e32 v219, v219, v145
	v_permlane32_swap_b32_e32 v188, v190
	s_waitcnt lgkmcnt(6)
; __device__ __forceinline__ void finishSM(f32x16& p0, f32x16& p1, float alpha, float& l_reg, bf16x8& pa0, bf16x8& pa1, bf16x8& pa2, bf16x8& pa3) {
; #pragma unroll
;   for (int r = 0; r < 16; ++r) p1[r] = __builtin_amdgcn_exp2f(p1[r]);
;   float ps = 0;
; #pragma unroll
;   for (int r = 0; r < 16; ++r) ps += p0[r];
; #pragma unroll
;   for (int r = 0; r < 16; ++r) ps += p1[r];
;   { auto rr = __builtin_amdgcn_permlane32_swap(__float_as_uint(ps), __float_as_uint(ps), false, false);
;     ps = __uint_as_float(rr[0]) + __uint_as_float(rr[1]); }
;   l_reg = l_reg * alpha + ps;
;     ...
;   PK4(p0, 0, pa0); PK4(p0, 8, pa1); PK4(p1, 0, pa2); PK4(p1, 8, pa3);
;     ...
; }
; __device__ __forceinline__ void qkt(f32x16& p0, f32x16& p1, const bf16* Ks, const bf16x8* qr, int r32, int hi) {
;   p0 = f32x16{}; p1 = f32x16{};
; #pragma unroll
;   for (int d0 = 0; d0 < 8; ++d0) { int cb = (d0 * 16 + hi * 8) * 2;
;     bf16x8 b0 = *reinterpret_cast<const bf16x8*>((const char*)Ks + KSWZ(r32, cb));
;     bf16x8 b1 = *reinterpret_cast<const bf16x8*>((const char*)Ks + KSWZ(32 + r32, cb));
;     p0 = __builtin_amdgcn_mfma_f32_32x32x16_bf16(b0, qr[d0], p0, 0, 0, 0);
;     p1 = __builtin_amdgcn_mfma_f32_32x32x16_bf16(b1, qr[d0], p1, 0, 0, 0); }
; }
; __device__ __forceinline__ int v_st(int k, int c) { const int kk = (k & ~0xC) | ((k & 4) << 1) | ((k & 8) >> 1); return ((kk >> 3) * 4 + (c >> 5)) * 512 + ((kk & 7) * 32 + (c & 31)) * 2; }
; __device__ __forceinline__ int v_rd_base(int lane) { return ((lane & 3) << 3) | (((lane >> 2) & 3) << 6) | (((lane >> 4) & 1) << 5) | (((lane >> 5) & 1) << 8); }
; template <int OFF> __device__ __forceinline__ s16x4 tr_read(int vb) {
;   s16x4 r; asm volatile("ds_read_b64_tr_b16 %0, %1 offset:%2" : "=&v"(r) : "v"(vb), "i"(OFF) : "memory"); return r;
; }
; template <int D0> __device__ __forceinline__ void pv_one(f32x16& od, int vb, bf16x8 pa0, bf16x8 pa1, bf16x8 pa2, bf16x8 pa3) {
;   const s16x4 l0 = tr_read<v_rd_off(D0, 0, 0)>(vb), h0 = tr_read<v_rd_off(D0, 0, 1)>(vb), l1 = tr_read<v_rd_off(D0, 1, 0)>(vb), h1 = tr_read<v_rd_off(D0, 1, 1)>(vb);
;   const s16x4 l2 = tr_read<v_rd_off(D0, 2, 0)>(vb), h2 = tr_read<v_rd_off(D0, 2, 1)>(vb), l3 = tr_read<v_rd_off(D0, 3, 0)>(vb), h3 = tr_read<v_rd_off(D0, 3, 1)>(vb);
;   asm volatile("s_waitcnt lgkmcnt(0)" ::: "memory"); SBAR();
;     ...
;   od = __builtin_amdgcn_mfma_f32_32x32x16_bf16(pa0, PK(l0, h0), od, 0, 0, 0);
	v_mfma_f32_32x32x16_bf16 v[80:95], v[204:207], v[108:111], v[80:95]
	v_cvt_pk_bf16_f32 v193, v146, v147
	v_add_f32_e32 v222, v222, v146
	v_add_f32_e32 v254, v254, v147
	v_permlane32_swap_b32_e32 v189, v191
	s_waitcnt lgkmcnt(5)
	v_mfma_f32_32x32x16_bf16 v[64:79], v[208:211], v[104:107], v[64:79]
	v_cvt_pk_bf16_f32 v194, v148, v149
	v_add_f32_e32 v169, v169, v148
	v_add_f32_e32 v219, v219, v149
	s_waitcnt lgkmcnt(4)
	v_mfma_f32_32x32x16_bf16 v[80:95], v[212:215], v[104:107], v[80:95]
	ds_read_b64_tr_b16 v[200:201], v182 offset:16384
	ds_read_b64_tr_b16 v[202:203], v182 offset:18432
	v_cvt_pk_bf16_f32 v195, v150, v151
	v_add_f32_e32 v222, v222, v150
	v_add_f32_e32 v254, v254, v151
	s_waitcnt lgkmcnt(5)
	v_mfma_f32_32x32x16_bf16 v[64:79], v[230:233], v[100:103], v[64:79]
	ds_read_b64_tr_b16 v[204:205], v182 offset:20480
	ds_read_b64_tr_b16 v[206:207], v182 offset:22528
	v_cvt_pk_bf16_f32 v196, v152, v153
	v_add_f32_e32 v169, v169, v152
	v_add_f32_e32 v219, v219, v153
	v_permlane32_swap_b32_e32 v192, v194
	s_waitcnt lgkmcnt(6)
	v_mfma_f32_32x32x16_bf16 v[80:95], v[234:237], v[100:103], v[80:95]
	ds_read_b64_tr_b16 v[208:209], v182 offset:24576
	ds_read_b64_tr_b16 v[210:211], v182 offset:26624
	v_cvt_pk_bf16_f32 v197, v154, v155
	v_add_f32_e32 v222, v222, v154
	v_add_f32_e32 v254, v254, v155
	v_permlane32_swap_b32_e32 v193, v195
	s_waitcnt lgkmcnt(7)
	v_mfma_f32_32x32x16_bf16 v[64:79], v[238:241], v[96:99], v[64:79]
	ds_read_b64_tr_b16 v[212:213], v182 offset:28672
	ds_read_b64_tr_b16 v[214:215], v182 offset:30720
	v_cvt_pk_bf16_f32 v198, v156, v157
	v_add_f32_e32 v169, v169, v156
	v_add_f32_e32 v219, v219, v157
	s_waitcnt lgkmcnt(8)
	v_mfma_f32_32x32x16_bf16 v[80:95], v[242:245], v[96:99], v[80:95]
	ds_read_b64_tr_b16 v[230:231], v182 offset:16896
	ds_read_b64_tr_b16 v[232:233], v182 offset:18944
	v_cvt_pk_bf16_f32 v199, v158, v159
	v_add_f32_e32 v222, v222, v158
	v_add_f32_e32 v254, v254, v159
	v_permlane32_swap_b32_e32 v196, v198
	v_permlane32_swap_b32_e32 v197, v199
	s_waitcnt lgkmcnt(8)
	v_mfma_f32_32x32x16_bf16 v[0:15], v[184:187], v[200:203], v[0:15]
	ds_read_b64_tr_b16 v[234:235], v182 offset:20992
	ds_read_b64_tr_b16 v[236:237], v182 offset:23040
	v_exp_f32_e32 v64, v64
	v_exp_f32_e32 v65, v65
	s_waitcnt lgkmcnt(8)
	v_mfma_f32_32x32x16_bf16 v[0:15], v[188:191], v[204:207], v[0:15]
	ds_read_b64_tr_b16 v[238:239], v182 offset:25088
	ds_read_b64_tr_b16 v[240:241], v182 offset:27136
	v_exp_f32_e32 v66, v66
	v_exp_f32_e32 v67, v67
	s_waitcnt vmcnt(3)
	ds_write_b128 v181, v[246:249] offset:0
	s_waitcnt lgkmcnt(9)
	v_mfma_f32_32x32x16_bf16 v[0:15], v[192:195], v[208:211], v[0:15]
	ds_read_b64_tr_b16 v[242:243], v182 offset:29184
	ds_read_b64_tr_b16 v[244:245], v182 offset:31232
	v_exp_f32_e32 v68, v68
	v_exp_f32_e32 v69, v69
	s_waitcnt lgkmcnt(9)
	v_mfma_f32_32x32x16_bf16 v[0:15], v[196:199], v[212:215], v[0:15]
	ds_read_b64_tr_b16 v[200:201], v182 offset:17408
	ds_read_b64_tr_b16 v[202:203], v182 offset:19456
	v_exp_f32_e32 v70, v70
	v_exp_f32_e32 v71, v71
	s_waitcnt vmcnt(2)
	ds_write_b128 v181, v[250:253] offset:8192
	s_waitcnt lgkmcnt(10)
	v_mfma_f32_32x32x16_bf16 v[48:63], v[184:187], v[230:233], v[48:63]
	ds_read_b64_tr_b16 v[204:205], v182 offset:21504
	ds_read_b64_tr_b16 v[206:207], v182 offset:23552
	v_exp_f32_e32 v72, v72
	v_exp_f32_e32 v73, v73
	s_waitcnt lgkmcnt(10)
	v_mfma_f32_32x32x16_bf16 v[48:63], v[188:191], v[234:237], v[48:63]
	ds_read_b64_tr_b16 v[208:209], v182 offset:25600
	ds_read_b64_tr_b16 v[210:211], v182 offset:27648
	v_exp_f32_e32 v74, v74
	v_exp_f32_e32 v75, v75
	s_waitcnt vmcnt(1)
	ds_write_b128 v180, v[164:167] offset:49152
	s_waitcnt lgkmcnt(11)
	v_mfma_f32_32x32x16_bf16 v[48:63], v[192:195], v[238:241], v[48:63]
	ds_read_b64_tr_b16 v[212:213], v182 offset:29696
	ds_read_b64_tr_b16 v[214:215], v182 offset:31744
	v_exp_f32_e32 v76, v76
	v_exp_f32_e32 v77, v77
	s_waitcnt lgkmcnt(10)
	v_mfma_f32_32x32x16_bf16 v[48:63], v[196:199], v[242:245], v[48:63]
	ds_read_b64_tr_b16 v[230:231], v182 offset:17920
	ds_read_b64_tr_b16 v[232:233], v182 offset:19968
	v_exp_f32_e32 v78, v78
	v_exp_f32_e32 v79, v79
	s_waitcnt vmcnt(0)
	ds_write_b128 v180, v[160:163] offset:57344
	s_waitcnt lgkmcnt(11)
	v_mfma_f32_32x32x16_bf16 v[32:47], v[184:187], v[200:203], v[32:47]
	ds_read_b64_tr_b16 v[234:235], v182 offset:22016
	ds_read_b64_tr_b16 v[236:237], v182 offset:24064
	ds_read_b128 v[200:203], v172 offset:49152
	v_exp_f32_e32 v80, v80
	v_exp_f32_e32 v81, v81
	s_waitcnt lgkmcnt(11)
	v_mfma_f32_32x32x16_bf16 v[32:47], v[188:191], v[204:207], v[32:47]
	ds_read_b64_tr_b16 v[238:239], v182 offset:26112
	ds_read_b64_tr_b16 v[240:241], v182 offset:28160
	ds_read_b128 v[204:207], v172 offset:57344
	v_exp_f32_e32 v82, v82
	v_exp_f32_e32 v83, v83
	s_waitcnt lgkmcnt(12)
	v_mfma_f32_32x32x16_bf16 v[32:47], v[192:195], v[208:211], v[32:47]
	ds_read_b64_tr_b16 v[242:243], v182 offset:30208
	ds_read_b64_tr_b16 v[244:245], v182 offset:32256
	ds_read_b128 v[208:211], v173 offset:49152
	v_exp_f32_e32 v84, v84
	v_exp_f32_e32 v85, v85
	s_waitcnt lgkmcnt(12)
	v_mfma_f32_32x32x16_bf16 v[32:47], v[196:199], v[212:215], v[32:47]
	ds_read_b128 v[212:215], v173 offset:57344
	v_exp_f32_e32 v86, v86
	v_exp_f32_e32 v87, v87
	s_waitcnt lgkmcnt(11)
	v_mfma_f32_32x32x16_bf16 v[16:31], v[184:187], v[230:233], v[16:31]
	ds_read_b128 v[230:233], v174 offset:49152
	v_exp_f32_e32 v88, v88
	v_exp_f32_e32 v89, v89
	s_waitcnt lgkmcnt(9)
	v_mfma_f32_32x32x16_bf16 v[16:31], v[188:191], v[234:237], v[16:31]
	ds_read_b128 v[234:237], v174 offset:57344
	v_exp_f32_e32 v90, v90
	v_exp_f32_e32 v91, v91
	s_waitcnt lgkmcnt(7)
	v_mfma_f32_32x32x16_bf16 v[16:31], v[192:195], v[238:241], v[16:31]
	ds_read_b128 v[238:241], v175 offset:49152
	v_exp_f32_e32 v92, v92
	v_exp_f32_e32 v93, v93
	s_waitcnt lgkmcnt(5)
	v_mfma_f32_32x32x16_bf16 v[16:31], v[196:199], v[242:245], v[16:31]
	ds_read_b128 v[242:245], v175 offset:57344
	v_exp_f32_e32 v94, v94
	v_exp_f32_e32 v95, v95
	s_barrier
; __device__ __forceinline__ void finishSM(f32x16& p0, f32x16& p1, float alpha, float& l_reg, bf16x8& pa0, bf16x8& pa1, bf16x8& pa2, bf16x8& pa3) {
; #pragma unroll
;   for (int r = 0; r < 16; ++r) p1[r] = __builtin_amdgcn_exp2f(p1[r]);
;   float ps = 0;
; #pragma unroll
;   for (int r = 0; r < 16; ++r) ps += p0[r];
; #pragma unroll
;   for (int r = 0; r < 16; ++r) ps += p1[r];
;   { auto rr = __builtin_amdgcn_permlane32_swap(__float_as_uint(ps), __float_as_uint(ps), false, false);
;     ps = __uint_as_float(rr[0]) + __uint_as_float(rr[1]); }
;   l_reg = l_reg * alpha + ps;
;     ...
;   PK4(p0, 0, pa0); PK4(p0, 8, pa1); PK4(p1, 0, pa2); PK4(p1, 8, pa3);
;     ...
; }
; __device__ __forceinline__ void qkt(f32x16& p0, f32x16& p1, const bf16* Ks, const bf16x8* qr, int r32, int hi) {
;   p0 = f32x16{}; p1 = f32x16{};
; #pragma unroll
;   for (int d0 = 0; d0 < 8; ++d0) { int cb = (d0 * 16 + hi * 8) * 2;
;     bf16x8 b0 = *reinterpret_cast<const bf16x8*>((const char*)Ks + KSWZ(r32, cb));
;     bf16x8 b1 = *reinterpret_cast<const bf16x8*>((const char*)Ks + KSWZ(32 + r32, cb));
;     p0 = __builtin_amdgcn_mfma_f32_32x32x16_bf16(b0, qr[d0], p0, 0, 0, 0);
;     p1 = __builtin_amdgcn_mfma_f32_32x32x16_bf16(b1, qr[d0], p1, 0, 0, 0); }
; }
; __device__ __forceinline__ int v_st(int k, int c) { const int kk = (k & ~0xC) | ((k & 4) << 1) | ((k & 8) >> 1); return ((kk >> 3) * 4 + (c >> 5)) * 512 + ((kk & 7) * 32 + (c & 31)) * 2; }
; __device__ __forceinline__ int v_rd_base(int lane) { return ((lane & 3) << 3) | (((lane >> 2) & 3) << 6) | (((lane >> 4) & 1) << 5) | (((lane >> 5) & 1) << 8); }
; template <int OFF> __device__ __forceinline__ s16x4 tr_read(int vb) {
;   s16x4 r; asm volatile("ds_read_b64_tr_b16 %0, %1 offset:%2" : "=&v"(r) : "v"(vb), "i"(OFF) : "memory"); return r;
; }
; template <int D0> __device__ __forceinline__ void pv_one(f32x16& od, int vb, bf16x8 pa0, bf16x8 pa1, bf16x8 pa2, bf16x8 pa3) {
;   const s16x4 l0 = tr_read<v_rd_off(D0, 0, 0)>(vb), h0 = tr_read<v_rd_off(D0, 0, 1)>(vb), l1 = tr_read<v_rd_off(D0, 1, 0)>(vb), h1 = tr_read<v_rd_off(D0, 1, 1)>(vb);
;   const s16x4 l2 = tr_read<v_rd_off(D0, 2, 0)>(vb), h2 = tr_read<v_rd_off(D0, 2, 1)>(vb), l3 = tr_read<v_rd_off(D0, 3, 0)>(vb), h3 = tr_read<v_rd_off(D0, 3, 1)>(vb);
;   asm volatile("s_waitcnt lgkmcnt(0)" ::: "memory"); SBAR();
;     ...
;   od = __builtin_amdgcn_mfma_f32_32x32x16_bf16(pa0, PK(l0, h0), od, 0, 0, 0);
	v_mfma_f32_32x32x16_bf16 v[128:143], v[200:203], v[124:127], 0
	ds_read_b128 v[200:203], v176 offset:49152
	v_cvt_pk_bf16_f32 v184, v64, v65
	v_add_f32_e32 v169, v169, v64
	v_add_f32_e32 v219, v219, v65
	global_load_dwordx4 v[246:249], v183, s[98:99]
	v_mfma_f32_32x32x16_bf16 v[144:159], v[204:207], v[124:127], 0
	ds_read_b128 v[204:207], v176 offset:57344
	v_cvt_pk_bf16_f32 v185, v66, v67
	v_add_f32_e32 v222, v222, v66
	v_add_f32_e32 v254, v254, v67
	s_waitcnt lgkmcnt(7)
	v_mfma_f32_32x32x16_bf16 v[128:143], v[208:211], v[120:123], v[128:143]
	ds_read_b128 v[208:211], v177 offset:49152
	v_cvt_pk_bf16_f32 v186, v68, v69
	v_add_f32_e32 v169, v169, v68
	v_add_f32_e32 v219, v219, v69
	global_load_dwordx4 v[250:253], v183, s[100:101]
	s_add_u32 s98, s98, 0x150000
	s_addc_u32 s99, s99, 0
	s_add_u32 s100, s100, 0x150000
	s_addc_u32 s101, s101, 0
	s_waitcnt lgkmcnt(7)
	v_mfma_f32_32x32x16_bf16 v[144:159], v[212:215], v[120:123], v[144:159]
	ds_read_b128 v[212:215], v177 offset:57344
	v_cvt_pk_bf16_f32 v187, v70, v71
	v_add_f32_e32 v222, v222, v70
	v_add_f32_e32 v254, v254, v71
	s_waitcnt lgkmcnt(7)
	v_mfma_f32_32x32x16_bf16 v[128:143], v[230:233], v[116:119], v[128:143]
	ds_read_b128 v[230:233], v178 offset:49152
	v_cvt_pk_bf16_f32 v188, v72, v73
	v_add_f32_e32 v169, v169, v72
	v_add_f32_e32 v219, v219, v73
	v_permlane32_swap_b32_e32 v184, v186
	global_load_dwordx4 v[164:167], v183, s[0:1] offset:512
	s_waitcnt lgkmcnt(7)
	v_mfma_f32_32x32x16_bf16 v[144:159], v[234:237], v[116:119], v[144:159]
	ds_read_b128 v[234:237], v178 offset:57344
	v_cvt_pk_bf16_f32 v189, v74, v75
	v_add_f32_e32 v222, v222, v74
	v_add_f32_e32 v254, v254, v75
	v_permlane32_swap_b32_e32 v185, v187
	s_waitcnt lgkmcnt(7)
	v_mfma_f32_32x32x16_bf16 v[128:143], v[238:241], v[112:115], v[128:143]
	ds_read_b128 v[238:241], v179 offset:49152
	v_cvt_pk_bf16_f32 v190, v76, v77
	v_add_f32_e32 v169, v169, v76
	v_add_f32_e32 v219, v219, v77
	global_load_dwordx4 v[160:163], v183, s[4:5] offset:512
	s_add_u32 s0, s0, 0x150000
	s_addc_u32 s1, s1, 0
	s_add_u32 s4, s4, 0x150000
	s_addc_u32 s5, s5, 0
	s_waitcnt lgkmcnt(7)
	v_mfma_f32_32x32x16_bf16 v[144:159], v[242:245], v[112:115], v[144:159]
	ds_read_b128 v[242:245], v179 offset:57344
	v_cvt_pk_bf16_f32 v191, v78, v79
	v_add_f32_e32 v222, v222, v78
	v_add_f32_e32 v254, v254, v79
	s_waitcnt lgkmcnt(7)
	v_mfma_f32_32x32x16_bf16 v[128:143], v[200:203], v[108:111], v[128:143]
	v_cvt_pk_bf16_f32 v192, v80, v81
	v_add_f32_e32 v169, v169, v80
	v_add_f32_e32 v219, v219, v81
	v_permlane32_swap_b32_e32 v188, v190
	s_waitcnt lgkmcnt(6)
	v_mfma_f32_32x32x16_bf16 v[144:159], v[204:207], v[108:111], v[144:159]
	v_cvt_pk_bf16_f32 v193, v82, v83
	v_add_f32_e32 v222, v222, v82
	v_add_f32_e32 v254, v254, v83
	v_permlane32_swap_b32_e32 v189, v191
	s_waitcnt lgkmcnt(5)
	v_mfma_f32_32x32x16_bf16 v[128:143], v[208:211], v[104:107], v[128:143]
	v_cvt_pk_bf16_f32 v194, v84, v85
	v_add_f32_e32 v169, v169, v84
	v_add_f32_e32 v219, v219, v85
	s_waitcnt lgkmcnt(4)
	v_mfma_f32_32x32x16_bf16 v[144:159], v[212:215], v[104:107], v[144:159]
	ds_read_b64_tr_b16 v[200:201], v182 offset:32768
	ds_read_b64_tr_b16 v[202:203], v182 offset:34816
	v_cvt_pk_bf16_f32 v195, v86, v87
	v_add_f32_e32 v222, v222, v86
	v_add_f32_e32 v254, v254, v87
	s_waitcnt lgkmcnt(5)
	v_mfma_f32_32x32x16_bf16 v[128:143], v[230:233], v[100:103], v[128:143]
	ds_read_b64_tr_b16 v[204:205], v182 offset:36864
	ds_read_b64_tr_b16 v[206:207], v182 offset:38912
	v_cvt_pk_bf16_f32 v196, v88, v89
	v_add_f32_e32 v169, v169, v88
	v_add_f32_e32 v219, v219, v89
	v_permlane32_swap_b32_e32 v192, v194
	s_waitcnt lgkmcnt(6)
	v_mfma_f32_32x32x16_bf16 v[144:159], v[234:237], v[100:103], v[144:159]
	ds_read_b64_tr_b16 v[208:209], v182 offset:40960
	ds_read_b64_tr_b16 v[210:211], v182 offset:43008
	v_cvt_pk_bf16_f32 v197, v90, v91
	v_add_f32_e32 v222, v222, v90
	v_add_f32_e32 v254, v254, v91
	v_permlane32_swap_b32_e32 v193, v195
	s_waitcnt lgkmcnt(7)
	v_mfma_f32_32x32x16_bf16 v[128:143], v[238:241], v[96:99], v[128:143]
	ds_read_b64_tr_b16 v[212:213], v182 offset:45056
	ds_read_b64_tr_b16 v[214:215], v182 offset:47104
	v_cvt_pk_bf16_f32 v198, v92, v93
	v_add_f32_e32 v169, v169, v92
	v_add_f32_e32 v219, v219, v93
	s_waitcnt lgkmcnt(8)
	v_mfma_f32_32x32x16_bf16 v[144:159], v[242:245], v[96:99], v[144:159]
	ds_read_b64_tr_b16 v[230:231], v182 offset:33280
	ds_read_b64_tr_b16 v[232:233], v182 offset:35328
	v_cvt_pk_bf16_f32 v199, v94, v95
	v_add_f32_e32 v222, v222, v94
	v_add_f32_e32 v254, v254, v95
	v_permlane32_swap_b32_e32 v196, v198
	v_permlane32_swap_b32_e32 v197, v199
	s_waitcnt lgkmcnt(8)
	v_mfma_f32_32x32x16_bf16 v[0:15], v[184:187], v[200:203], v[0:15]
	ds_read_b64_tr_b16 v[234:235], v182 offset:37376
	ds_read_b64_tr_b16 v[236:237], v182 offset:39424
	v_exp_f32_e32 v128, v128
	v_exp_f32_e32 v129, v129
	s_waitcnt lgkmcnt(8)
	v_mfma_f32_32x32x16_bf16 v[0:15], v[188:191], v[204:207], v[0:15]
	ds_read_b64_tr_b16 v[238:239], v182 offset:41472
	ds_read_b64_tr_b16 v[240:241], v182 offset:43520
	v_exp_f32_e32 v130, v130
	v_exp_f32_e32 v131, v131
	s_waitcnt vmcnt(3)
	ds_write_b128 v181, v[246:249] offset:16384
	s_waitcnt lgkmcnt(9)
	v_mfma_f32_32x32x16_bf16 v[0:15], v[192:195], v[208:211], v[0:15]
	ds_read_b64_tr_b16 v[242:243], v182 offset:45568
	ds_read_b64_tr_b16 v[244:245], v182 offset:47616
	v_exp_f32_e32 v132, v132
	v_exp_f32_e32 v133, v133
	s_waitcnt lgkmcnt(9)
	v_mfma_f32_32x32x16_bf16 v[0:15], v[196:199], v[212:215], v[0:15]
	ds_read_b64_tr_b16 v[200:201], v182 offset:33792
	ds_read_b64_tr_b16 v[202:203], v182 offset:35840
	v_exp_f32_e32 v134, v134
	v_exp_f32_e32 v135, v135
	s_waitcnt vmcnt(2)
; __device__ __forceinline__ void finishSM(f32x16& p0, f32x16& p1, float alpha, float& l_reg, bf16x8& pa0, bf16x8& pa1, bf16x8& pa2, bf16x8& pa3) {
; #pragma unroll
;   for (int r = 0; r < 16; ++r) p1[r] = __builtin_amdgcn_exp2f(p1[r]);
;   float ps = 0;
; #pragma unroll
;   for (int r = 0; r < 16; ++r) ps += p0[r];
; #pragma unroll
;   for (int r = 0; r < 16; ++r) ps += p1[r];
;   { auto rr = __builtin_amdgcn_permlane32_swap(__float_as_uint(ps), __float_as_uint(ps), false, false);
;     ps = __uint_as_float(rr[0]) + __uint_as_float(rr[1]); }
;   l_reg = l_reg * alpha + ps;
;     ...
;   PK4(p0, 0, pa0); PK4(p0, 8, pa1); PK4(p1, 0, pa2); PK4(p1, 8, pa3);
;     ...
; }
; __device__ __forceinline__ void qkt(f32x16& p0, f32x16& p1, const bf16* Ks, const bf16x8* qr, int r32, int hi) {
;   p0 = f32x16{}; p1 = f32x16{};
; #pragma unroll
;   for (int d0 = 0; d0 < 8; ++d0) { int cb = (d0 * 16 + hi * 8) * 2;
;     bf16x8 b0 = *reinterpret_cast<const bf16x8*>((const char*)Ks + KSWZ(r32, cb));
;     bf16x8 b1 = *reinterpret_cast<const bf16x8*>((const char*)Ks + KSWZ(32 + r32, cb));
;     p0 = __builtin_amdgcn_mfma_f32_32x32x16_bf16(b0, qr[d0], p0, 0, 0, 0);
;     p1 = __builtin_amdgcn_mfma_f32_32x32x16_bf16(b1, qr[d0], p1, 0, 0, 0); }
; }
; __device__ __forceinline__ int v_st(int k, int c) { const int kk = (k & ~0xC) | ((k & 4) << 1) | ((k & 8) >> 1); return ((kk >> 3) * 4 + (c >> 5)) * 512 + ((kk & 7) * 32 + (c & 31)) * 2; }
; __device__ __forceinline__ int v_rd_base(int lane) { return ((lane & 3) << 3) | (((lane >> 2) & 3) << 6) | (((lane >> 4) & 1) << 5) | (((lane >> 5) & 1) << 8); }
; template <int OFF> __device__ __forceinline__ s16x4 tr_read(int vb) {
;   s16x4 r; asm volatile("ds_read_b64_tr_b16 %0, %1 offset:%2" : "=&v"(r) : "v"(vb), "i"(OFF) : "memory"); return r;
; }
; template <int D0> __device__ __forceinline__ void pv_one(f32x16& od, int vb, bf16x8 pa0, bf16x8 pa1, bf16x8 pa2, bf16x8 pa3) {
;   const s16x4 l0 = tr_read<v_rd_off(D0, 0, 0)>(vb), h0 = tr_read<v_rd_off(D0, 0, 1)>(vb), l1 = tr_read<v_rd_off(D0, 1, 0)>(vb), h1 = tr_read<v_rd_off(D0, 1, 1)>(vb);
;   const s16x4 l2 = tr_read<v_rd_off(D0, 2, 0)>(vb), h2 = tr_read<v_rd_off(D0, 2, 1)>(vb), l3 = tr_read<v_rd_off(D0, 3, 0)>(vb), h3 = tr_read<v_rd_off(D0, 3, 1)>(vb);
;   asm volatile("s_waitcnt lgkmcnt(0)" ::: "memory"); SBAR();
;     ...
;   od = __builtin_amdgcn_mfma_f32_32x32x16_bf16(pa0, PK(l0, h0), od, 0, 0, 0);
	ds_write_b128 v181, v[250:253] offset:24576
	s_waitcnt lgkmcnt(10)
	v_mfma_f32_32x32x16_bf16 v[48:63], v[184:187], v[230:233], v[48:63]
	ds_read_b64_tr_b16 v[204:205], v182 offset:37888
	ds_read_b64_tr_b16 v[206:207], v182 offset:39936
	v_exp_f32_e32 v136, v136
	v_exp_f32_e32 v137, v137
	s_waitcnt lgkmcnt(10)
	v_mfma_f32_32x32x16_bf16 v[48:63], v[188:191], v[234:237], v[48:63]
	ds_read_b64_tr_b16 v[208:209], v182 offset:41984
	ds_read_b64_tr_b16 v[210:211], v182 offset:44032
	v_exp_f32_e32 v138, v138
	v_exp_f32_e32 v139, v139
	s_waitcnt vmcnt(1)
	ds_write_b128 v180, v[164:167] offset:0
	s_waitcnt lgkmcnt(11)
	v_mfma_f32_32x32x16_bf16 v[48:63], v[192:195], v[238:241], v[48:63]
	ds_read_b64_tr_b16 v[212:213], v182 offset:46080
	ds_read_b64_tr_b16 v[214:215], v182 offset:48128
	v_exp_f32_e32 v140, v140
	v_exp_f32_e32 v141, v141
	s_waitcnt lgkmcnt(10)
	v_mfma_f32_32x32x16_bf16 v[48:63], v[196:199], v[242:245], v[48:63]
	ds_read_b64_tr_b16 v[230:231], v182 offset:34304
	ds_read_b64_tr_b16 v[232:233], v182 offset:36352
	v_exp_f32_e32 v142, v142
	v_exp_f32_e32 v143, v143
	s_waitcnt vmcnt(0)
	ds_write_b128 v180, v[160:163] offset:8192
	s_waitcnt lgkmcnt(11)
	v_mfma_f32_32x32x16_bf16 v[32:47], v[184:187], v[200:203], v[32:47]
	ds_read_b64_tr_b16 v[234:235], v182 offset:38400
	ds_read_b64_tr_b16 v[236:237], v182 offset:40448
	ds_read_b128 v[200:203], v172 offset:0
	v_exp_f32_e32 v144, v144
	v_exp_f32_e32 v145, v145
	s_waitcnt lgkmcnt(11)
	v_mfma_f32_32x32x16_bf16 v[32:47], v[188:191], v[204:207], v[32:47]
	ds_read_b64_tr_b16 v[238:239], v182 offset:42496
	ds_read_b64_tr_b16 v[240:241], v182 offset:44544
	ds_read_b128 v[204:207], v172 offset:8192
	v_exp_f32_e32 v146, v146
	v_exp_f32_e32 v147, v147
	s_waitcnt lgkmcnt(12)
	v_mfma_f32_32x32x16_bf16 v[32:47], v[192:195], v[208:211], v[32:47]
	ds_read_b64_tr_b16 v[242:243], v182 offset:46592
	ds_read_b64_tr_b16 v[244:245], v182 offset:48640
	ds_read_b128 v[208:211], v173 offset:0
	v_exp_f32_e32 v148, v148
	v_exp_f32_e32 v149, v149
	s_waitcnt lgkmcnt(12)
	v_mfma_f32_32x32x16_bf16 v[32:47], v[196:199], v[212:215], v[32:47]
	ds_read_b128 v[212:215], v173 offset:8192
	v_exp_f32_e32 v150, v150
	v_exp_f32_e32 v151, v151
	s_waitcnt lgkmcnt(11)
	v_mfma_f32_32x32x16_bf16 v[16:31], v[184:187], v[230:233], v[16:31]
	ds_read_b128 v[230:233], v174 offset:0
	v_exp_f32_e32 v152, v152
	v_exp_f32_e32 v153, v153
	s_waitcnt lgkmcnt(9)
	v_mfma_f32_32x32x16_bf16 v[16:31], v[188:191], v[234:237], v[16:31]
	ds_read_b128 v[234:237], v174 offset:8192
	v_exp_f32_e32 v154, v154
	v_exp_f32_e32 v155, v155
	s_waitcnt lgkmcnt(7)
	v_mfma_f32_32x32x16_bf16 v[16:31], v[192:195], v[238:241], v[16:31]
	ds_read_b128 v[238:241], v175 offset:0
	v_exp_f32_e32 v156, v156
	v_exp_f32_e32 v157, v157
	s_waitcnt lgkmcnt(5)
	v_mfma_f32_32x32x16_bf16 v[16:31], v[196:199], v[242:245], v[16:31]
	ds_read_b128 v[242:245], v175 offset:8192
	v_exp_f32_e32 v158, v158
	v_exp_f32_e32 v159, v159
	s_barrier
	v_mfma_f32_32x32x16_bf16 v[64:79], v[200:203], v[124:127], 0
	ds_read_b128 v[200:203], v176 offset:0
	v_cvt_pk_bf16_f32 v184, v128, v129
	v_add_f32_e32 v169, v169, v128
	v_add_f32_e32 v219, v219, v129
	global_load_dwordx4 v[246:249], v183, s[98:99]
	v_mfma_f32_32x32x16_bf16 v[80:95], v[204:207], v[124:127], 0
	ds_read_b128 v[204:207], v176 offset:8192
	v_cvt_pk_bf16_f32 v185, v130, v131
	v_add_f32_e32 v222, v222, v130
	v_add_f32_e32 v254, v254, v131
	s_waitcnt lgkmcnt(7)
	v_mfma_f32_32x32x16_bf16 v[64:79], v[208:211], v[120:123], v[64:79]
	ds_read_b128 v[208:211], v177 offset:0
	v_cvt_pk_bf16_f32 v186, v132, v133
	v_add_f32_e32 v169, v169, v132
	v_add_f32_e32 v219, v219, v133
	global_load_dwordx4 v[250:253], v183, s[100:101]
	s_add_u32 s98, s98, 0x150000
	s_addc_u32 s99, s99, 0
	s_add_u32 s100, s100, 0x150000
	s_addc_u32 s101, s101, 0
	s_waitcnt lgkmcnt(7)
	v_mfma_f32_32x32x16_bf16 v[80:95], v[212:215], v[120:123], v[80:95]
	ds_read_b128 v[212:215], v177 offset:8192
	v_cvt_pk_bf16_f32 v187, v134, v135
	v_add_f32_e32 v222, v222, v134
	v_add_f32_e32 v254, v254, v135
	s_waitcnt lgkmcnt(7)
	v_mfma_f32_32x32x16_bf16 v[64:79], v[230:233], v[116:119], v[64:79]
	ds_read_b128 v[230:233], v178 offset:0
	v_cvt_pk_bf16_f32 v188, v136, v137
	v_add_f32_e32 v169, v169, v136
	v_add_f32_e32 v219, v219, v137
	v_permlane32_swap_b32_e32 v184, v186
	global_load_dwordx4 v[164:167], v183, s[0:1] offset:512
	s_waitcnt lgkmcnt(7)
	v_mfma_f32_32x32x16_bf16 v[80:95], v[234:237], v[116:119], v[80:95]
	ds_read_b128 v[234:237], v178 offset:8192
	v_cvt_pk_bf16_f32 v189, v138, v139
	v_add_f32_e32 v222, v222, v138
	v_add_f32_e32 v254, v254, v139
	v_permlane32_swap_b32_e32 v185, v187
	s_waitcnt lgkmcnt(7)
	v_mfma_f32_32x32x16_bf16 v[64:79], v[238:241], v[112:115], v[64:79]
	ds_read_b128 v[238:241], v179 offset:0
	v_cvt_pk_bf16_f32 v190, v140, v141
	v_add_f32_e32 v169, v169, v140
	v_add_f32_e32 v219, v219, v141
	global_load_dwordx4 v[160:163], v183, s[4:5] offset:512
	s_add_u32 s0, s0, 0x150000
	s_addc_u32 s1, s1, 0
	s_add_u32 s4, s4, 0x150000
	s_addc_u32 s5, s5, 0
	s_waitcnt lgkmcnt(7)
	v_mfma_f32_32x32x16_bf16 v[80:95], v[242:245], v[112:115], v[80:95]
	ds_read_b128 v[242:245], v179 offset:8192
	v_cvt_pk_bf16_f32 v191, v142, v143
	v_add_f32_e32 v222, v222, v142
	v_add_f32_e32 v254, v254, v143
	s_waitcnt lgkmcnt(7)
	v_mfma_f32_32x32x16_bf16 v[64:79], v[200:203], v[108:111], v[64:79]
	v_cvt_pk_bf16_f32 v192, v144, v145
	v_add_f32_e32 v169, v169, v144
	v_add_f32_e32 v219, v219, v145
	v_permlane32_swap_b32_e32 v188, v190
	s_waitcnt lgkmcnt(6)
	v_mfma_f32_32x32x16_bf16 v[80:95], v[204:207], v[108:111], v[80:95]
	v_cvt_pk_bf16_f32 v193, v146, v147
	v_add_f32_e32 v222, v222, v146
	v_add_f32_e32 v254, v254, v147
	v_permlane32_swap_b32_e32 v189, v191
	s_waitcnt lgkmcnt(5)
; __device__ __forceinline__ void finishSM(f32x16& p0, f32x16& p1, float alpha, float& l_reg, bf16x8& pa0, bf16x8& pa1, bf16x8& pa2, bf16x8& pa3) {
; #pragma unroll
;   for (int r = 0; r < 16; ++r) p1[r] = __builtin_amdgcn_exp2f(p1[r]);
;   float ps = 0;
; #pragma unroll
;   for (int r = 0; r < 16; ++r) ps += p0[r];
; #pragma unroll
;   for (int r = 0; r < 16; ++r) ps += p1[r];
;   { auto rr = __builtin_amdgcn_permlane32_swap(__float_as_uint(ps), __float_as_uint(ps), false, false);
;     ps = __uint_as_float(rr[0]) + __uint_as_float(rr[1]); }
;   l_reg = l_reg * alpha + ps;
;     ...
;   PK4(p0, 0, pa0); PK4(p0, 8, pa1); PK4(p1, 0, pa2); PK4(p1, 8, pa3);
;     ...
; }
; __device__ __forceinline__ void qkt(f32x16& p0, f32x16& p1, const bf16* Ks, const bf16x8* qr, int r32, int hi) {
;   p0 = f32x16{}; p1 = f32x16{};
; #pragma unroll
;   for (int d0 = 0; d0 < 8; ++d0) { int cb = (d0 * 16 + hi * 8) * 2;
;     bf16x8 b0 = *reinterpret_cast<const bf16x8*>((const char*)Ks + KSWZ(r32, cb));
;     bf16x8 b1 = *reinterpret_cast<const bf16x8*>((const char*)Ks + KSWZ(32 + r32, cb));
;     p0 = __builtin_amdgcn_mfma_f32_32x32x16_bf16(b0, qr[d0], p0, 0, 0, 0);
;     p1 = __builtin_amdgcn_mfma_f32_32x32x16_bf16(b1, qr[d0], p1, 0, 0, 0); }
; }
; __device__ __forceinline__ int v_st(int k, int c) { const int kk = (k & ~0xC) | ((k & 4) << 1) | ((k & 8) >> 1); return ((kk >> 3) * 4 + (c >> 5)) * 512 + ((kk & 7) * 32 + (c & 31)) * 2; }
; __device__ __forceinline__ int v_rd_base(int lane) { return ((lane & 3) << 3) | (((lane >> 2) & 3) << 6) | (((lane >> 4) & 1) << 5) | (((lane >> 5) & 1) << 8); }
; template <int OFF> __device__ __forceinline__ s16x4 tr_read(int vb) {
;   s16x4 r; asm volatile("ds_read_b64_tr_b16 %0, %1 offset:%2" : "=&v"(r) : "v"(vb), "i"(OFF) : "memory"); return r;
; }
; template <int D0> __device__ __forceinline__ void pv_one(f32x16& od, int vb, bf16x8 pa0, bf16x8 pa1, bf16x8 pa2, bf16x8 pa3) {
;   const s16x4 l0 = tr_read<v_rd_off(D0, 0, 0)>(vb), h0 = tr_read<v_rd_off(D0, 0, 1)>(vb), l1 = tr_read<v_rd_off(D0, 1, 0)>(vb), h1 = tr_read<v_rd_off(D0, 1, 1)>(vb);
;   const s16x4 l2 = tr_read<v_rd_off(D0, 2, 0)>(vb), h2 = tr_read<v_rd_off(D0, 2, 1)>(vb), l3 = tr_read<v_rd_off(D0, 3, 0)>(vb), h3 = tr_read<v_rd_off(D0, 3, 1)>(vb);
;   asm volatile("s_waitcnt lgkmcnt(0)" ::: "memory"); SBAR();
;     ...
;   od = __builtin_amdgcn_mfma_f32_32x32x16_bf16(pa0, PK(l0, h0), od, 0, 0, 0);
	v_mfma_f32_32x32x16_bf16 v[64:79], v[208:211], v[104:107], v[64:79]
	v_cvt_pk_bf16_f32 v194, v148, v149
	v_add_f32_e32 v169, v169, v148
	v_add_f32_e32 v219, v219, v149
	s_waitcnt lgkmcnt(4)
	v_mfma_f32_32x32x16_bf16 v[80:95], v[212:215], v[104:107], v[80:95]
	ds_read_b64_tr_b16 v[200:201], v182 offset:49152
	ds_read_b64_tr_b16 v[202:203], v182 offset:51200
	v_cvt_pk_bf16_f32 v195, v150, v151
	v_add_f32_e32 v222, v222, v150
	v_add_f32_e32 v254, v254, v151
	s_waitcnt lgkmcnt(5)
	v_mfma_f32_32x32x16_bf16 v[64:79], v[230:233], v[100:103], v[64:79]
	ds_read_b64_tr_b16 v[204:205], v182 offset:53248
	ds_read_b64_tr_b16 v[206:207], v182 offset:55296
	v_cvt_pk_bf16_f32 v196, v152, v153
	v_add_f32_e32 v169, v169, v152
	v_add_f32_e32 v219, v219, v153
	v_permlane32_swap_b32_e32 v192, v194
	s_waitcnt lgkmcnt(6)
	v_mfma_f32_32x32x16_bf16 v[80:95], v[234:237], v[100:103], v[80:95]
	ds_read_b64_tr_b16 v[208:209], v182 offset:57344
	ds_read_b64_tr_b16 v[210:211], v182 offset:59392
	v_cvt_pk_bf16_f32 v197, v154, v155
	v_add_f32_e32 v222, v222, v154
	v_add_f32_e32 v254, v254, v155
	v_permlane32_swap_b32_e32 v193, v195
	s_waitcnt lgkmcnt(7)
	v_mfma_f32_32x32x16_bf16 v[64:79], v[238:241], v[96:99], v[64:79]
	ds_read_b64_tr_b16 v[212:213], v182 offset:61440
	ds_read_b64_tr_b16 v[214:215], v182 offset:63488
	v_cvt_pk_bf16_f32 v198, v156, v157
	v_add_f32_e32 v169, v169, v156
	v_add_f32_e32 v219, v219, v157
	s_waitcnt lgkmcnt(8)
	v_mfma_f32_32x32x16_bf16 v[80:95], v[242:245], v[96:99], v[80:95]
	ds_read_b64_tr_b16 v[230:231], v182 offset:49664
	ds_read_b64_tr_b16 v[232:233], v182 offset:51712
	v_cvt_pk_bf16_f32 v199, v158, v159
	v_add_f32_e32 v222, v222, v158
	v_add_f32_e32 v254, v254, v159
	v_permlane32_swap_b32_e32 v196, v198
	v_permlane32_swap_b32_e32 v197, v199
	s_waitcnt lgkmcnt(8)
	v_mfma_f32_32x32x16_bf16 v[0:15], v[184:187], v[200:203], v[0:15]
	ds_read_b64_tr_b16 v[234:235], v182 offset:53760
	ds_read_b64_tr_b16 v[236:237], v182 offset:55808
	v_exp_f32_e32 v64, v64
	v_exp_f32_e32 v65, v65
	s_waitcnt lgkmcnt(8)
	v_mfma_f32_32x32x16_bf16 v[0:15], v[188:191], v[204:207], v[0:15]
	ds_read_b64_tr_b16 v[238:239], v182 offset:57856
	ds_read_b64_tr_b16 v[240:241], v182 offset:59904
	v_exp_f32_e32 v66, v66
	v_exp_f32_e32 v67, v67
	s_waitcnt vmcnt(3)
	ds_write_b128 v181, v[246:249] offset:32768
	s_waitcnt lgkmcnt(9)
	v_mfma_f32_32x32x16_bf16 v[0:15], v[192:195], v[208:211], v[0:15]
	ds_read_b64_tr_b16 v[242:243], v182 offset:61952
	ds_read_b64_tr_b16 v[244:245], v182 offset:64000
	v_exp_f32_e32 v68, v68
	v_exp_f32_e32 v69, v69
	s_waitcnt lgkmcnt(9)
	v_mfma_f32_32x32x16_bf16 v[0:15], v[196:199], v[212:215], v[0:15]
	ds_read_b64_tr_b16 v[200:201], v182 offset:50176
	ds_read_b64_tr_b16 v[202:203], v182 offset:52224
	v_exp_f32_e32 v70, v70
	v_exp_f32_e32 v71, v71
	s_waitcnt vmcnt(2)
	ds_write_b128 v181, v[250:253] offset:40960
	s_waitcnt lgkmcnt(10)
	v_mfma_f32_32x32x16_bf16 v[48:63], v[184:187], v[230:233], v[48:63]
	ds_read_b64_tr_b16 v[204:205], v182 offset:54272
	ds_read_b64_tr_b16 v[206:207], v182 offset:56320
	v_exp_f32_e32 v72, v72
	v_exp_f32_e32 v73, v73
	s_waitcnt lgkmcnt(10)
	v_mfma_f32_32x32x16_bf16 v[48:63], v[188:191], v[234:237], v[48:63]
	ds_read_b64_tr_b16 v[208:209], v182 offset:58368
	ds_read_b64_tr_b16 v[210:211], v182 offset:60416
	v_exp_f32_e32 v74, v74
	v_exp_f32_e32 v75, v75
	s_waitcnt vmcnt(1)
	ds_write_b128 v180, v[164:167] offset:16384
	s_waitcnt lgkmcnt(11)
	v_mfma_f32_32x32x16_bf16 v[48:63], v[192:195], v[238:241], v[48:63]
	ds_read_b64_tr_b16 v[212:213], v182 offset:62464
	ds_read_b64_tr_b16 v[214:215], v182 offset:64512
	v_exp_f32_e32 v76, v76
	v_exp_f32_e32 v77, v77
	s_waitcnt lgkmcnt(10)
	v_mfma_f32_32x32x16_bf16 v[48:63], v[196:199], v[242:245], v[48:63]
	ds_read_b64_tr_b16 v[230:231], v182 offset:50688
	ds_read_b64_tr_b16 v[232:233], v182 offset:52736
	v_exp_f32_e32 v78, v78
	v_exp_f32_e32 v79, v79
	s_waitcnt vmcnt(0)
	ds_write_b128 v180, v[160:163] offset:24576
	s_waitcnt lgkmcnt(11)
	v_mfma_f32_32x32x16_bf16 v[32:47], v[184:187], v[200:203], v[32:47]
	ds_read_b64_tr_b16 v[234:235], v182 offset:54784
	ds_read_b64_tr_b16 v[236:237], v182 offset:56832
	ds_read_b128 v[200:203], v172 offset:16384
	v_exp_f32_e32 v80, v80
	v_exp_f32_e32 v81, v81
	s_waitcnt lgkmcnt(11)
	v_mfma_f32_32x32x16_bf16 v[32:47], v[188:191], v[204:207], v[32:47]
	ds_read_b64_tr_b16 v[238:239], v182 offset:58880
	ds_read_b64_tr_b16 v[240:241], v182 offset:60928
	ds_read_b128 v[204:207], v172 offset:24576
	v_exp_f32_e32 v82, v82
	v_exp_f32_e32 v83, v83
	s_waitcnt lgkmcnt(12)
	v_mfma_f32_32x32x16_bf16 v[32:47], v[192:195], v[208:211], v[32:47]
	ds_read_b64_tr_b16 v[242:243], v182 offset:62976
	ds_read_b64_tr_b16 v[244:245], v182 offset:65024
	ds_read_b128 v[208:211], v173 offset:16384
	v_exp_f32_e32 v84, v84
	v_exp_f32_e32 v85, v85
	s_waitcnt lgkmcnt(12)
	v_mfma_f32_32x32x16_bf16 v[32:47], v[196:199], v[212:215], v[32:47]
	ds_read_b128 v[212:215], v173 offset:24576
	v_exp_f32_e32 v86, v86
	v_exp_f32_e32 v87, v87
	s_waitcnt lgkmcnt(11)
	v_mfma_f32_32x32x16_bf16 v[16:31], v[184:187], v[230:233], v[16:31]
	ds_read_b128 v[230:233], v174 offset:16384
	v_exp_f32_e32 v88, v88
	v_exp_f32_e32 v89, v89
	s_waitcnt lgkmcnt(9)
	v_mfma_f32_32x32x16_bf16 v[16:31], v[188:191], v[234:237], v[16:31]
	ds_read_b128 v[234:237], v174 offset:24576
	v_exp_f32_e32 v90, v90
	v_exp_f32_e32 v91, v91
	s_waitcnt lgkmcnt(7)
	v_mfma_f32_32x32x16_bf16 v[16:31], v[192:195], v[238:241], v[16:31]
	ds_read_b128 v[238:241], v175 offset:16384
	v_exp_f32_e32 v92, v92
	v_exp_f32_e32 v93, v93
	s_waitcnt lgkmcnt(5)
	v_mfma_f32_32x32x16_bf16 v[16:31], v[196:199], v[242:245], v[16:31]
	ds_read_b128 v[242:245], v175 offset:24576
	v_exp_f32_e32 v94, v94
	v_exp_f32_e32 v95, v95
	s_barrier
; __device__ __forceinline__ void finishSM(f32x16& p0, f32x16& p1, float alpha, float& l_reg, bf16x8& pa0, bf16x8& pa1, bf16x8& pa2, bf16x8& pa3) {
; #pragma unroll
;   for (int r = 0; r < 16; ++r) p1[r] = __builtin_amdgcn_exp2f(p1[r]);
;   float ps = 0;
; #pragma unroll
;   for (int r = 0; r < 16; ++r) ps += p0[r];
; #pragma unroll
;   for (int r = 0; r < 16; ++r) ps += p1[r];
;   { auto rr = __builtin_amdgcn_permlane32_swap(__float_as_uint(ps), __float_as_uint(ps), false, false);
;     ps = __uint_as_float(rr[0]) + __uint_as_float(rr[1]); }
;   l_reg = l_reg * alpha + ps;
;     ...
;   PK4(p0, 0, pa0); PK4(p0, 8, pa1); PK4(p1, 0, pa2); PK4(p1, 8, pa3);
;     ...
; }
; __device__ __forceinline__ void qkt(f32x16& p0, f32x16& p1, const bf16* Ks, const bf16x8* qr, int r32, int hi) {
;   p0 = f32x16{}; p1 = f32x16{};
; #pragma unroll
;   for (int d0 = 0; d0 < 8; ++d0) { int cb = (d0 * 16 + hi * 8) * 2;
;     bf16x8 b0 = *reinterpret_cast<const bf16x8*>((const char*)Ks + KSWZ(r32, cb));
;     bf16x8 b1 = *reinterpret_cast<const bf16x8*>((const char*)Ks + KSWZ(32 + r32, cb));
;     p0 = __builtin_amdgcn_mfma_f32_32x32x16_bf16(b0, qr[d0], p0, 0, 0, 0);
;     p1 = __builtin_amdgcn_mfma_f32_32x32x16_bf16(b1, qr[d0], p1, 0, 0, 0); }
; }
; __device__ __forceinline__ int v_st(int k, int c) { const int kk = (k & ~0xC) | ((k & 4) << 1) | ((k & 8) >> 1); return ((kk >> 3) * 4 + (c >> 5)) * 512 + ((kk & 7) * 32 + (c & 31)) * 2; }
; __device__ __forceinline__ int v_rd_base(int lane) { return ((lane & 3) << 3) | (((lane >> 2) & 3) << 6) | (((lane >> 4) & 1) << 5) | (((lane >> 5) & 1) << 8); }
; template <int OFF> __device__ __forceinline__ s16x4 tr_read(int vb) {
;   s16x4 r; asm volatile("ds_read_b64_tr_b16 %0, %1 offset:%2" : "=&v"(r) : "v"(vb), "i"(OFF) : "memory"); return r;
; }
; template <int D0> __device__ __forceinline__ void pv_one(f32x16& od, int vb, bf16x8 pa0, bf16x8 pa1, bf16x8 pa2, bf16x8 pa3) {
;   const s16x4 l0 = tr_read<v_rd_off(D0, 0, 0)>(vb), h0 = tr_read<v_rd_off(D0, 0, 1)>(vb), l1 = tr_read<v_rd_off(D0, 1, 0)>(vb), h1 = tr_read<v_rd_off(D0, 1, 1)>(vb);
;   const s16x4 l2 = tr_read<v_rd_off(D0, 2, 0)>(vb), h2 = tr_read<v_rd_off(D0, 2, 1)>(vb), l3 = tr_read<v_rd_off(D0, 3, 0)>(vb), h3 = tr_read<v_rd_off(D0, 3, 1)>(vb);
;   asm volatile("s_waitcnt lgkmcnt(0)" ::: "memory"); SBAR();
;     ...
;   od = __builtin_amdgcn_mfma_f32_32x32x16_bf16(pa0, PK(l0, h0), od, 0, 0, 0);
	s_add_i32 s44, s44, 1
	s_cmp_lt_u32 s44, 63
	s_cbranch_scc1 .Ldense_loop
	v_mfma_f32_32x32x16_bf16 v[128:143], v[200:203], v[124:127], 0
	ds_read_b128 v[200:203], v176 offset:16384
	v_cvt_pk_bf16_f32 v184, v64, v65
	v_add_f32_e32 v169, v169, v64
	v_add_f32_e32 v219, v219, v65
	global_load_dwordx4 v[246:249], v183, s[98:99]
	v_mfma_f32_32x32x16_bf16 v[144:159], v[204:207], v[124:127], 0
	ds_read_b128 v[204:207], v176 offset:24576
	v_cvt_pk_bf16_f32 v185, v66, v67
	v_add_f32_e32 v222, v222, v66
	v_add_f32_e32 v254, v254, v67
	s_waitcnt lgkmcnt(7)
	v_mfma_f32_32x32x16_bf16 v[128:143], v[208:211], v[120:123], v[128:143]
	ds_read_b128 v[208:211], v177 offset:16384
	v_cvt_pk_bf16_f32 v186, v68, v69
	v_add_f32_e32 v169, v169, v68
	v_add_f32_e32 v219, v219, v69
	global_load_dwordx4 v[250:253], v183, s[100:101]
	s_add_u32 s98, s98, 0x150000
	s_addc_u32 s99, s99, 0
	s_add_u32 s100, s100, 0x150000
	s_addc_u32 s101, s101, 0
	s_waitcnt lgkmcnt(7)
	v_mfma_f32_32x32x16_bf16 v[144:159], v[212:215], v[120:123], v[144:159]
	ds_read_b128 v[212:215], v177 offset:24576
	v_cvt_pk_bf16_f32 v187, v70, v71
	v_add_f32_e32 v222, v222, v70
	v_add_f32_e32 v254, v254, v71
	s_waitcnt lgkmcnt(7)
	v_mfma_f32_32x32x16_bf16 v[128:143], v[230:233], v[116:119], v[128:143]
	ds_read_b128 v[230:233], v178 offset:16384
	v_cvt_pk_bf16_f32 v188, v72, v73
	v_add_f32_e32 v169, v169, v72
	v_add_f32_e32 v219, v219, v73
	v_permlane32_swap_b32_e32 v184, v186
	global_load_dwordx4 v[164:167], v183, s[0:1] offset:512
	s_waitcnt lgkmcnt(7)
	v_mfma_f32_32x32x16_bf16 v[144:159], v[234:237], v[116:119], v[144:159]
	ds_read_b128 v[234:237], v178 offset:24576
	v_cvt_pk_bf16_f32 v189, v74, v75
	v_add_f32_e32 v222, v222, v74
	v_add_f32_e32 v254, v254, v75
	v_permlane32_swap_b32_e32 v185, v187
	s_waitcnt lgkmcnt(7)
	v_mfma_f32_32x32x16_bf16 v[128:143], v[238:241], v[112:115], v[128:143]
	ds_read_b128 v[238:241], v179 offset:16384
	v_cvt_pk_bf16_f32 v190, v76, v77
	v_add_f32_e32 v169, v169, v76
	v_add_f32_e32 v219, v219, v77
	global_load_dwordx4 v[160:163], v183, s[4:5] offset:512
	s_add_u32 s0, s0, 0x150000
	s_addc_u32 s1, s1, 0
	s_add_u32 s4, s4, 0x150000
	s_addc_u32 s5, s5, 0
	s_waitcnt lgkmcnt(7)
	v_mfma_f32_32x32x16_bf16 v[144:159], v[242:245], v[112:115], v[144:159]
	ds_read_b128 v[242:245], v179 offset:24576
	v_cvt_pk_bf16_f32 v191, v78, v79
	v_add_f32_e32 v222, v222, v78
	v_add_f32_e32 v254, v254, v79
	s_waitcnt lgkmcnt(7)
	v_mfma_f32_32x32x16_bf16 v[128:143], v[200:203], v[108:111], v[128:143]
	v_cvt_pk_bf16_f32 v192, v80, v81
	v_add_f32_e32 v169, v169, v80
	v_add_f32_e32 v219, v219, v81
	v_permlane32_swap_b32_e32 v188, v190
	s_waitcnt lgkmcnt(6)
	v_mfma_f32_32x32x16_bf16 v[144:159], v[204:207], v[108:111], v[144:159]
	v_cvt_pk_bf16_f32 v193, v82, v83
	v_add_f32_e32 v222, v222, v82
	v_add_f32_e32 v254, v254, v83
	v_permlane32_swap_b32_e32 v189, v191
	s_waitcnt lgkmcnt(5)
	v_mfma_f32_32x32x16_bf16 v[128:143], v[208:211], v[104:107], v[128:143]
	v_cvt_pk_bf16_f32 v194, v84, v85
	v_add_f32_e32 v169, v169, v84
	v_add_f32_e32 v219, v219, v85
	s_waitcnt lgkmcnt(4)
	v_mfma_f32_32x32x16_bf16 v[144:159], v[212:215], v[104:107], v[144:159]
	ds_read_b64_tr_b16 v[200:201], v182 offset:0
	ds_read_b64_tr_b16 v[202:203], v182 offset:2048
	v_cvt_pk_bf16_f32 v195, v86, v87
	v_add_f32_e32 v222, v222, v86
	v_add_f32_e32 v254, v254, v87
	s_waitcnt lgkmcnt(5)
	v_mfma_f32_32x32x16_bf16 v[128:143], v[230:233], v[100:103], v[128:143]
	ds_read_b64_tr_b16 v[204:205], v182 offset:4096
	ds_read_b64_tr_b16 v[206:207], v182 offset:6144
	v_cvt_pk_bf16_f32 v196, v88, v89
	v_add_f32_e32 v169, v169, v88
	v_add_f32_e32 v219, v219, v89
	v_permlane32_swap_b32_e32 v192, v194
	s_waitcnt lgkmcnt(6)
	v_mfma_f32_32x32x16_bf16 v[144:159], v[234:237], v[100:103], v[144:159]
	ds_read_b64_tr_b16 v[208:209], v182 offset:8192
	ds_read_b64_tr_b16 v[210:211], v182 offset:10240
	v_cvt_pk_bf16_f32 v197, v90, v91
	v_add_f32_e32 v222, v222, v90
	v_add_f32_e32 v254, v254, v91
	v_permlane32_swap_b32_e32 v193, v195
	s_waitcnt lgkmcnt(7)
	v_mfma_f32_32x32x16_bf16 v[128:143], v[238:241], v[96:99], v[128:143]
	ds_read_b64_tr_b16 v[212:213], v182 offset:12288
	ds_read_b64_tr_b16 v[214:215], v182 offset:14336
	v_cvt_pk_bf16_f32 v198, v92, v93
	v_add_f32_e32 v169, v169, v92
	v_add_f32_e32 v219, v219, v93
	s_waitcnt lgkmcnt(8)
	v_mfma_f32_32x32x16_bf16 v[144:159], v[242:245], v[96:99], v[144:159]
	ds_read_b64_tr_b16 v[230:231], v182 offset:512
	ds_read_b64_tr_b16 v[232:233], v182 offset:2560
	v_cvt_pk_bf16_f32 v199, v94, v95
	v_add_f32_e32 v222, v222, v94
	v_add_f32_e32 v254, v254, v95
	v_permlane32_swap_b32_e32 v196, v198
	v_permlane32_swap_b32_e32 v197, v199
	s_waitcnt lgkmcnt(8)
	v_mfma_f32_32x32x16_bf16 v[0:15], v[184:187], v[200:203], v[0:15]
	ds_read_b64_tr_b16 v[234:235], v182 offset:4608
	ds_read_b64_tr_b16 v[236:237], v182 offset:6656
	v_exp_f32_e32 v128, v128
	v_exp_f32_e32 v129, v129
	s_waitcnt lgkmcnt(8)
	v_mfma_f32_32x32x16_bf16 v[0:15], v[188:191], v[204:207], v[0:15]
	ds_read_b64_tr_b16 v[238:239], v182 offset:8704
	ds_read_b64_tr_b16 v[240:241], v182 offset:10752
	v_exp_f32_e32 v130, v130
	v_exp_f32_e32 v131, v131
	s_waitcnt vmcnt(3)
	ds_write_b128 v181, v[246:249] offset:49152
	s_waitcnt lgkmcnt(9)
	v_mfma_f32_32x32x16_bf16 v[0:15], v[192:195], v[208:211], v[0:15]
	ds_read_b64_tr_b16 v[242:243], v182 offset:12800
	ds_read_b64_tr_b16 v[244:245], v182 offset:14848
	v_exp_f32_e32 v132, v132
	v_exp_f32_e32 v133, v133
	s_waitcnt lgkmcnt(9)
	v_mfma_f32_32x32x16_bf16 v[0:15], v[196:199], v[212:215], v[0:15]
	ds_read_b64_tr_b16 v[200:201], v182 offset:1024
	ds_read_b64_tr_b16 v[202:203], v182 offset:3072
	v_exp_f32_e32 v134, v134
	v_exp_f32_e32 v135, v135
	s_waitcnt vmcnt(2)
; __device__ __forceinline__ void finishSM(f32x16& p0, f32x16& p1, float alpha, float& l_reg, bf16x8& pa0, bf16x8& pa1, bf16x8& pa2, bf16x8& pa3) {
; #pragma unroll
;   for (int r = 0; r < 16; ++r) p1[r] = __builtin_amdgcn_exp2f(p1[r]);
;   float ps = 0;
; #pragma unroll
;   for (int r = 0; r < 16; ++r) ps += p0[r];
; #pragma unroll
;   for (int r = 0; r < 16; ++r) ps += p1[r];
;   { auto rr = __builtin_amdgcn_permlane32_swap(__float_as_uint(ps), __float_as_uint(ps), false, false);
;     ps = __uint_as_float(rr[0]) + __uint_as_float(rr[1]); }
;   l_reg = l_reg * alpha + ps;
;     ...
;   PK4(p0, 0, pa0); PK4(p0, 8, pa1); PK4(p1, 0, pa2); PK4(p1, 8, pa3);
;     ...
; }
; __device__ __forceinline__ void qkt(f32x16& p0, f32x16& p1, const bf16* Ks, const bf16x8* qr, int r32, int hi) {
;   p0 = f32x16{}; p1 = f32x16{};
; #pragma unroll
;   for (int d0 = 0; d0 < 8; ++d0) { int cb = (d0 * 16 + hi * 8) * 2;
;     bf16x8 b0 = *reinterpret_cast<const bf16x8*>((const char*)Ks + KSWZ(r32, cb));
;     bf16x8 b1 = *reinterpret_cast<const bf16x8*>((const char*)Ks + KSWZ(32 + r32, cb));
;     p0 = __builtin_amdgcn_mfma_f32_32x32x16_bf16(b0, qr[d0], p0, 0, 0, 0);
;     p1 = __builtin_amdgcn_mfma_f32_32x32x16_bf16(b1, qr[d0], p1, 0, 0, 0); }
; }
; __device__ __forceinline__ int v_st(int k, int c) { const int kk = (k & ~0xC) | ((k & 4) << 1) | ((k & 8) >> 1); return ((kk >> 3) * 4 + (c >> 5)) * 512 + ((kk & 7) * 32 + (c & 31)) * 2; }
; __device__ __forceinline__ int v_rd_base(int lane) { return ((lane & 3) << 3) | (((lane >> 2) & 3) << 6) | (((lane >> 4) & 1) << 5) | (((lane >> 5) & 1) << 8); }
; template <int OFF> __device__ __forceinline__ s16x4 tr_read(int vb) {
;   s16x4 r; asm volatile("ds_read_b64_tr_b16 %0, %1 offset:%2" : "=&v"(r) : "v"(vb), "i"(OFF) : "memory"); return r;
; }
; template <int D0> __device__ __forceinline__ void pv_one(f32x16& od, int vb, bf16x8 pa0, bf16x8 pa1, bf16x8 pa2, bf16x8 pa3) {
;   const s16x4 l0 = tr_read<v_rd_off(D0, 0, 0)>(vb), h0 = tr_read<v_rd_off(D0, 0, 1)>(vb), l1 = tr_read<v_rd_off(D0, 1, 0)>(vb), h1 = tr_read<v_rd_off(D0, 1, 1)>(vb);
;   const s16x4 l2 = tr_read<v_rd_off(D0, 2, 0)>(vb), h2 = tr_read<v_rd_off(D0, 2, 1)>(vb), l3 = tr_read<v_rd_off(D0, 3, 0)>(vb), h3 = tr_read<v_rd_off(D0, 3, 1)>(vb);
;   asm volatile("s_waitcnt lgkmcnt(0)" ::: "memory"); SBAR();
;     ...
;   od = __builtin_amdgcn_mfma_f32_32x32x16_bf16(pa0, PK(l0, h0), od, 0, 0, 0);
	ds_write_b128 v181, v[250:253] offset:57344
	s_waitcnt lgkmcnt(10)
	v_mfma_f32_32x32x16_bf16 v[48:63], v[184:187], v[230:233], v[48:63]
	ds_read_b64_tr_b16 v[204:205], v182 offset:5120
	ds_read_b64_tr_b16 v[206:207], v182 offset:7168
	v_exp_f32_e32 v136, v136
	v_exp_f32_e32 v137, v137
	s_waitcnt lgkmcnt(10)
	v_mfma_f32_32x32x16_bf16 v[48:63], v[188:191], v[234:237], v[48:63]
	ds_read_b64_tr_b16 v[208:209], v182 offset:9216
	ds_read_b64_tr_b16 v[210:211], v182 offset:11264
	v_exp_f32_e32 v138, v138
	v_exp_f32_e32 v139, v139
	s_waitcnt vmcnt(1)
	ds_write_b128 v180, v[164:167] offset:32768
	s_waitcnt lgkmcnt(11)
	v_mfma_f32_32x32x16_bf16 v[48:63], v[192:195], v[238:241], v[48:63]
	ds_read_b64_tr_b16 v[212:213], v182 offset:13312
	ds_read_b64_tr_b16 v[214:215], v182 offset:15360
	v_exp_f32_e32 v140, v140
	v_exp_f32_e32 v141, v141
	s_waitcnt lgkmcnt(10)
	v_mfma_f32_32x32x16_bf16 v[48:63], v[196:199], v[242:245], v[48:63]
	ds_read_b64_tr_b16 v[230:231], v182 offset:1536
	ds_read_b64_tr_b16 v[232:233], v182 offset:3584
	v_exp_f32_e32 v142, v142
	v_exp_f32_e32 v143, v143
	s_waitcnt vmcnt(0)
	ds_write_b128 v180, v[160:163] offset:40960
	s_waitcnt lgkmcnt(11)
	v_mfma_f32_32x32x16_bf16 v[32:47], v[184:187], v[200:203], v[32:47]
	ds_read_b64_tr_b16 v[234:235], v182 offset:5632
	ds_read_b64_tr_b16 v[236:237], v182 offset:7680
	ds_read_b128 v[200:203], v172 offset:32768
	v_exp_f32_e32 v144, v144
	v_exp_f32_e32 v145, v145
	s_waitcnt lgkmcnt(11)
	v_mfma_f32_32x32x16_bf16 v[32:47], v[188:191], v[204:207], v[32:47]
	ds_read_b64_tr_b16 v[238:239], v182 offset:9728
	ds_read_b64_tr_b16 v[240:241], v182 offset:11776
	ds_read_b128 v[204:207], v172 offset:40960
	v_exp_f32_e32 v146, v146
	v_exp_f32_e32 v147, v147
	s_waitcnt lgkmcnt(12)
	v_mfma_f32_32x32x16_bf16 v[32:47], v[192:195], v[208:211], v[32:47]
	ds_read_b64_tr_b16 v[242:243], v182 offset:13824
	ds_read_b64_tr_b16 v[244:245], v182 offset:15872
	ds_read_b128 v[208:211], v173 offset:32768
	v_exp_f32_e32 v148, v148
	v_exp_f32_e32 v149, v149
	s_waitcnt lgkmcnt(12)
	v_mfma_f32_32x32x16_bf16 v[32:47], v[196:199], v[212:215], v[32:47]
	ds_read_b128 v[212:215], v173 offset:40960
	v_exp_f32_e32 v150, v150
	v_exp_f32_e32 v151, v151
	s_waitcnt lgkmcnt(11)
	v_mfma_f32_32x32x16_bf16 v[16:31], v[184:187], v[230:233], v[16:31]
	ds_read_b128 v[230:233], v174 offset:32768
	v_exp_f32_e32 v152, v152
	v_exp_f32_e32 v153, v153
	s_waitcnt lgkmcnt(9)
	v_mfma_f32_32x32x16_bf16 v[16:31], v[188:191], v[234:237], v[16:31]
	ds_read_b128 v[234:237], v174 offset:40960
	v_exp_f32_e32 v154, v154
	v_exp_f32_e32 v155, v155
	s_waitcnt lgkmcnt(7)
	v_mfma_f32_32x32x16_bf16 v[16:31], v[192:195], v[238:241], v[16:31]
	ds_read_b128 v[238:241], v175 offset:32768
	v_exp_f32_e32 v156, v156
	v_exp_f32_e32 v157, v157
	s_waitcnt lgkmcnt(5)
	v_mfma_f32_32x32x16_bf16 v[16:31], v[196:199], v[242:245], v[16:31]
	ds_read_b128 v[242:245], v175 offset:40960
	v_exp_f32_e32 v158, v158
	v_exp_f32_e32 v159, v159
	s_barrier
	v_mfma_f32_32x32x16_bf16 v[64:79], v[200:203], v[124:127], 0
	ds_read_b128 v[200:203], v176 offset:32768
	v_cvt_pk_bf16_f32 v184, v128, v129
	v_add_f32_e32 v169, v169, v128
	v_add_f32_e32 v219, v219, v129
	global_load_dwordx4 v[164:167], v183, s[0:1] offset:512
	v_mfma_f32_32x32x16_bf16 v[80:95], v[204:207], v[124:127], 0
	ds_read_b128 v[204:207], v176 offset:40960
	v_cvt_pk_bf16_f32 v185, v130, v131
	v_add_f32_e32 v222, v222, v130
	v_add_f32_e32 v254, v254, v131
	s_waitcnt lgkmcnt(7)
	v_mfma_f32_32x32x16_bf16 v[64:79], v[208:211], v[120:123], v[64:79]
	ds_read_b128 v[208:211], v177 offset:32768
	v_cvt_pk_bf16_f32 v186, v132, v133
	v_add_f32_e32 v169, v169, v132
	v_add_f32_e32 v219, v219, v133
	global_load_dwordx4 v[160:163], v183, s[4:5] offset:512
	s_add_u32 s0, s0, 0x150000
	s_addc_u32 s1, s1, 0
	s_add_u32 s4, s4, 0x150000
	s_addc_u32 s5, s5, 0
	s_waitcnt lgkmcnt(7)
	v_mfma_f32_32x32x16_bf16 v[80:95], v[212:215], v[120:123], v[80:95]
	ds_read_b128 v[212:215], v177 offset:40960
	v_cvt_pk_bf16_f32 v187, v134, v135
	v_add_f32_e32 v222, v222, v134
	v_add_f32_e32 v254, v254, v135
	s_waitcnt lgkmcnt(7)
	v_mfma_f32_32x32x16_bf16 v[64:79], v[230:233], v[116:119], v[64:79]
	ds_read_b128 v[230:233], v178 offset:32768
	v_cvt_pk_bf16_f32 v188, v136, v137
	v_add_f32_e32 v169, v169, v136
	v_add_f32_e32 v219, v219, v137
	v_permlane32_swap_b32_e32 v184, v186
	s_waitcnt lgkmcnt(7)
	v_mfma_f32_32x32x16_bf16 v[80:95], v[234:237], v[116:119], v[80:95]
	ds_read_b128 v[234:237], v178 offset:40960
	v_cvt_pk_bf16_f32 v189, v138, v139
	v_add_f32_e32 v222, v222, v138
	v_add_f32_e32 v254, v254, v139
	v_permlane32_swap_b32_e32 v185, v187
	s_waitcnt lgkmcnt(7)
	v_mfma_f32_32x32x16_bf16 v[64:79], v[238:241], v[112:115], v[64:79]
	ds_read_b128 v[238:241], v179 offset:32768
	v_cvt_pk_bf16_f32 v190, v140, v141
	v_add_f32_e32 v169, v169, v140
	v_add_f32_e32 v219, v219, v141
	s_waitcnt lgkmcnt(7)
	v_mfma_f32_32x32x16_bf16 v[80:95], v[242:245], v[112:115], v[80:95]
	ds_read_b128 v[242:245], v179 offset:40960
	v_cvt_pk_bf16_f32 v191, v142, v143
	v_add_f32_e32 v222, v222, v142
	v_add_f32_e32 v254, v254, v143
	s_waitcnt lgkmcnt(7)
	v_mfma_f32_32x32x16_bf16 v[64:79], v[200:203], v[108:111], v[64:79]
	v_cvt_pk_bf16_f32 v192, v144, v145
	v_add_f32_e32 v169, v169, v144
	v_add_f32_e32 v219, v219, v145
	v_permlane32_swap_b32_e32 v188, v190
	s_waitcnt lgkmcnt(6)
	v_mfma_f32_32x32x16_bf16 v[80:95], v[204:207], v[108:111], v[80:95]
	v_cvt_pk_bf16_f32 v193, v146, v147
	v_add_f32_e32 v222, v222, v146
	v_add_f32_e32 v254, v254, v147
	v_permlane32_swap_b32_e32 v189, v191
	s_waitcnt lgkmcnt(5)
; __device__ __forceinline__ void finishSM(f32x16& p0, f32x16& p1, float alpha, float& l_reg, bf16x8& pa0, bf16x8& pa1, bf16x8& pa2, bf16x8& pa3) {
; #pragma unroll
;   for (int r = 0; r < 16; ++r) p1[r] = __builtin_amdgcn_exp2f(p1[r]);
;   float ps = 0;
; #pragma unroll
;   for (int r = 0; r < 16; ++r) ps += p0[r];
; #pragma unroll
;   for (int r = 0; r < 16; ++r) ps += p1[r];
;   { auto rr = __builtin_amdgcn_permlane32_swap(__float_as_uint(ps), __float_as_uint(ps), false, false);
;     ps = __uint_as_float(rr[0]) + __uint_as_float(rr[1]); }
;   l_reg = l_reg * alpha + ps;
;     ...
;   PK4(p0, 0, pa0); PK4(p0, 8, pa1); PK4(p1, 0, pa2); PK4(p1, 8, pa3);
;     ...
; }
; __device__ __forceinline__ void qkt(f32x16& p0, f32x16& p1, const bf16* Ks, const bf16x8* qr, int r32, int hi) {
;   p0 = f32x16{}; p1 = f32x16{};
; #pragma unroll
;   for (int d0 = 0; d0 < 8; ++d0) { int cb = (d0 * 16 + hi * 8) * 2;
;     bf16x8 b0 = *reinterpret_cast<const bf16x8*>((const char*)Ks + KSWZ(r32, cb));
;     bf16x8 b1 = *reinterpret_cast<const bf16x8*>((const char*)Ks + KSWZ(32 + r32, cb));
;     p0 = __builtin_amdgcn_mfma_f32_32x32x16_bf16(b0, qr[d0], p0, 0, 0, 0);
;     p1 = __builtin_amdgcn_mfma_f32_32x32x16_bf16(b1, qr[d0], p1, 0, 0, 0); }
; }
; __device__ __forceinline__ int v_st(int k, int c) { const int kk = (k & ~0xC) | ((k & 4) << 1) | ((k & 8) >> 1); return ((kk >> 3) * 4 + (c >> 5)) * 512 + ((kk & 7) * 32 + (c & 31)) * 2; }
; __device__ __forceinline__ int v_rd_base(int lane) { return ((lane & 3) << 3) | (((lane >> 2) & 3) << 6) | (((lane >> 4) & 1) << 5) | (((lane >> 5) & 1) << 8); }
; template <int OFF> __device__ __forceinline__ s16x4 tr_read(int vb) {
;   s16x4 r; asm volatile("ds_read_b64_tr_b16 %0, %1 offset:%2" : "=&v"(r) : "v"(vb), "i"(OFF) : "memory"); return r;
; }
; template <int D0> __device__ __forceinline__ void pv_one(f32x16& od, int vb, bf16x8 pa0, bf16x8 pa1, bf16x8 pa2, bf16x8 pa3) {
;   const s16x4 l0 = tr_read<v_rd_off(D0, 0, 0)>(vb), h0 = tr_read<v_rd_off(D0, 0, 1)>(vb), l1 = tr_read<v_rd_off(D0, 1, 0)>(vb), h1 = tr_read<v_rd_off(D0, 1, 1)>(vb);
;   const s16x4 l2 = tr_read<v_rd_off(D0, 2, 0)>(vb), h2 = tr_read<v_rd_off(D0, 2, 1)>(vb), l3 = tr_read<v_rd_off(D0, 3, 0)>(vb), h3 = tr_read<v_rd_off(D0, 3, 1)>(vb);
;   asm volatile("s_waitcnt lgkmcnt(0)" ::: "memory"); SBAR();
;     ...
;   od = __builtin_amdgcn_mfma_f32_32x32x16_bf16(pa0, PK(l0, h0), od, 0, 0, 0);
	v_mfma_f32_32x32x16_bf16 v[64:79], v[208:211], v[104:107], v[64:79]
	v_cvt_pk_bf16_f32 v194, v148, v149
	v_add_f32_e32 v169, v169, v148
	v_add_f32_e32 v219, v219, v149
	s_waitcnt lgkmcnt(4)
	v_mfma_f32_32x32x16_bf16 v[80:95], v[212:215], v[104:107], v[80:95]
	ds_read_b64_tr_b16 v[200:201], v182 offset:16384
	ds_read_b64_tr_b16 v[202:203], v182 offset:18432
	v_cvt_pk_bf16_f32 v195, v150, v151
	v_add_f32_e32 v222, v222, v150
	v_add_f32_e32 v254, v254, v151
	s_waitcnt lgkmcnt(5)
	v_mfma_f32_32x32x16_bf16 v[64:79], v[230:233], v[100:103], v[64:79]
	ds_read_b64_tr_b16 v[204:205], v182 offset:20480
	ds_read_b64_tr_b16 v[206:207], v182 offset:22528
	v_cvt_pk_bf16_f32 v196, v152, v153
	v_add_f32_e32 v169, v169, v152
	v_add_f32_e32 v219, v219, v153
	v_permlane32_swap_b32_e32 v192, v194
	s_waitcnt lgkmcnt(6)
	v_mfma_f32_32x32x16_bf16 v[80:95], v[234:237], v[100:103], v[80:95]
	ds_read_b64_tr_b16 v[208:209], v182 offset:24576
	ds_read_b64_tr_b16 v[210:211], v182 offset:26624
	v_cvt_pk_bf16_f32 v197, v154, v155
	v_add_f32_e32 v222, v222, v154
	v_add_f32_e32 v254, v254, v155
	v_permlane32_swap_b32_e32 v193, v195
	s_waitcnt lgkmcnt(7)
	v_mfma_f32_32x32x16_bf16 v[64:79], v[238:241], v[96:99], v[64:79]
	ds_read_b64_tr_b16 v[212:213], v182 offset:28672
	ds_read_b64_tr_b16 v[214:215], v182 offset:30720
	v_cvt_pk_bf16_f32 v198, v156, v157
	v_add_f32_e32 v169, v169, v156
	v_add_f32_e32 v219, v219, v157
	s_waitcnt lgkmcnt(8)
	v_mfma_f32_32x32x16_bf16 v[80:95], v[242:245], v[96:99], v[80:95]
	ds_read_b64_tr_b16 v[230:231], v182 offset:16896
	ds_read_b64_tr_b16 v[232:233], v182 offset:18944
	v_cvt_pk_bf16_f32 v199, v158, v159
	v_add_f32_e32 v222, v222, v158
	v_add_f32_e32 v254, v254, v159
	v_permlane32_swap_b32_e32 v196, v198
	v_permlane32_swap_b32_e32 v197, v199
	s_waitcnt lgkmcnt(8)
	v_mfma_f32_32x32x16_bf16 v[0:15], v[184:187], v[200:203], v[0:15]
	ds_read_b64_tr_b16 v[234:235], v182 offset:20992
	ds_read_b64_tr_b16 v[236:237], v182 offset:23040
	v_exp_f32_e32 v64, v64
	v_exp_f32_e32 v65, v65
	s_waitcnt lgkmcnt(8)
	v_mfma_f32_32x32x16_bf16 v[0:15], v[188:191], v[204:207], v[0:15]
	ds_read_b64_tr_b16 v[238:239], v182 offset:25088
	ds_read_b64_tr_b16 v[240:241], v182 offset:27136
	v_exp_f32_e32 v66, v66
	v_exp_f32_e32 v67, v67
	s_waitcnt vmcnt(1)
	ds_write_b128 v180, v[164:167] offset:49152
	s_waitcnt lgkmcnt(9)
	v_mfma_f32_32x32x16_bf16 v[0:15], v[192:195], v[208:211], v[0:15]
	ds_read_b64_tr_b16 v[242:243], v182 offset:29184
	ds_read_b64_tr_b16 v[244:245], v182 offset:31232
	v_exp_f32_e32 v68, v68
	v_exp_f32_e32 v69, v69
	s_waitcnt lgkmcnt(9)
	v_mfma_f32_32x32x16_bf16 v[0:15], v[196:199], v[212:215], v[0:15]
	ds_read_b64_tr_b16 v[200:201], v182 offset:17408
	ds_read_b64_tr_b16 v[202:203], v182 offset:19456
	v_exp_f32_e32 v70, v70
	v_exp_f32_e32 v71, v71
	s_waitcnt vmcnt(0)
	ds_write_b128 v180, v[160:163] offset:57344
	s_waitcnt lgkmcnt(10)
	v_mfma_f32_32x32x16_bf16 v[48:63], v[184:187], v[230:233], v[48:63]
	ds_read_b64_tr_b16 v[204:205], v182 offset:21504
	ds_read_b64_tr_b16 v[206:207], v182 offset:23552
	v_exp_f32_e32 v72, v72
	v_exp_f32_e32 v73, v73
	s_waitcnt lgkmcnt(10)
	v_mfma_f32_32x32x16_bf16 v[48:63], v[188:191], v[234:237], v[48:63]
	ds_read_b64_tr_b16 v[208:209], v182 offset:25600
	ds_read_b64_tr_b16 v[210:211], v182 offset:27648
	v_exp_f32_e32 v74, v74
	v_exp_f32_e32 v75, v75
	s_waitcnt lgkmcnt(10)
	v_mfma_f32_32x32x16_bf16 v[48:63], v[192:195], v[238:241], v[48:63]
	ds_read_b64_tr_b16 v[212:213], v182 offset:29696
	ds_read_b64_tr_b16 v[214:215], v182 offset:31744
	v_exp_f32_e32 v76, v76
	v_exp_f32_e32 v77, v77
	s_waitcnt lgkmcnt(9)
	v_mfma_f32_32x32x16_bf16 v[48:63], v[196:199], v[242:245], v[48:63]
	ds_read_b64_tr_b16 v[230:231], v182 offset:17920
	ds_read_b64_tr_b16 v[232:233], v182 offset:19968
	v_exp_f32_e32 v78, v78
	v_exp_f32_e32 v79, v79
	s_waitcnt lgkmcnt(9)
	v_mfma_f32_32x32x16_bf16 v[32:47], v[184:187], v[200:203], v[32:47]
	ds_read_b64_tr_b16 v[234:235], v182 offset:22016
	ds_read_b64_tr_b16 v[236:237], v182 offset:24064
	ds_read_b128 v[200:203], v172 offset:49152
	v_exp_f32_e32 v80, v80
	v_exp_f32_e32 v81, v81
	s_waitcnt lgkmcnt(9)
	v_mfma_f32_32x32x16_bf16 v[32:47], v[188:191], v[204:207], v[32:47]
	ds_read_b64_tr_b16 v[238:239], v182 offset:26112
	ds_read_b64_tr_b16 v[240:241], v182 offset:28160
	ds_read_b128 v[204:207], v172 offset:57344
	v_exp_f32_e32 v82, v82
	v_exp_f32_e32 v83, v83
	s_waitcnt lgkmcnt(10)
	v_mfma_f32_32x32x16_bf16 v[32:47], v[192:195], v[208:211], v[32:47]
	ds_read_b64_tr_b16 v[242:243], v182 offset:30208
	ds_read_b64_tr_b16 v[244:245], v182 offset:32256
	ds_read_b128 v[208:211], v173 offset:49152
	v_exp_f32_e32 v84, v84
	v_exp_f32_e32 v85, v85
	s_waitcnt lgkmcnt(11)
	v_mfma_f32_32x32x16_bf16 v[32:47], v[196:199], v[212:215], v[32:47]
	ds_read_b128 v[212:215], v173 offset:57344
	v_exp_f32_e32 v86, v86
	v_exp_f32_e32 v87, v87
	s_waitcnt lgkmcnt(10)
	v_mfma_f32_32x32x16_bf16 v[16:31], v[184:187], v[230:233], v[16:31]
	ds_read_b128 v[230:233], v174 offset:49152
	v_exp_f32_e32 v88, v88
	v_exp_f32_e32 v89, v89
	s_waitcnt lgkmcnt(9)
	v_mfma_f32_32x32x16_bf16 v[16:31], v[188:191], v[234:237], v[16:31]
	ds_read_b128 v[234:237], v174 offset:57344
	v_exp_f32_e32 v90, v90
	v_exp_f32_e32 v91, v91
	s_waitcnt lgkmcnt(7)
	v_mfma_f32_32x32x16_bf16 v[16:31], v[192:195], v[238:241], v[16:31]
	ds_read_b128 v[238:241], v175 offset:49152
	v_exp_f32_e32 v92, v92
	v_exp_f32_e32 v93, v93
	s_waitcnt lgkmcnt(5)
	v_mfma_f32_32x32x16_bf16 v[16:31], v[196:199], v[242:245], v[16:31]
	ds_read_b128 v[242:245], v175 offset:57344
	v_exp_f32_e32 v94, v94
	v_exp_f32_e32 v95, v95
	s_barrier
; __device__ __forceinline__ void finishSM(f32x16& p0, f32x16& p1, float alpha, float& l_reg, bf16x8& pa0, bf16x8& pa1, bf16x8& pa2, bf16x8& pa3) {
; #pragma unroll
;   for (int r = 0; r < 16; ++r) p1[r] = __builtin_amdgcn_exp2f(p1[r]);
;   float ps = 0;
; #pragma unroll
;   for (int r = 0; r < 16; ++r) ps += p0[r];
; #pragma unroll
;   for (int r = 0; r < 16; ++r) ps += p1[r];
;   { auto rr = __builtin_amdgcn_permlane32_swap(__float_as_uint(ps), __float_as_uint(ps), false, false);
;     ps = __uint_as_float(rr[0]) + __uint_as_float(rr[1]); }
;   l_reg = l_reg * alpha + ps;
;     ...
;   PK4(p0, 0, pa0); PK4(p0, 8, pa1); PK4(p1, 0, pa2); PK4(p1, 8, pa3);
;     ...
; }
; __device__ __forceinline__ void qkt(f32x16& p0, f32x16& p1, const bf16* Ks, const bf16x8* qr, int r32, int hi) {
;   p0 = f32x16{}; p1 = f32x16{};
; #pragma unroll
;   for (int d0 = 0; d0 < 8; ++d0) { int cb = (d0 * 16 + hi * 8) * 2;
;     bf16x8 b0 = *reinterpret_cast<const bf16x8*>((const char*)Ks + KSWZ(r32, cb));
;     bf16x8 b1 = *reinterpret_cast<const bf16x8*>((const char*)Ks + KSWZ(32 + r32, cb));
;     p0 = __builtin_amdgcn_mfma_f32_32x32x16_bf16(b0, qr[d0], p0, 0, 0, 0);
;     p1 = __builtin_amdgcn_mfma_f32_32x32x16_bf16(b1, qr[d0], p1, 0, 0, 0); }
; }
; __device__ __forceinline__ int v_st(int k, int c) { const int kk = (k & ~0xC) | ((k & 4) << 1) | ((k & 8) >> 1); return ((kk >> 3) * 4 + (c >> 5)) * 512 + ((kk & 7) * 32 + (c & 31)) * 2; }
; __device__ __forceinline__ int v_rd_base(int lane) { return ((lane & 3) << 3) | (((lane >> 2) & 3) << 6) | (((lane >> 4) & 1) << 5) | (((lane >> 5) & 1) << 8); }
; template <int OFF> __device__ __forceinline__ s16x4 tr_read(int vb) {
;   s16x4 r; asm volatile("ds_read_b64_tr_b16 %0, %1 offset:%2" : "=&v"(r) : "v"(vb), "i"(OFF) : "memory"); return r;
; }
; template <int D0> __device__ __forceinline__ void pv_one(f32x16& od, int vb, bf16x8 pa0, bf16x8 pa1, bf16x8 pa2, bf16x8 pa3) {
;   const s16x4 l0 = tr_read<v_rd_off(D0, 0, 0)>(vb), h0 = tr_read<v_rd_off(D0, 0, 1)>(vb), l1 = tr_read<v_rd_off(D0, 1, 0)>(vb), h1 = tr_read<v_rd_off(D0, 1, 1)>(vb);
;   const s16x4 l2 = tr_read<v_rd_off(D0, 2, 0)>(vb), h2 = tr_read<v_rd_off(D0, 2, 1)>(vb), l3 = tr_read<v_rd_off(D0, 3, 0)>(vb), h3 = tr_read<v_rd_off(D0, 3, 1)>(vb);
;   asm volatile("s_waitcnt lgkmcnt(0)" ::: "memory"); SBAR();
;     ...
;   od = __builtin_amdgcn_mfma_f32_32x32x16_bf16(pa0, PK(l0, h0), od, 0, 0, 0);
	v_mfma_f32_32x32x16_bf16 v[128:143], v[200:203], v[124:127], 0
	ds_read_b128 v[200:203], v176 offset:49152
	v_cvt_pk_bf16_f32 v184, v64, v65
	v_add_f32_e32 v169, v169, v64
	v_add_f32_e32 v219, v219, v65
	v_mfma_f32_32x32x16_bf16 v[144:159], v[204:207], v[124:127], 0
	ds_read_b128 v[204:207], v176 offset:57344
	v_cvt_pk_bf16_f32 v185, v66, v67
	v_add_f32_e32 v222, v222, v66
	v_add_f32_e32 v254, v254, v67
	s_waitcnt lgkmcnt(7)
	v_mfma_f32_32x32x16_bf16 v[128:143], v[208:211], v[120:123], v[128:143]
	ds_read_b128 v[208:211], v177 offset:49152
	v_cvt_pk_bf16_f32 v186, v68, v69
	v_add_f32_e32 v169, v169, v68
	v_add_f32_e32 v219, v219, v69
	s_waitcnt lgkmcnt(7)
	v_mfma_f32_32x32x16_bf16 v[144:159], v[212:215], v[120:123], v[144:159]
	ds_read_b128 v[212:215], v177 offset:57344
	v_cvt_pk_bf16_f32 v187, v70, v71
	v_add_f32_e32 v222, v222, v70
	v_add_f32_e32 v254, v254, v71
	s_waitcnt lgkmcnt(7)
	v_mfma_f32_32x32x16_bf16 v[128:143], v[230:233], v[116:119], v[128:143]
	ds_read_b128 v[230:233], v178 offset:49152
	v_cvt_pk_bf16_f32 v188, v72, v73
	v_add_f32_e32 v169, v169, v72
	v_add_f32_e32 v219, v219, v73
	v_permlane32_swap_b32_e32 v184, v186
	s_waitcnt lgkmcnt(7)
	v_mfma_f32_32x32x16_bf16 v[144:159], v[234:237], v[116:119], v[144:159]
	ds_read_b128 v[234:237], v178 offset:57344
	v_cvt_pk_bf16_f32 v189, v74, v75
	v_add_f32_e32 v222, v222, v74
	v_add_f32_e32 v254, v254, v75
	v_permlane32_swap_b32_e32 v185, v187
	s_waitcnt lgkmcnt(7)
	v_mfma_f32_32x32x16_bf16 v[128:143], v[238:241], v[112:115], v[128:143]
	ds_read_b128 v[238:241], v179 offset:49152
	v_cvt_pk_bf16_f32 v190, v76, v77
	v_add_f32_e32 v169, v169, v76
	v_add_f32_e32 v219, v219, v77
	s_waitcnt lgkmcnt(7)
	v_mfma_f32_32x32x16_bf16 v[144:159], v[242:245], v[112:115], v[144:159]
	ds_read_b128 v[242:245], v179 offset:57344
	v_cvt_pk_bf16_f32 v191, v78, v79
	v_add_f32_e32 v222, v222, v78
	v_add_f32_e32 v254, v254, v79
	s_waitcnt lgkmcnt(7)
	v_mfma_f32_32x32x16_bf16 v[128:143], v[200:203], v[108:111], v[128:143]
	v_cvt_pk_bf16_f32 v192, v80, v81
	v_add_f32_e32 v169, v169, v80
	v_add_f32_e32 v219, v219, v81
	v_permlane32_swap_b32_e32 v188, v190
	s_waitcnt lgkmcnt(6)
	v_mfma_f32_32x32x16_bf16 v[144:159], v[204:207], v[108:111], v[144:159]
	v_cvt_pk_bf16_f32 v193, v82, v83
	v_add_f32_e32 v222, v222, v82
	v_add_f32_e32 v254, v254, v83
	v_permlane32_swap_b32_e32 v189, v191
	s_waitcnt lgkmcnt(5)
	v_mfma_f32_32x32x16_bf16 v[128:143], v[208:211], v[104:107], v[128:143]
	v_cvt_pk_bf16_f32 v194, v84, v85
	v_add_f32_e32 v169, v169, v84
	v_add_f32_e32 v219, v219, v85
	s_waitcnt lgkmcnt(4)
	v_mfma_f32_32x32x16_bf16 v[144:159], v[212:215], v[104:107], v[144:159]
	ds_read_b64_tr_b16 v[200:201], v182 offset:32768
	ds_read_b64_tr_b16 v[202:203], v182 offset:34816
	v_cvt_pk_bf16_f32 v195, v86, v87
	v_add_f32_e32 v222, v222, v86
	v_add_f32_e32 v254, v254, v87
	s_waitcnt lgkmcnt(5)
	v_mfma_f32_32x32x16_bf16 v[128:143], v[230:233], v[100:103], v[128:143]
	ds_read_b64_tr_b16 v[204:205], v182 offset:36864
	ds_read_b64_tr_b16 v[206:207], v182 offset:38912
	v_cvt_pk_bf16_f32 v196, v88, v89
	v_add_f32_e32 v169, v169, v88
	v_add_f32_e32 v219, v219, v89
	v_permlane32_swap_b32_e32 v192, v194
	s_waitcnt lgkmcnt(6)
	v_mfma_f32_32x32x16_bf16 v[144:159], v[234:237], v[100:103], v[144:159]
	ds_read_b64_tr_b16 v[208:209], v182 offset:40960
	ds_read_b64_tr_b16 v[210:211], v182 offset:43008
	v_cvt_pk_bf16_f32 v197, v90, v91
	v_add_f32_e32 v222, v222, v90
	v_add_f32_e32 v254, v254, v91
	v_permlane32_swap_b32_e32 v193, v195
	s_waitcnt lgkmcnt(7)
	v_mfma_f32_32x32x16_bf16 v[128:143], v[238:241], v[96:99], v[128:143]
	ds_read_b64_tr_b16 v[212:213], v182 offset:45056
	ds_read_b64_tr_b16 v[214:215], v182 offset:47104
	v_cvt_pk_bf16_f32 v198, v92, v93
	v_add_f32_e32 v169, v169, v92
	v_add_f32_e32 v219, v219, v93
	s_waitcnt lgkmcnt(8)
	v_mfma_f32_32x32x16_bf16 v[144:159], v[242:245], v[96:99], v[144:159]
	ds_read_b64_tr_b16 v[230:231], v182 offset:33280
	ds_read_b64_tr_b16 v[232:233], v182 offset:35328
	v_cvt_pk_bf16_f32 v199, v94, v95
	v_add_f32_e32 v222, v222, v94
	v_add_f32_e32 v254, v254, v95
	v_permlane32_swap_b32_e32 v196, v198
	v_permlane32_swap_b32_e32 v197, v199
	s_waitcnt lgkmcnt(8)
	v_mfma_f32_32x32x16_bf16 v[0:15], v[184:187], v[200:203], v[0:15]
	ds_read_b64_tr_b16 v[234:235], v182 offset:37376
	ds_read_b64_tr_b16 v[236:237], v182 offset:39424
	v_exp_f32_e32 v128, v128
	v_exp_f32_e32 v129, v129
	s_waitcnt lgkmcnt(8)
	v_mfma_f32_32x32x16_bf16 v[0:15], v[188:191], v[204:207], v[0:15]
	ds_read_b64_tr_b16 v[238:239], v182 offset:41472
	ds_read_b64_tr_b16 v[240:241], v182 offset:43520
	v_exp_f32_e32 v130, v130
	v_exp_f32_e32 v131, v131
	s_waitcnt lgkmcnt(8)
	v_mfma_f32_32x32x16_bf16 v[0:15], v[192:195], v[208:211], v[0:15]
	ds_read_b64_tr_b16 v[242:243], v182 offset:45568
	ds_read_b64_tr_b16 v[244:245], v182 offset:47616
	v_exp_f32_e32 v132, v132
	v_exp_f32_e32 v133, v133
	s_waitcnt lgkmcnt(8)
	v_mfma_f32_32x32x16_bf16 v[0:15], v[196:199], v[212:215], v[0:15]
	ds_read_b64_tr_b16 v[200:201], v182 offset:33792
	ds_read_b64_tr_b16 v[202:203], v182 offset:35840
	v_exp_f32_e32 v134, v134
	v_exp_f32_e32 v135, v135
	s_waitcnt lgkmcnt(8)
	v_mfma_f32_32x32x16_bf16 v[48:63], v[184:187], v[230:233], v[48:63]
	ds_read_b64_tr_b16 v[204:205], v182 offset:37888
	ds_read_b64_tr_b16 v[206:207], v182 offset:39936
	v_exp_f32_e32 v136, v136
	v_exp_f32_e32 v137, v137
	s_waitcnt lgkmcnt(8)
	v_mfma_f32_32x32x16_bf16 v[48:63], v[188:191], v[234:237], v[48:63]
	ds_read_b64_tr_b16 v[208:209], v182 offset:41984
	ds_read_b64_tr_b16 v[210:211], v182 offset:44032
	v_exp_f32_e32 v138, v138
	v_exp_f32_e32 v139, v139
	s_waitcnt lgkmcnt(8)
; #define SBAR() __builtin_amdgcn_sched_barrier(0)
; __device__ __forceinline__ void finishSM(f32x16& p0, f32x16& p1, float alpha, float& l_reg, bf16x8& pa0, bf16x8& pa1, bf16x8& pa2, bf16x8& pa3) {
; #pragma unroll
;   for (int r = 0; r < 16; ++r) p1[r] = __builtin_amdgcn_exp2f(p1[r]);
; template <int D0> __device__ __forceinline__ void pv_one(f32x16& od, int vb, bf16x8 pa0, bf16x8 pa1, bf16x8 pa2, bf16x8 pa3) {
;   const s16x4 l0 = tr_read<v_rd_off(D0, 0, 0)>(vb), h0 = tr_read<v_rd_off(D0, 0, 1)>(vb), l1 = tr_read<v_rd_off(D0, 1, 0)>(vb), h1 = tr_read<v_rd_off(D0, 1, 1)>(vb);
;   const s16x4 l2 = tr_read<v_rd_off(D0, 2, 0)>(vb), h2 = tr_read<v_rd_off(D0, 2, 1)>(vb), l3 = tr_read<v_rd_off(D0, 3, 0)>(vb), h3 = tr_read<v_rd_off(D0, 3, 1)>(vb);
;   asm volatile("s_waitcnt lgkmcnt(0)" ::: "memory"); SBAR();
;     ...
;   od = __builtin_amdgcn_mfma_f32_32x32x16_bf16(pa0, PK(l0, h0), od, 0, 0, 0);
;   od = __builtin_amdgcn_mfma_f32_32x32x16_bf16(pa1, PK(l1, h1), od, 0, 0, 0);
;   od = __builtin_amdgcn_mfma_f32_32x32x16_bf16(pa2, PK(l2, h2), od, 0, 0, 0);
;   od = __builtin_amdgcn_mfma_f32_32x32x16_bf16(pa3, PK(l3, h3), od, 0, 0, 0);
;     ...
; }
; __device__ __forceinline__ void pv_d0(f32x16* o, int vb, bf16x8 pa0, bf16x8 pa1, bf16x8 pa2, bf16x8 pa3) {
;   pv_one<0>(o[0], vb, pa0, pa1, pa2, pa3); pv_one<1>(o[1], vb, pa0, pa1, pa2, pa3); pv_one<2>(o[2], vb, pa0, pa1, pa2, pa3); pv_one<3>(o[3], vb, pa0, pa1, pa2, pa3);
	v_mfma_f32_32x32x16_bf16 v[48:63], v[192:195], v[238:241], v[48:63]
	ds_read_b64_tr_b16 v[212:213], v182 offset:46080
	ds_read_b64_tr_b16 v[214:215], v182 offset:48128
	v_exp_f32_e32 v140, v140
	v_exp_f32_e32 v141, v141
	s_waitcnt lgkmcnt(8)
	v_mfma_f32_32x32x16_bf16 v[48:63], v[196:199], v[242:245], v[48:63]
	ds_read_b64_tr_b16 v[230:231], v182 offset:34304
	ds_read_b64_tr_b16 v[232:233], v182 offset:36352
	v_exp_f32_e32 v142, v142
	v_exp_f32_e32 v143, v143
	s_waitcnt lgkmcnt(8)
	v_mfma_f32_32x32x16_bf16 v[32:47], v[184:187], v[200:203], v[32:47]
	ds_read_b64_tr_b16 v[234:235], v182 offset:38400
	ds_read_b64_tr_b16 v[236:237], v182 offset:40448
	v_exp_f32_e32 v144, v144
	v_exp_f32_e32 v145, v145
	s_waitcnt lgkmcnt(8)
	v_mfma_f32_32x32x16_bf16 v[32:47], v[188:191], v[204:207], v[32:47]
	ds_read_b64_tr_b16 v[238:239], v182 offset:42496
	ds_read_b64_tr_b16 v[240:241], v182 offset:44544
	v_exp_f32_e32 v146, v146
	v_exp_f32_e32 v147, v147
	s_waitcnt lgkmcnt(8)
	v_mfma_f32_32x32x16_bf16 v[32:47], v[192:195], v[208:211], v[32:47]
	ds_read_b64_tr_b16 v[242:243], v182 offset:46592
	ds_read_b64_tr_b16 v[244:245], v182 offset:48640
	v_exp_f32_e32 v148, v148
	v_exp_f32_e32 v149, v149
	s_waitcnt lgkmcnt(8)
	v_mfma_f32_32x32x16_bf16 v[32:47], v[196:199], v[212:215], v[32:47]
	v_exp_f32_e32 v150, v150
	v_exp_f32_e32 v151, v151
	s_waitcnt lgkmcnt(6)
	v_mfma_f32_32x32x16_bf16 v[16:31], v[184:187], v[230:233], v[16:31]
	v_exp_f32_e32 v152, v152
	v_exp_f32_e32 v153, v153
	s_waitcnt lgkmcnt(4)
	v_mfma_f32_32x32x16_bf16 v[16:31], v[188:191], v[234:237], v[16:31]
	v_exp_f32_e32 v154, v154
	v_exp_f32_e32 v155, v155
	s_waitcnt lgkmcnt(2)
	v_mfma_f32_32x32x16_bf16 v[16:31], v[192:195], v[238:241], v[16:31]
	v_exp_f32_e32 v156, v156
	v_exp_f32_e32 v157, v157
	s_waitcnt lgkmcnt(0)
	v_mfma_f32_32x32x16_bf16 v[16:31], v[196:199], v[242:245], v[16:31]
	v_exp_f32_e32 v158, v158
	v_exp_f32_e32 v159, v159
	s_waitcnt lgkmcnt(0)
	s_barrier
; #define SBAR() __builtin_amdgcn_sched_barrier(0)
; #define RESC(a) do { if (__any((a) < 1.f)) { if (hi == 0) al_l[r32] = (a); asm volatile("s_waitcnt lgkmcnt(0)" ::: "memory"); \
;     _Pragma("unroll") for (int d = 0; d < 4; ++d) _Pragma("unroll") for (int r = 0; r < 16; ++r) o[d][r] *= al_l[crow(r, hi)]; } } while (0)
;     ...
;   { SBAR(); qkt(pB0, pB1, KSUB(1, 1), qr, r32, hi);
;     finishSM(pA0, pA1, alA, l_reg, pa0, pa1, pa2, pa3); SBAR();
;     pv_d0(o, VSUB(1, 0), pa0, pa1, pa2, pa3); partialSM(pB0, pB1, m_reg, mnB, alB);
;     RESC(alB);
;     finishSM(pB0, pB1, alB, l_reg, pa0, pa1, pa2, pa3); SBAR();
;     pv_d0(o, VSUB(1, 1), pa0, pa1, pa2, pa3); }
;     ...
;   }
;   if (hi == 0) li_l[r32] = l_reg; asm volatile("s_waitcnt lgkmcnt(0)" ::: "memory");
	v_cvt_pk_bf16_f32 v184, v128, v129
	v_add_f32_e32 v169, v169, v128
	v_add_f32_e32 v219, v219, v129
	v_cvt_pk_bf16_f32 v185, v130, v131
	v_add_f32_e32 v222, v222, v130
	v_add_f32_e32 v254, v254, v131
	v_cvt_pk_bf16_f32 v186, v132, v133
	v_add_f32_e32 v169, v169, v132
	v_add_f32_e32 v219, v219, v133
	v_cvt_pk_bf16_f32 v187, v134, v135
	v_add_f32_e32 v222, v222, v134
	v_add_f32_e32 v254, v254, v135
	v_cvt_pk_bf16_f32 v188, v136, v137
	v_add_f32_e32 v169, v169, v136
	v_add_f32_e32 v219, v219, v137
	v_permlane32_swap_b32_e32 v184, v186
	v_cvt_pk_bf16_f32 v189, v138, v139
	v_add_f32_e32 v222, v222, v138
	v_add_f32_e32 v254, v254, v139
	v_permlane32_swap_b32_e32 v185, v187
	v_cvt_pk_bf16_f32 v190, v140, v141
	v_add_f32_e32 v169, v169, v140
	v_add_f32_e32 v219, v219, v141
	v_cvt_pk_bf16_f32 v191, v142, v143
	v_add_f32_e32 v222, v222, v142
	v_add_f32_e32 v254, v254, v143
	v_cvt_pk_bf16_f32 v192, v144, v145
	v_add_f32_e32 v169, v169, v144
	v_add_f32_e32 v219, v219, v145
	v_permlane32_swap_b32_e32 v188, v190
	v_cvt_pk_bf16_f32 v193, v146, v147
	v_add_f32_e32 v222, v222, v146
	v_add_f32_e32 v254, v254, v147
	v_permlane32_swap_b32_e32 v189, v191
	v_cvt_pk_bf16_f32 v194, v148, v149
	v_add_f32_e32 v169, v169, v148
	v_add_f32_e32 v219, v219, v149
	ds_read_b64_tr_b16 v[200:201], v182 offset:49152
	ds_read_b64_tr_b16 v[202:203], v182 offset:51200
	v_cvt_pk_bf16_f32 v195, v150, v151
	v_add_f32_e32 v222, v222, v150
	v_add_f32_e32 v254, v254, v151
	ds_read_b64_tr_b16 v[204:205], v182 offset:53248
	ds_read_b64_tr_b16 v[206:207], v182 offset:55296
	v_cvt_pk_bf16_f32 v196, v152, v153
	v_add_f32_e32 v169, v169, v152
	v_add_f32_e32 v219, v219, v153
	v_permlane32_swap_b32_e32 v192, v194
	ds_read_b64_tr_b16 v[208:209], v182 offset:57344
	ds_read_b64_tr_b16 v[210:211], v182 offset:59392
	v_cvt_pk_bf16_f32 v197, v154, v155
	v_add_f32_e32 v222, v222, v154
	v_add_f32_e32 v254, v254, v155
	v_permlane32_swap_b32_e32 v193, v195
	ds_read_b64_tr_b16 v[212:213], v182 offset:61440
	ds_read_b64_tr_b16 v[214:215], v182 offset:63488
	v_cvt_pk_bf16_f32 v198, v156, v157
	v_add_f32_e32 v169, v169, v156
	v_add_f32_e32 v219, v219, v157
	ds_read_b64_tr_b16 v[230:231], v182 offset:49664
	ds_read_b64_tr_b16 v[232:233], v182 offset:51712
	v_cvt_pk_bf16_f32 v199, v158, v159
	v_add_f32_e32 v222, v222, v158
	v_add_f32_e32 v254, v254, v159
	v_permlane32_swap_b32_e32 v196, v198
	v_permlane32_swap_b32_e32 v197, v199
	s_waitcnt lgkmcnt(8)
	v_mfma_f32_32x32x16_bf16 v[0:15], v[184:187], v[200:203], v[0:15]
	ds_read_b64_tr_b16 v[234:235], v182 offset:53760
	ds_read_b64_tr_b16 v[236:237], v182 offset:55808
	s_waitcnt lgkmcnt(8)
	v_mfma_f32_32x32x16_bf16 v[0:15], v[188:191], v[204:207], v[0:15]
	ds_read_b64_tr_b16 v[238:239], v182 offset:57856
	ds_read_b64_tr_b16 v[240:241], v182 offset:59904
	s_waitcnt lgkmcnt(8)
	v_mfma_f32_32x32x16_bf16 v[0:15], v[192:195], v[208:211], v[0:15]
	ds_read_b64_tr_b16 v[242:243], v182 offset:61952
	ds_read_b64_tr_b16 v[244:245], v182 offset:64000
	s_waitcnt lgkmcnt(8)
	v_mfma_f32_32x32x16_bf16 v[0:15], v[196:199], v[212:215], v[0:15]
	ds_read_b64_tr_b16 v[200:201], v182 offset:50176
	ds_read_b64_tr_b16 v[202:203], v182 offset:52224
	s_waitcnt lgkmcnt(8)
	v_mfma_f32_32x32x16_bf16 v[48:63], v[184:187], v[230:233], v[48:63]
	ds_read_b64_tr_b16 v[204:205], v182 offset:54272
	ds_read_b64_tr_b16 v[206:207], v182 offset:56320
	s_waitcnt lgkmcnt(8)
	v_mfma_f32_32x32x16_bf16 v[48:63], v[188:191], v[234:237], v[48:63]
	ds_read_b64_tr_b16 v[208:209], v182 offset:58368
	ds_read_b64_tr_b16 v[210:211], v182 offset:60416
	s_waitcnt lgkmcnt(8)
	v_mfma_f32_32x32x16_bf16 v[48:63], v[192:195], v[238:241], v[48:63]
	ds_read_b64_tr_b16 v[212:213], v182 offset:62464
	ds_read_b64_tr_b16 v[214:215], v182 offset:64512
	s_waitcnt lgkmcnt(8)
	v_mfma_f32_32x32x16_bf16 v[48:63], v[196:199], v[242:245], v[48:63]
	ds_read_b64_tr_b16 v[230:231], v182 offset:50688
	ds_read_b64_tr_b16 v[232:233], v182 offset:52736
	s_waitcnt lgkmcnt(8)
	v_mfma_f32_32x32x16_bf16 v[32:47], v[184:187], v[200:203], v[32:47]
	ds_read_b64_tr_b16 v[234:235], v182 offset:54784
	ds_read_b64_tr_b16 v[236:237], v182 offset:56832
	s_waitcnt lgkmcnt(8)
	v_mfma_f32_32x32x16_bf16 v[32:47], v[188:191], v[204:207], v[32:47]
	ds_read_b64_tr_b16 v[238:239], v182 offset:58880
	ds_read_b64_tr_b16 v[240:241], v182 offset:60928
	s_waitcnt lgkmcnt(8)
	v_mfma_f32_32x32x16_bf16 v[32:47], v[192:195], v[208:211], v[32:47]
	ds_read_b64_tr_b16 v[242:243], v182 offset:62976
	ds_read_b64_tr_b16 v[244:245], v182 offset:65024
	s_waitcnt lgkmcnt(8)
	v_mfma_f32_32x32x16_bf16 v[32:47], v[196:199], v[212:215], v[32:47]
	s_waitcnt lgkmcnt(6)
	v_mfma_f32_32x32x16_bf16 v[16:31], v[184:187], v[230:233], v[16:31]
	s_waitcnt lgkmcnt(4)
	v_mfma_f32_32x32x16_bf16 v[16:31], v[188:191], v[234:237], v[16:31]
	s_waitcnt lgkmcnt(2)
	v_mfma_f32_32x32x16_bf16 v[16:31], v[192:195], v[238:241], v[16:31]
	s_waitcnt lgkmcnt(0)
	v_mfma_f32_32x32x16_bf16 v[16:31], v[196:199], v[242:245], v[16:31]
	s_waitcnt lgkmcnt(0)
	s_barrier
	v_add_f32_e32 v169, v169, v219
	v_add_f32_e32 v222, v222, v254
	v_add_f32_e32 v169, v169, v222
	v_mov_b32_e32 v219, v169
	s_nop 1
	v_permlane32_swap_b32_e32 v169, v219
	v_add_f32_e32 v64, v169, v219
	v_lshlrev_b32_e32 v164, 4, v229
	v_mov_b32_e32 v165, 0
	s_and_saveexec_b64 s[0:1], s[2:3]
	ds_write_b32 v168, v64
	s_branch .LBB0_477
